# GDN prep forward substitution: LDS-read wait sunk below the current row FMA chain
# baseline (speedup 1.0000x reference)
; DI void gdn_prep_item(const Params& P, int l, int n, int hh, char* smem) {
;     ...
;   if (tid < 256) {
;     const int c = tid; const bool isu = c < 128; const int cc = c & 127;
;     const float* rp = (isu ? vf : kf) + cc; const float* sp = gcs + (isu ? 64 : 192);
;     f32x2 xx[32];
;     f32x4 LA[16], LB[16]; float rh[2];
;     xx[0].x = sp[0] * rp[0];
;     LA[0] = *(const f32x4*)(Lm + 64); rh[1] = sp[1] * rp[128];
; #pragma unroll
;     for (int i = 1; i < 64; ++i) {
;       f32x4 (&CUR)[16] = (i & 1) ? LA : LB; f32x4 (&NXT)[16] = (i & 1) ? LB : LA;
;       if (i + 1 < 64) {
; #pragma unroll
;         for (int c = 0; c < (i + 4) / 4; ++c) NXT[c] = *(const f32x4*)(Lm + (i + 1) * 64 + 4 * c);
;         rh[(i + 1) & 1] = sp[i + 1] * rp[(i + 1) * 128];
;       }
;       __builtin_amdgcn_sched_barrier(0);
;       f32x2 acc = {rh[i & 1], 0.f};
; #pragma unroll
;       for (int p = 0; p < i / 2; ++p) { const f32x2 lp = (p & 1) ? (f32x2){CUR[p >> 1].z, CUR[p >> 1].w} : (f32x2){CUR[p >> 1].x, CUR[p >> 1].y}; acc = acc - lp * xx[p]; }
;       if (i & 1) { const int j = i - 1; const float lj = ((j & 3) == 0) ? CUR[j >> 2].x : CUR[j >> 2].z; acc.x = fmaf(-lj, xx[j >> 1].x, acc.x); }
;       const float xi = acc.x + acc.y;
;       if (i & 1) xx[i >> 1].y = xi; else xx[i >> 1].x = xi;
;       __builtin_amdgcn_sched_barrier(0);
;     }
.LBB0_527:
	s_or_b64 exec, exec, s[2:3]
	v_cmp_gt_i32_e32 vcc, s97, v82
	s_waitcnt lgkmcnt(0)
	s_barrier
	s_and_saveexec_b64 s[2:3], vcc
	s_cbranch_execz .LBB0_418
	v_mov_b32_e32 v0, 0x8800
	v_mov_b32_e32 v2, 0x10800
	v_cmp_gt_i32_e32 vcc, s55, v82
	v_and_b32_e32 v69, 0x7f, v82
	v_mov_b32_e32 v4, 0x18900
	v_cndmask_b32_e32 v0, v0, v2, vcc
	v_lshl_or_b32 v66, v69, 2, v0
	v_mov_b32_e32 v0, 0x300
	v_mov_b32_e32 v2, 0x100
	v_cndmask_b32_e32 v67, v0, v2, vcc
	v_or_b32_e32 v0, 0x1c800, v67
	ds_read2st64_b32 v[2:3], v66 offset1:2
	ds_read_b96 v[8:10], v0
	ds_read_b128 v[4:7], v4
	v_mov_b32_e32 v0, 0x18a00
	s_waitcnt lgkmcnt(0)
	ds_read_b32 v5, v66 offset:1024
	ds_read_b64 v[12:13], v0
	s_movk_i32 s10, 0x7f
	v_mul_f32_e32 v2, v8, v2
	v_mul_f32_e32 v3, v9, v3
	v_cmp_lt_i32_e32 vcc, s10, v82
	v_fma_f32 v3, -v4, v2, v3
	v_add_f32_e32 v3, 0, v3
	s_waitcnt lgkmcnt(0)
	v_mul_f32_e32 v0, v10, v5
	v_or_b32_e32 v4, 0x1c80c, v67
	ds_read_b32 v5, v66 offset:1536
	ds_read_b32 v4, v4
	v_mov_b32_e32 v6, 0x18b00
	ds_read_b128 v[6:9], v6
	s_waitcnt lgkmcnt(0)
	v_mul_f32_e32 v14, v4, v5
	v_pk_fma_f32 v[4:5], v[12:13], v[2:3], v[0:1] neg_lo:[1,0,0] neg_hi:[1,0,0]
	s_nop 0
	v_pk_add_f32 v[4:5], v[4:5], v[4:5] op_sel:[0,1] op_sel_hi:[1,0]
	v_or_b32_e32 v0, 0x1c810, v67
	v_mov_b32_e32 v9, 0x18c00
	ds_read_b32 v5, v66 offset:2048
	ds_read_b32 v0, v0
	ds_read_b128 v[10:13], v9
	v_mov_b32_e32 v15, v1
	v_pk_fma_f32 v[6:7], v[2:3], v[6:7], v[14:15] neg_lo:[1,0,0] neg_hi:[1,0,0]
	s_nop 0
	s_waitcnt lgkmcnt(0)
	v_mul_f32_e32 v0, v0, v5
	v_fma_f32 v5, -v8, v4, v6
	v_add_f32_e32 v5, v7, v5
	v_mov_b32_e32 v6, 0x18d00
	ds_read_b128 v[14:17], v6
	v_mov_b32_e32 v6, 0x18d10
	ds_read_b128 v[18:21], v6
	v_or_b32_e32 v6, 0x1c814, v67
	ds_read_b32 v6, v6
	ds_read_b32 v7, v66 offset:2560
	s_waitcnt lgkmcnt(0)
	v_mul_f32_e32 v20, v6, v7
	v_pk_fma_f32 v[6:7], v[2:3], v[10:11], v[0:1] neg_lo:[1,0,0] neg_hi:[1,0,0]
	s_nop 0
	v_pk_fma_f32 v[6:7], v[12:13], v[4:5], v[6:7] neg_lo:[1,0,0] neg_hi:[1,0,0]
	s_nop 0
	v_pk_add_f32 v[6:7], v[6:7], v[6:7] op_sel:[0,1] op_sel_hi:[1,0]
	v_or_b32_e32 v0, 0x1c818, v67
	v_mov_b32_e32 v8, 0x18e00
	v_mov_b32_e32 v12, 0x18e10
	ds_read_b32 v0, v0
	ds_read_b32 v7, v66 offset:3072
	ds_read_b128 v[8:11], v8
	ds_read_b64 v[22:23], v12
	v_mov_b32_e32 v21, v1
	v_pk_fma_f32 v[12:13], v[2:3], v[14:15], v[20:21] neg_lo:[1,0,0] neg_hi:[1,0,0]
	s_nop 0
	v_pk_fma_f32 v[12:13], v[4:5], v[16:17], v[12:13] neg_lo:[1,0,0] neg_hi:[1,0,0]
	s_nop 0
	s_waitcnt lgkmcnt(0)
	v_mul_f32_e32 v0, v0, v7
	v_fma_f32 v7, -v18, v6, v12
	v_add_f32_e32 v7, v13, v7
	v_or_b32_e32 v12, 0x1c81c, v67
	ds_read_b32 v20, v12
	ds_read_b32 v21, v66 offset:3584
	v_mov_b32_e32 v12, 0x18f00
	v_mov_b32_e32 v16, 0x18f10
	ds_read_b128 v[12:15], v12
	ds_read_b128 v[16:19], v16
	v_pk_fma_f32 v[8:9], v[2:3], v[8:9], v[0:1] neg_lo:[1,0,0] neg_hi:[1,0,0]
	s_nop 0
	v_pk_fma_f32 v[8:9], v[4:5], v[10:11], v[8:9] neg_lo:[1,0,0] neg_hi:[1,0,0]
	s_nop 0
	v_pk_fma_f32 v[8:9], v[22:23], v[6:7], v[8:9] neg_lo:[1,0,0] neg_hi:[1,0,0]
	s_nop 0
	v_pk_add_f32 v[8:9], v[8:9], v[8:9] op_sel:[0,1] op_sel_hi:[1,0]
	s_waitcnt lgkmcnt(0)
	v_mul_f32_e32 v28, v20, v21
	v_or_b32_e32 v0, 0x1c820, v67
	v_mov_b32_e32 v10, 0x19000
	ds_read_b32 v0, v0
	ds_read_b32 v9, v66 offset:4096
	ds_read_b128 v[20:23], v10
	v_mov_b32_e32 v10, 0x19010
	ds_read_b128 v[24:27], v10
	v_mov_b32_e32 v29, v1
	v_pk_fma_f32 v[10:11], v[2:3], v[12:13], v[28:29] neg_lo:[1,0,0] neg_hi:[1,0,0]
	s_nop 0
	v_pk_fma_f32 v[10:11], v[4:5], v[14:15], v[10:11] neg_lo:[1,0,0] neg_hi:[1,0,0]
	s_nop 0
	v_pk_fma_f32 v[10:11], v[6:7], v[16:17], v[10:11] neg_lo:[1,0,0] neg_hi:[1,0,0]
	s_nop 0
	s_waitcnt lgkmcnt(0)
	v_mul_f32_e32 v0, v0, v9
	v_fma_f32 v9, -v18, v8, v10
	v_add_f32_e32 v9, v11, v9
	v_or_b32_e32 v10, 0x1c824, v67
	v_mov_b32_e32 v11, 0x19120
	ds_read_b128 v[12:15], v11
	ds_read_b32 v10, v10
	ds_read_b32 v11, v66 offset:4608
	s_waitcnt lgkmcnt(0)
	v_mov_b32_e32 v13, 0x19100
	ds_read_b128 v[14:17], v13
	v_mov_b32_e32 v13, 0x19110
	ds_read_b128 v[28:31], v13
	v_mul_f32_e32 v32, v10, v11
	v_pk_fma_f32 v[10:11], v[2:3], v[20:21], v[0:1] neg_lo:[1,0,0] neg_hi:[1,0,0]
	s_nop 0
	v_pk_fma_f32 v[10:11], v[4:5], v[22:23], v[10:11] neg_lo:[1,0,0] neg_hi:[1,0,0]
	s_nop 0
	v_pk_fma_f32 v[10:11], v[6:7], v[24:25], v[10:11] neg_lo:[1,0,0] neg_hi:[1,0,0]
	s_nop 0
	v_pk_fma_f32 v[10:11], v[26:27], v[8:9], v[10:11] neg_lo:[1,0,0] neg_hi:[1,0,0]
	s_nop 0
	v_pk_add_f32 v[10:11], v[10:11], v[10:11] op_sel:[0,1] op_sel_hi:[1,0]
	v_or_b32_e32 v0, 0x1c828, v67
	v_mov_b32_e32 v11, 0x19220
	v_mov_b32_e32 v13, 0x19200
	ds_read_b64 v[34:35], v11
	ds_read_b32 v0, v0
	ds_read_b32 v11, v66 offset:5120
	ds_read_b128 v[18:21], v13
	v_mov_b32_e32 v13, 0x19210
	ds_read_b128 v[22:25], v13
	v_mov_b32_e32 v33, v1
	s_waitcnt lgkmcnt(0)
	v_mul_f32_e32 v0, v0, v11
	v_pk_fma_f32 v[14:15], v[2:3], v[14:15], v[32:33] neg_lo:[1,0,0] neg_hi:[1,0,0]
	s_nop 0
	v_pk_fma_f32 v[14:15], v[4:5], v[16:17], v[14:15] neg_lo:[1,0,0] neg_hi:[1,0,0]
	s_nop 0
	v_pk_fma_f32 v[14:15], v[6:7], v[28:29], v[14:15] neg_lo:[1,0,0] neg_hi:[1,0,0]
	s_nop 0
	v_pk_fma_f32 v[14:15], v[8:9], v[30:31], v[14:15] neg_lo:[1,0,0] neg_hi:[1,0,0]
	s_nop 0
	v_fma_f32 v11, -v12, v10, v14
	v_add_f32_e32 v11, v15, v11
	v_or_b32_e32 v12, 0x1c82c, v67
	v_mov_b32_e32 v13, 0x19320
	ds_read_b128 v[14:17], v13
	ds_read_b32 v12, v12
	ds_read_b32 v13, v66 offset:5632
	s_waitcnt lgkmcnt(0)
; DI void gdn_prep_item(const Params& P, int l, int n, int hh, char* smem) {
;     ...
;     for (int i = 1; i < 64; ++i) {
;       f32x4 (&CUR)[16] = (i & 1) ? LA : LB; f32x4 (&NXT)[16] = (i & 1) ? LB : LA;
;       if (i + 1 < 64) {
; #pragma unroll
;         for (int c = 0; c < (i + 4) / 4; ++c) NXT[c] = *(const f32x4*)(Lm + (i + 1) * 64 + 4 * c);
;         rh[(i + 1) & 1] = sp[i + 1] * rp[(i + 1) * 128];
;       }
;       __builtin_amdgcn_sched_barrier(0);
;       f32x2 acc = {rh[i & 1], 0.f};
; #pragma unroll
;       for (int p = 0; p < i / 2; ++p) { const f32x2 lp = (p & 1) ? (f32x2){CUR[p >> 1].z, CUR[p >> 1].w} : (f32x2){CUR[p >> 1].x, CUR[p >> 1].y}; acc = acc - lp * xx[p]; }
;       if (i & 1) { const int j = i - 1; const float lj = ((j & 3) == 0) ? CUR[j >> 2].x : CUR[j >> 2].z; acc.x = fmaf(-lj, xx[j >> 1].x, acc.x); }
;       const float xi = acc.x + acc.y;
;       if (i & 1) xx[i >> 1].y = xi; else xx[i >> 1].x = xi;
;       __builtin_amdgcn_sched_barrier(0);
;     }
	v_mov_b32_e32 v17, 0x19300
	ds_read_b128 v[26:29], v17
	v_mov_b32_e32 v17, 0x19310
	ds_read_b128 v[30:33], v17
	v_mul_f32_e32 v38, v12, v13
	v_pk_fma_f32 v[12:13], v[2:3], v[18:19], v[0:1] neg_lo:[1,0,0] neg_hi:[1,0,0]
	s_nop 0
	v_pk_fma_f32 v[12:13], v[4:5], v[20:21], v[12:13] neg_lo:[1,0,0] neg_hi:[1,0,0]
	s_nop 0
	v_pk_fma_f32 v[12:13], v[6:7], v[22:23], v[12:13] neg_lo:[1,0,0] neg_hi:[1,0,0]
	s_nop 0
	v_pk_fma_f32 v[12:13], v[8:9], v[24:25], v[12:13] neg_lo:[1,0,0] neg_hi:[1,0,0]
	s_nop 0
	v_pk_fma_f32 v[12:13], v[34:35], v[10:11], v[12:13] neg_lo:[1,0,0] neg_hi:[1,0,0]
	s_nop 0
	v_pk_add_f32 v[12:13], v[12:13], v[12:13] op_sel:[0,1] op_sel_hi:[1,0]
	v_or_b32_e32 v0, 0x1c830, v67
	v_mov_b32_e32 v13, 0x19420
	v_mov_b32_e32 v17, 0x19400
	ds_read_b128 v[18:21], v13
	ds_read_b32 v0, v0
	ds_read_b32 v13, v66 offset:6144
	ds_read_b128 v[22:25], v17
	v_mov_b32_e32 v17, 0x19410
	ds_read_b128 v[34:37], v17
	v_mov_b32_e32 v39, v1
	s_waitcnt lgkmcnt(0)
	v_mul_f32_e32 v0, v0, v13
	v_pk_fma_f32 v[26:27], v[2:3], v[26:27], v[38:39] neg_lo:[1,0,0] neg_hi:[1,0,0]
	s_nop 0
	v_pk_fma_f32 v[26:27], v[4:5], v[28:29], v[26:27] neg_lo:[1,0,0] neg_hi:[1,0,0]
	s_nop 0
	v_pk_fma_f32 v[26:27], v[6:7], v[30:31], v[26:27] neg_lo:[1,0,0] neg_hi:[1,0,0]
	s_nop 0
	v_pk_fma_f32 v[26:27], v[8:9], v[32:33], v[26:27] neg_lo:[1,0,0] neg_hi:[1,0,0]
	s_nop 0
	v_pk_fma_f32 v[14:15], v[10:11], v[14:15], v[26:27] neg_lo:[1,0,0] neg_hi:[1,0,0]
	s_nop 0
	v_fma_f32 v13, -v16, v12, v14
	v_add_f32_e32 v13, v15, v13
	v_mov_b32_e32 v14, 0x19500
	ds_read_b128 v[26:29], v14
	v_mov_b32_e32 v14, 0x19510
	ds_read_b128 v[30:33], v14
	v_mov_b32_e32 v14, 0x19520
	ds_read_b128 v[38:41], v14
	v_mov_b32_e32 v14, 0x19530
	ds_read_b128 v[42:45], v14
	v_or_b32_e32 v14, 0x1c834, v67
	ds_read_b32 v14, v14
	ds_read_b32 v15, v66 offset:6656
	s_waitcnt lgkmcnt(0)
	v_mul_f32_e32 v44, v14, v15
	v_pk_fma_f32 v[14:15], v[2:3], v[22:23], v[0:1] neg_lo:[1,0,0] neg_hi:[1,0,0]
	s_nop 0
	v_pk_fma_f32 v[14:15], v[4:5], v[24:25], v[14:15] neg_lo:[1,0,0] neg_hi:[1,0,0]
	s_nop 0
	v_pk_fma_f32 v[14:15], v[6:7], v[34:35], v[14:15] neg_lo:[1,0,0] neg_hi:[1,0,0]
	s_nop 0
	v_pk_fma_f32 v[14:15], v[8:9], v[36:37], v[14:15] neg_lo:[1,0,0] neg_hi:[1,0,0]
	s_nop 0
	v_pk_fma_f32 v[14:15], v[10:11], v[18:19], v[14:15] neg_lo:[1,0,0] neg_hi:[1,0,0]
	s_nop 0
	v_pk_fma_f32 v[14:15], v[20:21], v[12:13], v[14:15] neg_lo:[1,0,0] neg_hi:[1,0,0]
	s_nop 0
	v_pk_add_f32 v[14:15], v[14:15], v[14:15] op_sel:[0,1] op_sel_hi:[1,0]
	v_mov_b32_e32 v0, 0x19600
	ds_read_b128 v[16:19], v0
	v_mov_b32_e32 v0, 0x19610
	ds_read_b128 v[20:23], v0
	v_or_b32_e32 v0, 0x1c838, v67
	v_mov_b32_e32 v24, 0x19620
	ds_read_b32 v0, v0
	ds_read_b32 v15, v66 offset:7168
	ds_read_b128 v[34:37], v24
	v_mov_b32_e32 v24, 0x19630
	ds_read_b64 v[46:47], v24
	v_mov_b32_e32 v45, v1
	v_pk_fma_f32 v[24:25], v[2:3], v[26:27], v[44:45] neg_lo:[1,0,0] neg_hi:[1,0,0]
	s_nop 0
	v_pk_fma_f32 v[24:25], v[4:5], v[28:29], v[24:25] neg_lo:[1,0,0] neg_hi:[1,0,0]
	s_nop 0
	v_pk_fma_f32 v[24:25], v[6:7], v[30:31], v[24:25] neg_lo:[1,0,0] neg_hi:[1,0,0]
	s_nop 0
	v_pk_fma_f32 v[24:25], v[8:9], v[32:33], v[24:25] neg_lo:[1,0,0] neg_hi:[1,0,0]
	s_nop 0
	v_pk_fma_f32 v[24:25], v[10:11], v[38:39], v[24:25] neg_lo:[1,0,0] neg_hi:[1,0,0]
	s_nop 0
	v_pk_fma_f32 v[24:25], v[12:13], v[40:41], v[24:25] neg_lo:[1,0,0] neg_hi:[1,0,0]
	s_nop 0
	s_waitcnt lgkmcnt(0)
	v_mul_f32_e32 v0, v0, v15
	v_fma_f32 v15, -v42, v14, v24
	v_add_f32_e32 v15, v25, v15
	v_mov_b32_e32 v24, 0x19700
	v_mov_b32_e32 v28, 0x19710
	v_or_b32_e32 v32, 0x1c83c, v67
	ds_read_b128 v[24:27], v24
	ds_read_b128 v[28:31], v28
	ds_read_b32 v32, v32
	ds_read_b32 v33, v66 offset:7680
	v_mov_b32_e32 v38, 0x19720
	v_mov_b32_e32 v42, 0x19730
	ds_read_b128 v[38:41], v38
	ds_read_b128 v[42:45], v42
	v_pk_fma_f32 v[16:17], v[2:3], v[16:17], v[0:1] neg_lo:[1,0,0] neg_hi:[1,0,0]
	s_nop 0
	v_pk_fma_f32 v[16:17], v[4:5], v[18:19], v[16:17] neg_lo:[1,0,0] neg_hi:[1,0,0]
	s_nop 0
	v_pk_fma_f32 v[16:17], v[6:7], v[20:21], v[16:17] neg_lo:[1,0,0] neg_hi:[1,0,0]
	s_nop 0
	v_pk_fma_f32 v[16:17], v[8:9], v[22:23], v[16:17] neg_lo:[1,0,0] neg_hi:[1,0,0]
	s_nop 0
	v_pk_fma_f32 v[16:17], v[10:11], v[34:35], v[16:17] neg_lo:[1,0,0] neg_hi:[1,0,0]
	s_nop 0
	v_pk_fma_f32 v[16:17], v[12:13], v[36:37], v[16:17] neg_lo:[1,0,0] neg_hi:[1,0,0]
	s_nop 0
	v_pk_fma_f32 v[16:17], v[46:47], v[14:15], v[16:17] neg_lo:[1,0,0] neg_hi:[1,0,0]
	s_nop 0
	v_pk_add_f32 v[16:17], v[16:17], v[16:17] op_sel:[0,1] op_sel_hi:[1,0]
	s_waitcnt lgkmcnt(0)
	v_mul_f32_e32 v56, v32, v33
	v_mov_b32_e32 v0, 0x19800
	ds_read_b128 v[18:21], v0
	v_mov_b32_e32 v0, 0x19810
	ds_read_b128 v[32:35], v0
	v_or_b32_e32 v0, 0x1c840, v67
	v_mov_b32_e32 v22, 0x19820
	ds_read_b32 v0, v0
	ds_read_b32 v17, v66 offset:8192
	ds_read_b128 v[46:49], v22
	v_mov_b32_e32 v22, 0x19830
	ds_read_b128 v[52:55], v22
	v_mov_b32_e32 v57, v1
	v_pk_fma_f32 v[22:23], v[2:3], v[24:25], v[56:57] neg_lo:[1,0,0] neg_hi:[1,0,0]
	s_nop 0
	v_pk_fma_f32 v[22:23], v[4:5], v[26:27], v[22:23] neg_lo:[1,0,0] neg_hi:[1,0,0]
	s_nop 0
	v_pk_fma_f32 v[22:23], v[6:7], v[28:29], v[22:23] neg_lo:[1,0,0] neg_hi:[1,0,0]
	s_nop 0
	v_pk_fma_f32 v[22:23], v[8:9], v[30:31], v[22:23] neg_lo:[1,0,0] neg_hi:[1,0,0]
	s_nop 0
	v_pk_fma_f32 v[22:23], v[10:11], v[38:39], v[22:23] neg_lo:[1,0,0] neg_hi:[1,0,0]
	s_nop 0
	v_pk_fma_f32 v[22:23], v[12:13], v[40:41], v[22:23] neg_lo:[1,0,0] neg_hi:[1,0,0]
	s_nop 0
	v_pk_fma_f32 v[22:23], v[14:15], v[42:43], v[22:23] neg_lo:[1,0,0] neg_hi:[1,0,0]
	s_nop 0
	s_waitcnt lgkmcnt(0)
; DI void gdn_prep_item(const Params& P, int l, int n, int hh, char* smem) {
;     ...
;     for (int i = 1; i < 64; ++i) {
;       f32x4 (&CUR)[16] = (i & 1) ? LA : LB; f32x4 (&NXT)[16] = (i & 1) ? LB : LA;
;       if (i + 1 < 64) {
; #pragma unroll
;         for (int c = 0; c < (i + 4) / 4; ++c) NXT[c] = *(const f32x4*)(Lm + (i + 1) * 64 + 4 * c);
;         rh[(i + 1) & 1] = sp[i + 1] * rp[(i + 1) * 128];
;       }
;       __builtin_amdgcn_sched_barrier(0);
;       f32x2 acc = {rh[i & 1], 0.f};
; #pragma unroll
;       for (int p = 0; p < i / 2; ++p) { const f32x2 lp = (p & 1) ? (f32x2){CUR[p >> 1].z, CUR[p >> 1].w} : (f32x2){CUR[p >> 1].x, CUR[p >> 1].y}; acc = acc - lp * xx[p]; }
;       if (i & 1) { const int j = i - 1; const float lj = ((j & 3) == 0) ? CUR[j >> 2].x : CUR[j >> 2].z; acc.x = fmaf(-lj, xx[j >> 1].x, acc.x); }
;       const float xi = acc.x + acc.y;
;       if (i & 1) xx[i >> 1].y = xi; else xx[i >> 1].x = xi;
;       __builtin_amdgcn_sched_barrier(0);
;     }
	v_mul_f32_e32 v0, v0, v17
	v_fma_f32 v17, -v44, v16, v22
	v_add_f32_e32 v17, v23, v17
	v_mov_b32_e32 v22, 0x19900
	v_mov_b32_e32 v26, 0x19910
	v_or_b32_e32 v30, 0x1c844, v67
	v_mov_b32_e32 v31, 0x19940
	ds_read_b128 v[22:25], v22
	ds_read_b128 v[26:29], v26
	ds_read_b128 v[36:39], v31
	ds_read_b32 v30, v30
	ds_read_b32 v31, v66 offset:8704
	s_waitcnt lgkmcnt(0)
	v_mov_b32_e32 v37, 0x19920
	ds_read_b128 v[38:41], v37
	v_mov_b32_e32 v37, 0x19930
	ds_read_b128 v[42:45], v37
	v_mul_f32_e32 v60, v30, v31
	v_pk_fma_f32 v[18:19], v[2:3], v[18:19], v[0:1] neg_lo:[1,0,0] neg_hi:[1,0,0]
	s_nop 0
	v_pk_fma_f32 v[18:19], v[4:5], v[20:21], v[18:19] neg_lo:[1,0,0] neg_hi:[1,0,0]
	s_nop 0
	v_pk_fma_f32 v[18:19], v[6:7], v[32:33], v[18:19] neg_lo:[1,0,0] neg_hi:[1,0,0]
	s_nop 0
	v_pk_fma_f32 v[18:19], v[8:9], v[34:35], v[18:19] neg_lo:[1,0,0] neg_hi:[1,0,0]
	s_nop 0
	v_pk_fma_f32 v[18:19], v[10:11], v[46:47], v[18:19] neg_lo:[1,0,0] neg_hi:[1,0,0]
	s_nop 0
	v_pk_fma_f32 v[18:19], v[12:13], v[48:49], v[18:19] neg_lo:[1,0,0] neg_hi:[1,0,0]
	s_nop 0
	v_pk_fma_f32 v[18:19], v[14:15], v[52:53], v[18:19] neg_lo:[1,0,0] neg_hi:[1,0,0]
	s_nop 0
	v_pk_fma_f32 v[18:19], v[54:55], v[16:17], v[18:19] neg_lo:[1,0,0] neg_hi:[1,0,0]
	s_nop 0
	v_pk_add_f32 v[18:19], v[18:19], v[18:19] op_sel:[0,1] op_sel_hi:[1,0]
	v_mov_b32_e32 v0, 0x19a00
	ds_read_b128 v[30:33], v0
	v_mov_b32_e32 v0, 0x19a10
	ds_read_b128 v[46:49], v0
	v_or_b32_e32 v0, 0x1c848, v67
	v_mov_b32_e32 v19, 0x19a40
	v_mov_b32_e32 v34, 0x19a20
	ds_read_b64 v[20:21], v19
	ds_read_b32 v0, v0
	ds_read_b32 v19, v66 offset:9216
	ds_read_b128 v[52:55], v34
	v_mov_b32_e32 v34, 0x19a30
	ds_read_b128 v[56:59], v34
	v_mov_b32_e32 v61, v1
	v_pk_fma_f32 v[22:23], v[2:3], v[22:23], v[60:61] neg_lo:[1,0,0] neg_hi:[1,0,0]
	s_nop 0
	v_pk_fma_f32 v[22:23], v[4:5], v[24:25], v[22:23] neg_lo:[1,0,0] neg_hi:[1,0,0]
	s_nop 0
	v_pk_fma_f32 v[22:23], v[6:7], v[26:27], v[22:23] neg_lo:[1,0,0] neg_hi:[1,0,0]
	s_nop 0
	v_pk_fma_f32 v[22:23], v[8:9], v[28:29], v[22:23] neg_lo:[1,0,0] neg_hi:[1,0,0]
	s_nop 0
	s_waitcnt lgkmcnt(0)
	v_mul_f32_e32 v0, v0, v19
	v_pk_fma_f32 v[22:23], v[10:11], v[38:39], v[22:23] neg_lo:[1,0,0] neg_hi:[1,0,0]
	s_nop 0
	v_pk_fma_f32 v[22:23], v[12:13], v[40:41], v[22:23] neg_lo:[1,0,0] neg_hi:[1,0,0]
	s_nop 0
	v_pk_fma_f32 v[22:23], v[14:15], v[42:43], v[22:23] neg_lo:[1,0,0] neg_hi:[1,0,0]
	s_nop 0
	v_pk_fma_f32 v[22:23], v[16:17], v[44:45], v[22:23] neg_lo:[1,0,0] neg_hi:[1,0,0]
	s_nop 0
	v_fma_f32 v19, -v36, v18, v22
	v_add_f32_e32 v19, v23, v19
	v_mov_b32_e32 v34, 0x19b40
	v_mov_b32_e32 v22, 0x19b00
	v_mov_b32_e32 v26, 0x19b10
	v_or_b32_e32 v38, 0x1c84c, v67
	ds_read_b128 v[34:37], v34
	ds_read_b128 v[22:25], v22
	ds_read_b128 v[26:29], v26
	s_waitcnt lgkmcnt(0)
	ds_read_b32 v37, v38
	ds_read_b32 v60, v66 offset:9728
	v_mov_b32_e32 v38, 0x19b20
	v_mov_b32_e32 v42, 0x19b30
	ds_read_b128 v[38:41], v38
	ds_read_b128 v[42:45], v42
	v_pk_fma_f32 v[30:31], v[2:3], v[30:31], v[0:1] neg_lo:[1,0,0] neg_hi:[1,0,0]
	s_nop 0
	v_pk_fma_f32 v[30:31], v[4:5], v[32:33], v[30:31] neg_lo:[1,0,0] neg_hi:[1,0,0]
	s_nop 0
	v_pk_fma_f32 v[30:31], v[6:7], v[46:47], v[30:31] neg_lo:[1,0,0] neg_hi:[1,0,0]
	s_nop 0
	v_pk_fma_f32 v[30:31], v[8:9], v[48:49], v[30:31] neg_lo:[1,0,0] neg_hi:[1,0,0]
	s_nop 0
	v_pk_fma_f32 v[30:31], v[10:11], v[52:53], v[30:31] neg_lo:[1,0,0] neg_hi:[1,0,0]
	s_nop 0
	v_pk_fma_f32 v[30:31], v[12:13], v[54:55], v[30:31] neg_lo:[1,0,0] neg_hi:[1,0,0]
	s_nop 0
	v_pk_fma_f32 v[30:31], v[14:15], v[56:57], v[30:31] neg_lo:[1,0,0] neg_hi:[1,0,0]
	s_nop 0
	v_pk_fma_f32 v[30:31], v[16:17], v[58:59], v[30:31] neg_lo:[1,0,0] neg_hi:[1,0,0]
	s_nop 0
	v_pk_fma_f32 v[20:21], v[20:21], v[18:19], v[30:31] neg_lo:[1,0,0] neg_hi:[1,0,0]
	s_nop 0
	v_pk_add_f32 v[20:21], v[20:21], v[20:21] op_sel:[0,1] op_sel_hi:[1,0]
	s_waitcnt lgkmcnt(0)
	v_mul_f32_e32 v64, v37, v60
	v_mov_b32_e32 v0, 0x19c00
	ds_read_b128 v[30:33], v0
	v_mov_b32_e32 v0, 0x19c10
	ds_read_b128 v[46:49], v0
	v_or_b32_e32 v0, 0x1c850, v67
	v_mov_b32_e32 v21, 0x19c40
	v_mov_b32_e32 v37, 0x19c20
	ds_read_b128 v[52:55], v21
	ds_read_b32 v0, v0
	ds_read_b32 v21, v66 offset:10240
	ds_read_b128 v[56:59], v37
	v_mov_b32_e32 v37, 0x19c30
	ds_read_b128 v[60:63], v37
	v_mov_b32_e32 v65, v1
	v_pk_fma_f32 v[22:23], v[2:3], v[22:23], v[64:65] neg_lo:[1,0,0] neg_hi:[1,0,0]
	s_nop 0
	v_pk_fma_f32 v[22:23], v[4:5], v[24:25], v[22:23] neg_lo:[1,0,0] neg_hi:[1,0,0]
	s_nop 0
	v_pk_fma_f32 v[22:23], v[6:7], v[26:27], v[22:23] neg_lo:[1,0,0] neg_hi:[1,0,0]
	s_nop 0
	v_pk_fma_f32 v[22:23], v[8:9], v[28:29], v[22:23] neg_lo:[1,0,0] neg_hi:[1,0,0]
	s_nop 0
	v_pk_fma_f32 v[22:23], v[10:11], v[38:39], v[22:23] neg_lo:[1,0,0] neg_hi:[1,0,0]
	s_nop 0
	v_pk_fma_f32 v[22:23], v[12:13], v[40:41], v[22:23] neg_lo:[1,0,0] neg_hi:[1,0,0]
	s_nop 0
	v_pk_fma_f32 v[22:23], v[14:15], v[42:43], v[22:23] neg_lo:[1,0,0] neg_hi:[1,0,0]
	s_nop 0
	v_pk_fma_f32 v[22:23], v[16:17], v[44:45], v[22:23] neg_lo:[1,0,0] neg_hi:[1,0,0]
	s_nop 0
	v_pk_fma_f32 v[22:23], v[18:19], v[34:35], v[22:23] neg_lo:[1,0,0] neg_hi:[1,0,0]
	s_nop 0
	s_waitcnt lgkmcnt(0)
	v_mul_f32_e32 v0, v0, v21
	v_fma_f32 v21, -v36, v20, v22
	v_add_f32_e32 v21, v23, v21
	v_mov_b32_e32 v22, 0x19d00
	ds_read_b128 v[24:27], v22
	v_mov_b32_e32 v22, 0x19d10
	ds_read_b128 v[34:37], v22
	v_mov_b32_e32 v22, 0x19d20
	ds_read_b128 v[38:41], v22
	v_mov_b32_e32 v22, 0x19d30
	ds_read_b128 v[42:45], v22
	v_mov_b32_e32 v22, 0x19d40
	ds_read_b128 v[70:73], v22
	v_mov_b32_e32 v22, 0x19d50
	ds_read_b128 v[74:77], v22
	v_or_b32_e32 v22, 0x1c854, v67
	ds_read_b32 v22, v22
	ds_read_b32 v23, v66 offset:10752
	s_waitcnt lgkmcnt(0)
; DI void gdn_prep_item(const Params& P, int l, int n, int hh, char* smem) {
;     ...
;     for (int i = 1; i < 64; ++i) {
;       f32x4 (&CUR)[16] = (i & 1) ? LA : LB; f32x4 (&NXT)[16] = (i & 1) ? LB : LA;
;       if (i + 1 < 64) {
; #pragma unroll
;         for (int c = 0; c < (i + 4) / 4; ++c) NXT[c] = *(const f32x4*)(Lm + (i + 1) * 64 + 4 * c);
;         rh[(i + 1) & 1] = sp[i + 1] * rp[(i + 1) * 128];
;       }
;       __builtin_amdgcn_sched_barrier(0);
;       f32x2 acc = {rh[i & 1], 0.f};
; #pragma unroll
;       for (int p = 0; p < i / 2; ++p) { const f32x2 lp = (p & 1) ? (f32x2){CUR[p >> 1].z, CUR[p >> 1].w} : (f32x2){CUR[p >> 1].x, CUR[p >> 1].y}; acc = acc - lp * xx[p]; }
;       if (i & 1) { const int j = i - 1; const float lj = ((j & 3) == 0) ? CUR[j >> 2].x : CUR[j >> 2].z; acc.x = fmaf(-lj, xx[j >> 1].x, acc.x); }
;       const float xi = acc.x + acc.y;
;       if (i & 1) xx[i >> 1].y = xi; else xx[i >> 1].x = xi;
;       __builtin_amdgcn_sched_barrier(0);
;     }
	v_mul_f32_e32 v64, v22, v23
	v_pk_fma_f32 v[22:23], v[2:3], v[30:31], v[0:1] neg_lo:[1,0,0] neg_hi:[1,0,0]
	s_nop 0
	v_pk_fma_f32 v[22:23], v[4:5], v[32:33], v[22:23] neg_lo:[1,0,0] neg_hi:[1,0,0]
	s_nop 0
	v_pk_fma_f32 v[22:23], v[6:7], v[46:47], v[22:23] neg_lo:[1,0,0] neg_hi:[1,0,0]
	s_nop 0
	v_pk_fma_f32 v[22:23], v[8:9], v[48:49], v[22:23] neg_lo:[1,0,0] neg_hi:[1,0,0]
	s_nop 0
	v_pk_fma_f32 v[22:23], v[10:11], v[56:57], v[22:23] neg_lo:[1,0,0] neg_hi:[1,0,0]
	s_nop 0
	v_pk_fma_f32 v[22:23], v[12:13], v[58:59], v[22:23] neg_lo:[1,0,0] neg_hi:[1,0,0]
	s_nop 0
	v_pk_fma_f32 v[22:23], v[14:15], v[60:61], v[22:23] neg_lo:[1,0,0] neg_hi:[1,0,0]
	s_nop 0
	v_pk_fma_f32 v[22:23], v[16:17], v[62:63], v[22:23] neg_lo:[1,0,0] neg_hi:[1,0,0]
	s_nop 0
	v_pk_fma_f32 v[22:23], v[18:19], v[52:53], v[22:23] neg_lo:[1,0,0] neg_hi:[1,0,0]
	s_nop 0
	v_pk_fma_f32 v[22:23], v[54:55], v[20:21], v[22:23] neg_lo:[1,0,0] neg_hi:[1,0,0]
	s_nop 0
	v_pk_add_f32 v[22:23], v[22:23], v[22:23] op_sel:[0,1] op_sel_hi:[1,0]
	v_mov_b32_e32 v0, 0x19e00
	ds_read_b128 v[28:31], v0
	v_mov_b32_e32 v0, 0x19e10
	ds_read_b128 v[46:49], v0
	v_mov_b32_e32 v0, 0x19e20
	ds_read_b128 v[52:55], v0
	v_mov_b32_e32 v0, 0x19e30
	ds_read_b128 v[56:59], v0
	v_or_b32_e32 v0, 0x1c858, v67
	v_mov_b32_e32 v32, 0x19e40
	ds_read_b32 v0, v0
	ds_read_b32 v23, v66 offset:11264
	ds_read_b128 v[60:63], v32
	v_mov_b32_e32 v32, 0x19e50
	ds_read_b64 v[84:85], v32
	v_pk_fma_f32 v[24:25], v[2:3], v[24:25], v[64:65] neg_lo:[1,0,0] neg_hi:[1,0,0]
	s_nop 0
	v_pk_fma_f32 v[24:25], v[4:5], v[26:27], v[24:25] neg_lo:[1,0,0] neg_hi:[1,0,0]
	s_nop 0
	v_pk_fma_f32 v[24:25], v[6:7], v[34:35], v[24:25] neg_lo:[1,0,0] neg_hi:[1,0,0]
	s_nop 0
	v_pk_fma_f32 v[24:25], v[8:9], v[36:37], v[24:25] neg_lo:[1,0,0] neg_hi:[1,0,0]
	s_nop 0
	v_pk_fma_f32 v[24:25], v[10:11], v[38:39], v[24:25] neg_lo:[1,0,0] neg_hi:[1,0,0]
	s_nop 0
	v_pk_fma_f32 v[24:25], v[12:13], v[40:41], v[24:25] neg_lo:[1,0,0] neg_hi:[1,0,0]
	s_nop 0
	v_pk_fma_f32 v[24:25], v[14:15], v[42:43], v[24:25] neg_lo:[1,0,0] neg_hi:[1,0,0]
	s_nop 0
	v_pk_fma_f32 v[24:25], v[16:17], v[44:45], v[24:25] neg_lo:[1,0,0] neg_hi:[1,0,0]
	s_nop 0
	v_pk_fma_f32 v[24:25], v[18:19], v[70:71], v[24:25] neg_lo:[1,0,0] neg_hi:[1,0,0]
	s_nop 0
	v_pk_fma_f32 v[24:25], v[20:21], v[72:73], v[24:25] neg_lo:[1,0,0] neg_hi:[1,0,0]
	s_nop 0
	s_waitcnt lgkmcnt(0)
	v_mul_f32_e32 v0, v0, v23
	v_fma_f32 v23, -v74, v22, v24
	v_add_f32_e32 v23, v25, v23
	v_mov_b32_e32 v24, 0x19f00
	ds_read_b128 v[32:35], v24
	v_mov_b32_e32 v24, 0x19f10
	ds_read_b128 v[36:39], v24
	v_mov_b32_e32 v24, 0x19f20
	ds_read_b128 v[40:43], v24
	v_mov_b32_e32 v24, 0x19f30
	ds_read_b128 v[70:73], v24
	v_or_b32_e32 v24, 0x1c85c, v67
	ds_read_b32 v24, v24
	ds_read_b32 v25, v66 offset:11776
	v_mov_b32_e32 v26, 0x19f40
	ds_read_b128 v[74:77], v26
	v_mov_b32_e32 v26, 0x19f50
	ds_read_b128 v[78:81], v26
	s_waitcnt lgkmcnt(0)
	v_mul_f32_e32 v64, v24, v25
	v_pk_fma_f32 v[24:25], v[2:3], v[28:29], v[0:1] neg_lo:[1,0,0] neg_hi:[1,0,0]
	s_nop 0
	v_pk_fma_f32 v[24:25], v[4:5], v[30:31], v[24:25] neg_lo:[1,0,0] neg_hi:[1,0,0]
	s_nop 0
	v_pk_fma_f32 v[24:25], v[6:7], v[46:47], v[24:25] neg_lo:[1,0,0] neg_hi:[1,0,0]
	s_nop 0
	v_pk_fma_f32 v[24:25], v[8:9], v[48:49], v[24:25] neg_lo:[1,0,0] neg_hi:[1,0,0]
	s_nop 0
	v_pk_fma_f32 v[24:25], v[10:11], v[52:53], v[24:25] neg_lo:[1,0,0] neg_hi:[1,0,0]
	s_nop 0
	v_pk_fma_f32 v[24:25], v[12:13], v[54:55], v[24:25] neg_lo:[1,0,0] neg_hi:[1,0,0]
	s_nop 0
	v_pk_fma_f32 v[24:25], v[14:15], v[56:57], v[24:25] neg_lo:[1,0,0] neg_hi:[1,0,0]
	s_nop 0
	v_pk_fma_f32 v[24:25], v[16:17], v[58:59], v[24:25] neg_lo:[1,0,0] neg_hi:[1,0,0]
	s_nop 0
	v_pk_fma_f32 v[24:25], v[18:19], v[60:61], v[24:25] neg_lo:[1,0,0] neg_hi:[1,0,0]
	s_nop 0
	v_pk_fma_f32 v[24:25], v[20:21], v[62:63], v[24:25] neg_lo:[1,0,0] neg_hi:[1,0,0]
	s_nop 0
	v_pk_fma_f32 v[24:25], v[84:85], v[22:23], v[24:25] neg_lo:[1,0,0] neg_hi:[1,0,0]
	s_nop 0
	v_pk_add_f32 v[24:25], v[24:25], v[24:25] op_sel:[0,1] op_sel_hi:[1,0]
	v_mov_b32_e32 v0, 0x1a000
	ds_read_b128 v[26:29], v0
	v_mov_b32_e32 v0, 0x1a010
	ds_read_b128 v[44:47], v0
	v_mov_b32_e32 v0, 0x1a020
	ds_read_b128 v[52:55], v0
	v_mov_b32_e32 v0, 0x1a030
	ds_read_b128 v[56:59], v0
	v_or_b32_e32 v0, 0x1c860, v67
	v_mov_b32_e32 v30, 0x1a040
	ds_read_b32 v0, v0
	ds_read_b32 v25, v66 offset:12288
	ds_read_b128 v[60:63], v30
	v_mov_b32_e32 v30, 0x1a050
	ds_read_b128 v[84:87], v30
	v_pk_fma_f32 v[30:31], v[2:3], v[32:33], v[64:65] neg_lo:[1,0,0] neg_hi:[1,0,0]
	s_nop 0
	v_pk_fma_f32 v[30:31], v[4:5], v[34:35], v[30:31] neg_lo:[1,0,0] neg_hi:[1,0,0]
	s_nop 0
	v_pk_fma_f32 v[30:31], v[6:7], v[36:37], v[30:31] neg_lo:[1,0,0] neg_hi:[1,0,0]
	s_nop 0
	v_pk_fma_f32 v[30:31], v[8:9], v[38:39], v[30:31] neg_lo:[1,0,0] neg_hi:[1,0,0]
	s_nop 0
	v_pk_fma_f32 v[30:31], v[10:11], v[40:41], v[30:31] neg_lo:[1,0,0] neg_hi:[1,0,0]
	s_nop 0
	v_pk_fma_f32 v[30:31], v[12:13], v[42:43], v[30:31] neg_lo:[1,0,0] neg_hi:[1,0,0]
	s_nop 0
	v_pk_fma_f32 v[30:31], v[14:15], v[70:71], v[30:31] neg_lo:[1,0,0] neg_hi:[1,0,0]
	s_nop 0
	v_pk_fma_f32 v[30:31], v[16:17], v[72:73], v[30:31] neg_lo:[1,0,0] neg_hi:[1,0,0]
	s_nop 0
	v_pk_fma_f32 v[30:31], v[18:19], v[74:75], v[30:31] neg_lo:[1,0,0] neg_hi:[1,0,0]
	s_nop 0
	v_pk_fma_f32 v[30:31], v[20:21], v[76:77], v[30:31] neg_lo:[1,0,0] neg_hi:[1,0,0]
	s_nop 0
	v_pk_fma_f32 v[30:31], v[22:23], v[78:79], v[30:31] neg_lo:[1,0,0] neg_hi:[1,0,0]
	s_nop 0
	s_waitcnt lgkmcnt(0)
; DI void gdn_prep_item(const Params& P, int l, int n, int hh, char* smem) {
;     ...
;     for (int i = 1; i < 64; ++i) {
;       f32x4 (&CUR)[16] = (i & 1) ? LA : LB; f32x4 (&NXT)[16] = (i & 1) ? LB : LA;
;       if (i + 1 < 64) {
; #pragma unroll
;         for (int c = 0; c < (i + 4) / 4; ++c) NXT[c] = *(const f32x4*)(Lm + (i + 1) * 64 + 4 * c);
;         rh[(i + 1) & 1] = sp[i + 1] * rp[(i + 1) * 128];
;       }
;       __builtin_amdgcn_sched_barrier(0);
;       f32x2 acc = {rh[i & 1], 0.f};
; #pragma unroll
;       for (int p = 0; p < i / 2; ++p) { const f32x2 lp = (p & 1) ? (f32x2){CUR[p >> 1].z, CUR[p >> 1].w} : (f32x2){CUR[p >> 1].x, CUR[p >> 1].y}; acc = acc - lp * xx[p]; }
;       if (i & 1) { const int j = i - 1; const float lj = ((j & 3) == 0) ? CUR[j >> 2].x : CUR[j >> 2].z; acc.x = fmaf(-lj, xx[j >> 1].x, acc.x); }
;       const float xi = acc.x + acc.y;
;       if (i & 1) xx[i >> 1].y = xi; else xx[i >> 1].x = xi;
;       __builtin_amdgcn_sched_barrier(0);
;     }
	v_mul_f32_e32 v0, v0, v25
	v_fma_f32 v25, -v80, v24, v30
	v_add_f32_e32 v25, v31, v25
	v_mov_b32_e32 v38, 0x1a120
	v_mov_b32_e32 v42, 0x1a130
	v_mov_b32_e32 v30, 0x1a100
	v_mov_b32_e32 v34, 0x1a110
	ds_read_b128 v[38:41], v38
	ds_read_b128 v[70:73], v42
	v_or_b32_e32 v42, 0x1c864, v67
	v_mov_b32_e32 v43, 0x1a160
	ds_read_b128 v[30:33], v30
	ds_read_b128 v[34:37], v34
	ds_read_b128 v[74:77], v43
	ds_read_b32 v42, v42
	ds_read_b32 v43, v66 offset:12800
	v_mov_b32_e32 v48, 0x1a140
	s_waitcnt lgkmcnt(0)
	ds_read_b128 v[76:79], v48
	v_mov_b32_e32 v48, 0x1a150
	ds_read_b128 v[88:91], v48
	v_mul_f32_e32 v64, v42, v43
	v_pk_fma_f32 v[26:27], v[2:3], v[26:27], v[0:1] neg_lo:[1,0,0] neg_hi:[1,0,0]
	s_nop 0
	v_pk_fma_f32 v[26:27], v[4:5], v[28:29], v[26:27] neg_lo:[1,0,0] neg_hi:[1,0,0]
	s_nop 0
	v_pk_fma_f32 v[26:27], v[6:7], v[44:45], v[26:27] neg_lo:[1,0,0] neg_hi:[1,0,0]
	s_nop 0
	v_pk_fma_f32 v[26:27], v[8:9], v[46:47], v[26:27] neg_lo:[1,0,0] neg_hi:[1,0,0]
	s_nop 0
	v_pk_fma_f32 v[26:27], v[10:11], v[52:53], v[26:27] neg_lo:[1,0,0] neg_hi:[1,0,0]
	s_nop 0
	v_pk_fma_f32 v[26:27], v[12:13], v[54:55], v[26:27] neg_lo:[1,0,0] neg_hi:[1,0,0]
	s_nop 0
	v_pk_fma_f32 v[26:27], v[14:15], v[56:57], v[26:27] neg_lo:[1,0,0] neg_hi:[1,0,0]
	s_nop 0
	v_pk_fma_f32 v[26:27], v[16:17], v[58:59], v[26:27] neg_lo:[1,0,0] neg_hi:[1,0,0]
	s_nop 0
	v_pk_fma_f32 v[26:27], v[18:19], v[60:61], v[26:27] neg_lo:[1,0,0] neg_hi:[1,0,0]
	s_nop 0
	v_pk_fma_f32 v[26:27], v[20:21], v[62:63], v[26:27] neg_lo:[1,0,0] neg_hi:[1,0,0]
	s_nop 0
	v_pk_fma_f32 v[26:27], v[22:23], v[84:85], v[26:27] neg_lo:[1,0,0] neg_hi:[1,0,0]
	s_nop 0
	v_pk_fma_f32 v[26:27], v[86:87], v[24:25], v[26:27] neg_lo:[1,0,0] neg_hi:[1,0,0]
	s_nop 0
	v_pk_add_f32 v[26:27], v[26:27], v[26:27] op_sel:[0,1] op_sel_hi:[1,0]
	v_mov_b32_e32 v0, 0x1a200
	ds_read_b128 v[42:45], v0
	v_mov_b32_e32 v0, 0x1a210
	ds_read_b128 v[46:49], v0
	v_mov_b32_e32 v0, 0x1a220
	ds_read_b128 v[52:55], v0
	v_mov_b32_e32 v0, 0x1a230
	ds_read_b128 v[56:59], v0
	v_or_b32_e32 v0, 0x1c868, v67
	v_mov_b32_e32 v27, 0x1a260
	v_mov_b32_e32 v60, 0x1a240
	ds_read_b64 v[28:29], v27
	ds_read_b32 v0, v0
	ds_read_b32 v27, v66 offset:13312
	ds_read_b128 v[60:63], v60
	v_mov_b32_e32 v65, 0x1a250
	ds_read_b128 v[84:87], v65
	v_mov_b32_e32 v65, v1
	v_pk_fma_f32 v[30:31], v[2:3], v[30:31], v[64:65] neg_lo:[1,0,0] neg_hi:[1,0,0]
	s_nop 0
	v_pk_fma_f32 v[30:31], v[4:5], v[32:33], v[30:31] neg_lo:[1,0,0] neg_hi:[1,0,0]
	s_nop 0
	v_pk_fma_f32 v[30:31], v[6:7], v[34:35], v[30:31] neg_lo:[1,0,0] neg_hi:[1,0,0]
	s_nop 0
	v_pk_fma_f32 v[30:31], v[8:9], v[36:37], v[30:31] neg_lo:[1,0,0] neg_hi:[1,0,0]
	s_nop 0
	v_pk_fma_f32 v[30:31], v[10:11], v[38:39], v[30:31] neg_lo:[1,0,0] neg_hi:[1,0,0]
	s_nop 0
	v_pk_fma_f32 v[30:31], v[12:13], v[40:41], v[30:31] neg_lo:[1,0,0] neg_hi:[1,0,0]
	s_nop 0
	v_pk_fma_f32 v[30:31], v[14:15], v[70:71], v[30:31] neg_lo:[1,0,0] neg_hi:[1,0,0]
	s_nop 0
	v_pk_fma_f32 v[30:31], v[16:17], v[72:73], v[30:31] neg_lo:[1,0,0] neg_hi:[1,0,0]
	s_nop 0
	s_waitcnt lgkmcnt(0)
	v_mul_f32_e32 v0, v0, v27
	v_pk_fma_f32 v[30:31], v[18:19], v[76:77], v[30:31] neg_lo:[1,0,0] neg_hi:[1,0,0]
	s_nop 0
	v_pk_fma_f32 v[30:31], v[20:21], v[78:79], v[30:31] neg_lo:[1,0,0] neg_hi:[1,0,0]
	s_nop 0
	v_pk_fma_f32 v[30:31], v[22:23], v[88:89], v[30:31] neg_lo:[1,0,0] neg_hi:[1,0,0]
	s_nop 0
	v_pk_fma_f32 v[30:31], v[24:25], v[90:91], v[30:31] neg_lo:[1,0,0] neg_hi:[1,0,0]
	s_nop 0
	v_fma_f32 v27, -v74, v26, v30
	v_add_f32_e32 v27, v31, v27
	v_mov_b32_e32 v38, 0x1a320
	v_mov_b32_e32 v64, 0x1a330
	v_mov_b32_e32 v30, 0x1a300
	v_mov_b32_e32 v34, 0x1a310
	ds_read_b128 v[38:41], v38
	ds_read_b128 v[70:73], v64
	v_or_b32_e32 v64, 0x1c86c, v67
	v_mov_b32_e32 v65, 0x1a360
	ds_read_b128 v[30:33], v30
	ds_read_b128 v[34:37], v34
	ds_read_b128 v[74:77], v65
	ds_read_b32 v64, v64
	ds_read_b32 v65, v66 offset:13824
	s_waitcnt lgkmcnt(0)
	v_mov_b32_e32 v77, 0x1a340
	ds_read_b128 v[78:81], v77
	v_mov_b32_e32 v77, 0x1a350
	ds_read_b128 v[88:91], v77
	v_mul_f32_e32 v64, v64, v65
	v_pk_fma_f32 v[42:43], v[2:3], v[42:43], v[0:1] neg_lo:[1,0,0] neg_hi:[1,0,0]
	s_nop 0
	v_pk_fma_f32 v[42:43], v[4:5], v[44:45], v[42:43] neg_lo:[1,0,0] neg_hi:[1,0,0]
	s_nop 0
	v_pk_fma_f32 v[42:43], v[6:7], v[46:47], v[42:43] neg_lo:[1,0,0] neg_hi:[1,0,0]
	s_nop 0
	v_pk_fma_f32 v[42:43], v[8:9], v[48:49], v[42:43] neg_lo:[1,0,0] neg_hi:[1,0,0]
	s_nop 0
	v_pk_fma_f32 v[42:43], v[10:11], v[52:53], v[42:43] neg_lo:[1,0,0] neg_hi:[1,0,0]
	s_nop 0
	v_pk_fma_f32 v[42:43], v[12:13], v[54:55], v[42:43] neg_lo:[1,0,0] neg_hi:[1,0,0]
	s_nop 0
	v_pk_fma_f32 v[42:43], v[14:15], v[56:57], v[42:43] neg_lo:[1,0,0] neg_hi:[1,0,0]
	s_nop 0
	v_pk_fma_f32 v[42:43], v[16:17], v[58:59], v[42:43] neg_lo:[1,0,0] neg_hi:[1,0,0]
	s_nop 0
	v_pk_fma_f32 v[42:43], v[18:19], v[60:61], v[42:43] neg_lo:[1,0,0] neg_hi:[1,0,0]
	s_nop 0
	v_pk_fma_f32 v[42:43], v[20:21], v[62:63], v[42:43] neg_lo:[1,0,0] neg_hi:[1,0,0]
	s_nop 0
	v_pk_fma_f32 v[42:43], v[22:23], v[84:85], v[42:43] neg_lo:[1,0,0] neg_hi:[1,0,0]
	s_nop 0
	v_pk_fma_f32 v[42:43], v[24:25], v[86:87], v[42:43] neg_lo:[1,0,0] neg_hi:[1,0,0]
	s_nop 0
	v_pk_fma_f32 v[28:29], v[28:29], v[26:27], v[42:43] neg_lo:[1,0,0] neg_hi:[1,0,0]
	s_nop 0
	v_pk_add_f32 v[28:29], v[28:29], v[28:29] op_sel:[0,1] op_sel_hi:[1,0]
	v_mov_b32_e32 v0, 0x1a400
	ds_read_b128 v[42:45], v0
	v_mov_b32_e32 v0, 0x1a410
	ds_read_b128 v[46:49], v0
	v_mov_b32_e32 v0, 0x1a420
	ds_read_b128 v[52:55], v0
	v_mov_b32_e32 v0, 0x1a430
	ds_read_b128 v[56:59], v0
	v_or_b32_e32 v0, 0x1c870, v67
	v_mov_b32_e32 v29, 0x1a460
	v_mov_b32_e32 v65, 0x1a440
	ds_read_b128 v[60:63], v29
	ds_read_b32 v0, v0
	ds_read_b32 v29, v66 offset:14336
	ds_read_b128 v[84:87], v65
	v_mov_b32_e32 v65, 0x1a450
	ds_read_b128 v[92:95], v65
	v_mov_b32_e32 v65, v1
	v_pk_fma_f32 v[30:31], v[2:3], v[30:31], v[64:65] neg_lo:[1,0,0] neg_hi:[1,0,0]
	s_nop 0
	v_pk_fma_f32 v[30:31], v[4:5], v[32:33], v[30:31] neg_lo:[1,0,0] neg_hi:[1,0,0]
	s_nop 0
	v_pk_fma_f32 v[30:31], v[6:7], v[34:35], v[30:31] neg_lo:[1,0,0] neg_hi:[1,0,0]
	s_nop 0
	v_pk_fma_f32 v[30:31], v[8:9], v[36:37], v[30:31] neg_lo:[1,0,0] neg_hi:[1,0,0]
	s_nop 0
	v_pk_fma_f32 v[30:31], v[10:11], v[38:39], v[30:31] neg_lo:[1,0,0] neg_hi:[1,0,0]
	s_nop 0
	v_pk_fma_f32 v[30:31], v[12:13], v[40:41], v[30:31] neg_lo:[1,0,0] neg_hi:[1,0,0]
	s_nop 0
	v_pk_fma_f32 v[30:31], v[14:15], v[70:71], v[30:31] neg_lo:[1,0,0] neg_hi:[1,0,0]
	s_nop 0
	v_pk_fma_f32 v[30:31], v[16:17], v[72:73], v[30:31] neg_lo:[1,0,0] neg_hi:[1,0,0]
	s_nop 0
	s_waitcnt lgkmcnt(0)
; DI void gdn_prep_item(const Params& P, int l, int n, int hh, char* smem) {
;     ...
;     for (int i = 1; i < 64; ++i) {
;       f32x4 (&CUR)[16] = (i & 1) ? LA : LB; f32x4 (&NXT)[16] = (i & 1) ? LB : LA;
;       if (i + 1 < 64) {
; #pragma unroll
;         for (int c = 0; c < (i + 4) / 4; ++c) NXT[c] = *(const f32x4*)(Lm + (i + 1) * 64 + 4 * c);
;         rh[(i + 1) & 1] = sp[i + 1] * rp[(i + 1) * 128];
;       }
;       __builtin_amdgcn_sched_barrier(0);
;       f32x2 acc = {rh[i & 1], 0.f};
; #pragma unroll
;       for (int p = 0; p < i / 2; ++p) { const f32x2 lp = (p & 1) ? (f32x2){CUR[p >> 1].z, CUR[p >> 1].w} : (f32x2){CUR[p >> 1].x, CUR[p >> 1].y}; acc = acc - lp * xx[p]; }
;       if (i & 1) { const int j = i - 1; const float lj = ((j & 3) == 0) ? CUR[j >> 2].x : CUR[j >> 2].z; acc.x = fmaf(-lj, xx[j >> 1].x, acc.x); }
;       const float xi = acc.x + acc.y;
;       if (i & 1) xx[i >> 1].y = xi; else xx[i >> 1].x = xi;
;       __builtin_amdgcn_sched_barrier(0);
;     }
	v_mul_f32_e32 v0, v0, v29
	v_pk_fma_f32 v[30:31], v[18:19], v[78:79], v[30:31] neg_lo:[1,0,0] neg_hi:[1,0,0]
	s_nop 0
	v_pk_fma_f32 v[30:31], v[20:21], v[80:81], v[30:31] neg_lo:[1,0,0] neg_hi:[1,0,0]
	s_nop 0
	v_pk_fma_f32 v[30:31], v[22:23], v[88:89], v[30:31] neg_lo:[1,0,0] neg_hi:[1,0,0]
	s_nop 0
	v_pk_fma_f32 v[30:31], v[24:25], v[90:91], v[30:31] neg_lo:[1,0,0] neg_hi:[1,0,0]
	s_nop 0
	v_pk_fma_f32 v[30:31], v[26:27], v[74:75], v[30:31] neg_lo:[1,0,0] neg_hi:[1,0,0]
	s_nop 0
	v_fma_f32 v29, -v76, v28, v30
	v_add_f32_e32 v29, v31, v29
	v_mov_b32_e32 v30, 0x1a500
	ds_read_b128 v[32:35], v30
	v_mov_b32_e32 v30, 0x1a510
	ds_read_b128 v[36:39], v30
	v_mov_b32_e32 v30, 0x1a520
	ds_read_b128 v[70:73], v30
	v_mov_b32_e32 v30, 0x1a530
	ds_read_b128 v[74:77], v30
	v_mov_b32_e32 v30, 0x1a540
	ds_read_b128 v[78:81], v30
	v_mov_b32_e32 v30, 0x1a550
	ds_read_b128 v[88:91], v30
	v_mov_b32_e32 v30, 0x1a560
	ds_read_b128 v[96:99], v30
	v_mov_b32_e32 v30, 0x1a570
	ds_read_b128 v[100:103], v30
	v_or_b32_e32 v30, 0x1c874, v67
	ds_read_b32 v30, v30
	ds_read_b32 v31, v66 offset:14848
	s_waitcnt lgkmcnt(0)
	v_mul_f32_e32 v64, v30, v31
	v_pk_fma_f32 v[30:31], v[2:3], v[42:43], v[0:1] neg_lo:[1,0,0] neg_hi:[1,0,0]
	s_nop 0
	v_pk_fma_f32 v[30:31], v[4:5], v[44:45], v[30:31] neg_lo:[1,0,0] neg_hi:[1,0,0]
	s_nop 0
	v_pk_fma_f32 v[30:31], v[6:7], v[46:47], v[30:31] neg_lo:[1,0,0] neg_hi:[1,0,0]
	s_nop 0
	v_pk_fma_f32 v[30:31], v[8:9], v[48:49], v[30:31] neg_lo:[1,0,0] neg_hi:[1,0,0]
	s_nop 0
	v_pk_fma_f32 v[30:31], v[10:11], v[52:53], v[30:31] neg_lo:[1,0,0] neg_hi:[1,0,0]
	s_nop 0
	v_pk_fma_f32 v[30:31], v[12:13], v[54:55], v[30:31] neg_lo:[1,0,0] neg_hi:[1,0,0]
	s_nop 0
	v_pk_fma_f32 v[30:31], v[14:15], v[56:57], v[30:31] neg_lo:[1,0,0] neg_hi:[1,0,0]
	s_nop 0
	v_pk_fma_f32 v[30:31], v[16:17], v[58:59], v[30:31] neg_lo:[1,0,0] neg_hi:[1,0,0]
	s_nop 0
	v_pk_fma_f32 v[30:31], v[18:19], v[84:85], v[30:31] neg_lo:[1,0,0] neg_hi:[1,0,0]
	s_nop 0
	v_pk_fma_f32 v[30:31], v[20:21], v[86:87], v[30:31] neg_lo:[1,0,0] neg_hi:[1,0,0]
	s_nop 0
	v_pk_fma_f32 v[30:31], v[22:23], v[92:93], v[30:31] neg_lo:[1,0,0] neg_hi:[1,0,0]
	s_nop 0
	v_pk_fma_f32 v[30:31], v[24:25], v[94:95], v[30:31] neg_lo:[1,0,0] neg_hi:[1,0,0]
	s_nop 0
	v_pk_fma_f32 v[30:31], v[26:27], v[60:61], v[30:31] neg_lo:[1,0,0] neg_hi:[1,0,0]
	s_nop 0
	v_pk_fma_f32 v[30:31], v[62:63], v[28:29], v[30:31] neg_lo:[1,0,0] neg_hi:[1,0,0]
	s_nop 0
	v_pk_add_f32 v[30:31], v[30:31], v[30:31] op_sel:[0,1] op_sel_hi:[1,0]
	v_mov_b32_e32 v0, 0x1a600
	ds_read_b128 v[40:43], v0
	v_mov_b32_e32 v0, 0x1a610
	ds_read_b128 v[44:47], v0
	v_mov_b32_e32 v0, 0x1a620
	ds_read_b128 v[52:55], v0
	v_mov_b32_e32 v0, 0x1a630
	ds_read_b128 v[56:59], v0
	v_mov_b32_e32 v0, 0x1a640
	ds_read_b128 v[60:63], v0
	v_mov_b32_e32 v0, 0x1a650
	ds_read_b128 v[84:87], v0
	v_or_b32_e32 v0, 0x1c878, v67
	v_mov_b32_e32 v48, 0x1a660
	ds_read_b32 v0, v0
	ds_read_b32 v31, v66 offset:15360
	ds_read_b128 v[92:95], v48
	v_mov_b32_e32 v48, 0x1a670
	ds_read_b64 v[48:49], v48
	v_pk_fma_f32 v[32:33], v[2:3], v[32:33], v[64:65] neg_lo:[1,0,0] neg_hi:[1,0,0]
	s_nop 0
	v_pk_fma_f32 v[32:33], v[4:5], v[34:35], v[32:33] neg_lo:[1,0,0] neg_hi:[1,0,0]
	s_nop 0
	v_pk_fma_f32 v[32:33], v[6:7], v[36:37], v[32:33] neg_lo:[1,0,0] neg_hi:[1,0,0]
	s_nop 0
	v_pk_fma_f32 v[32:33], v[8:9], v[38:39], v[32:33] neg_lo:[1,0,0] neg_hi:[1,0,0]
	s_nop 0
	v_pk_fma_f32 v[32:33], v[10:11], v[70:71], v[32:33] neg_lo:[1,0,0] neg_hi:[1,0,0]
	s_nop 0
	v_pk_fma_f32 v[32:33], v[12:13], v[72:73], v[32:33] neg_lo:[1,0,0] neg_hi:[1,0,0]
	s_nop 0
	v_pk_fma_f32 v[32:33], v[14:15], v[74:75], v[32:33] neg_lo:[1,0,0] neg_hi:[1,0,0]
	s_nop 0
	v_pk_fma_f32 v[32:33], v[16:17], v[76:77], v[32:33] neg_lo:[1,0,0] neg_hi:[1,0,0]
	s_nop 0
	v_pk_fma_f32 v[32:33], v[18:19], v[78:79], v[32:33] neg_lo:[1,0,0] neg_hi:[1,0,0]
	s_nop 0
	v_pk_fma_f32 v[32:33], v[20:21], v[80:81], v[32:33] neg_lo:[1,0,0] neg_hi:[1,0,0]
	s_nop 0
	v_pk_fma_f32 v[32:33], v[22:23], v[88:89], v[32:33] neg_lo:[1,0,0] neg_hi:[1,0,0]
	s_nop 0
	v_pk_fma_f32 v[32:33], v[24:25], v[90:91], v[32:33] neg_lo:[1,0,0] neg_hi:[1,0,0]
	s_nop 0
	v_pk_fma_f32 v[32:33], v[26:27], v[96:97], v[32:33] neg_lo:[1,0,0] neg_hi:[1,0,0]
	s_nop 0
	v_pk_fma_f32 v[32:33], v[28:29], v[98:99], v[32:33] neg_lo:[1,0,0] neg_hi:[1,0,0]
	s_nop 0
	s_waitcnt lgkmcnt(0)
	v_mul_f32_e32 v0, v0, v31
	v_fma_f32 v31, -v100, v30, v32
	v_add_f32_e32 v31, v33, v31
	v_mov_b32_e32 v32, 0x1a700
	ds_read_b128 v[34:37], v32
	v_mov_b32_e32 v32, 0x1a710
	ds_read_b128 v[70:73], v32
	v_mov_b32_e32 v32, 0x1a720
	ds_read_b128 v[74:77], v32
	v_mov_b32_e32 v32, 0x1a730
	ds_read_b128 v[78:81], v32
	v_mov_b32_e32 v32, 0x1a740
	ds_read_b128 v[88:91], v32
	v_mov_b32_e32 v32, 0x1a750
	ds_read_b128 v[96:99], v32
	v_or_b32_e32 v32, 0x1c87c, v67
	ds_read_b32 v32, v32
	ds_read_b32 v33, v66 offset:15872
	v_mov_b32_e32 v38, 0x1a760
	ds_read_b128 v[100:103], v38
	v_mov_b32_e32 v38, 0x1a770
	ds_read_b128 v[104:107], v38
	s_waitcnt lgkmcnt(0)
; DI void gdn_prep_item(const Params& P, int l, int n, int hh, char* smem) {
;     ...
;     for (int i = 1; i < 64; ++i) {
;       f32x4 (&CUR)[16] = (i & 1) ? LA : LB; f32x4 (&NXT)[16] = (i & 1) ? LB : LA;
;       if (i + 1 < 64) {
; #pragma unroll
;         for (int c = 0; c < (i + 4) / 4; ++c) NXT[c] = *(const f32x4*)(Lm + (i + 1) * 64 + 4 * c);
;         rh[(i + 1) & 1] = sp[i + 1] * rp[(i + 1) * 128];
;       }
;       __builtin_amdgcn_sched_barrier(0);
;       f32x2 acc = {rh[i & 1], 0.f};
; #pragma unroll
;       for (int p = 0; p < i / 2; ++p) { const f32x2 lp = (p & 1) ? (f32x2){CUR[p >> 1].z, CUR[p >> 1].w} : (f32x2){CUR[p >> 1].x, CUR[p >> 1].y}; acc = acc - lp * xx[p]; }
;       if (i & 1) { const int j = i - 1; const float lj = ((j & 3) == 0) ? CUR[j >> 2].x : CUR[j >> 2].z; acc.x = fmaf(-lj, xx[j >> 1].x, acc.x); }
;       const float xi = acc.x + acc.y;
;       if (i & 1) xx[i >> 1].y = xi; else xx[i >> 1].x = xi;
;       __builtin_amdgcn_sched_barrier(0);
;     }
	v_mul_f32_e32 v64, v32, v33
	v_pk_fma_f32 v[32:33], v[2:3], v[40:41], v[0:1] neg_lo:[1,0,0] neg_hi:[1,0,0]
	s_nop 0
	v_pk_fma_f32 v[32:33], v[4:5], v[42:43], v[32:33] neg_lo:[1,0,0] neg_hi:[1,0,0]
	s_nop 0
	v_pk_fma_f32 v[32:33], v[6:7], v[44:45], v[32:33] neg_lo:[1,0,0] neg_hi:[1,0,0]
	s_nop 0
	v_pk_fma_f32 v[32:33], v[8:9], v[46:47], v[32:33] neg_lo:[1,0,0] neg_hi:[1,0,0]
	s_nop 0
	v_pk_fma_f32 v[32:33], v[10:11], v[52:53], v[32:33] neg_lo:[1,0,0] neg_hi:[1,0,0]
	s_nop 0
	v_pk_fma_f32 v[32:33], v[12:13], v[54:55], v[32:33] neg_lo:[1,0,0] neg_hi:[1,0,0]
	s_nop 0
	v_pk_fma_f32 v[32:33], v[14:15], v[56:57], v[32:33] neg_lo:[1,0,0] neg_hi:[1,0,0]
	s_nop 0
	v_pk_fma_f32 v[32:33], v[16:17], v[58:59], v[32:33] neg_lo:[1,0,0] neg_hi:[1,0,0]
	s_nop 0
	v_pk_fma_f32 v[32:33], v[18:19], v[60:61], v[32:33] neg_lo:[1,0,0] neg_hi:[1,0,0]
	s_nop 0
	v_pk_fma_f32 v[32:33], v[20:21], v[62:63], v[32:33] neg_lo:[1,0,0] neg_hi:[1,0,0]
	s_nop 0
	v_pk_fma_f32 v[32:33], v[22:23], v[84:85], v[32:33] neg_lo:[1,0,0] neg_hi:[1,0,0]
	s_nop 0
	v_pk_fma_f32 v[32:33], v[24:25], v[86:87], v[32:33] neg_lo:[1,0,0] neg_hi:[1,0,0]
	s_nop 0
	v_pk_fma_f32 v[32:33], v[26:27], v[92:93], v[32:33] neg_lo:[1,0,0] neg_hi:[1,0,0]
	s_nop 0
	v_pk_fma_f32 v[32:33], v[28:29], v[94:95], v[32:33] neg_lo:[1,0,0] neg_hi:[1,0,0]
	s_nop 0
	v_pk_fma_f32 v[32:33], v[48:49], v[30:31], v[32:33] neg_lo:[1,0,0] neg_hi:[1,0,0]
	s_nop 0
	v_pk_add_f32 v[32:33], v[32:33], v[32:33] op_sel:[0,1] op_sel_hi:[1,0]
	v_mov_b32_e32 v0, 0x1a800
	ds_read_b128 v[38:41], v0
	v_mov_b32_e32 v0, 0x1a810
	ds_read_b128 v[42:45], v0
	v_mov_b32_e32 v0, 0x1a820
	ds_read_b128 v[46:49], v0
	v_mov_b32_e32 v0, 0x1a830
	ds_read_b128 v[52:55], v0
	v_mov_b32_e32 v0, 0x1a840
	ds_read_b128 v[56:59], v0
	v_mov_b32_e32 v0, 0x1a850
	ds_read_b128 v[60:63], v0
	v_or_b32_e32 v0, 0x1c880, v67
	v_mov_b32_e32 v65, 0x1a860
	ds_read_b32 v0, v0
	ds_read_b32 v33, v66 offset:16384
	ds_read_b128 v[84:87], v65
	v_mov_b32_e32 v65, 0x1a870
	ds_read_b128 v[92:95], v65
	v_mov_b32_e32 v65, v1
	v_pk_fma_f32 v[34:35], v[2:3], v[34:35], v[64:65] neg_lo:[1,0,0] neg_hi:[1,0,0]
	s_nop 0
	v_pk_fma_f32 v[34:35], v[4:5], v[36:37], v[34:35] neg_lo:[1,0,0] neg_hi:[1,0,0]
	s_nop 0
	v_pk_fma_f32 v[34:35], v[6:7], v[70:71], v[34:35] neg_lo:[1,0,0] neg_hi:[1,0,0]
	s_nop 0
	v_pk_fma_f32 v[34:35], v[8:9], v[72:73], v[34:35] neg_lo:[1,0,0] neg_hi:[1,0,0]
	s_nop 0
	v_pk_fma_f32 v[34:35], v[10:11], v[74:75], v[34:35] neg_lo:[1,0,0] neg_hi:[1,0,0]
	s_nop 0
	v_pk_fma_f32 v[34:35], v[12:13], v[76:77], v[34:35] neg_lo:[1,0,0] neg_hi:[1,0,0]
	s_nop 0
	v_pk_fma_f32 v[34:35], v[14:15], v[78:79], v[34:35] neg_lo:[1,0,0] neg_hi:[1,0,0]
	s_nop 0
	v_pk_fma_f32 v[34:35], v[16:17], v[80:81], v[34:35] neg_lo:[1,0,0] neg_hi:[1,0,0]
	s_nop 0
	v_pk_fma_f32 v[34:35], v[18:19], v[88:89], v[34:35] neg_lo:[1,0,0] neg_hi:[1,0,0]
	s_nop 0
	v_pk_fma_f32 v[34:35], v[20:21], v[90:91], v[34:35] neg_lo:[1,0,0] neg_hi:[1,0,0]
	s_nop 0
	v_pk_fma_f32 v[34:35], v[22:23], v[96:97], v[34:35] neg_lo:[1,0,0] neg_hi:[1,0,0]
	s_nop 0
	v_pk_fma_f32 v[34:35], v[24:25], v[98:99], v[34:35] neg_lo:[1,0,0] neg_hi:[1,0,0]
	s_nop 0
	v_pk_fma_f32 v[34:35], v[26:27], v[100:101], v[34:35] neg_lo:[1,0,0] neg_hi:[1,0,0]
	s_nop 0
	v_pk_fma_f32 v[34:35], v[28:29], v[102:103], v[34:35] neg_lo:[1,0,0] neg_hi:[1,0,0]
	s_nop 0
	v_pk_fma_f32 v[34:35], v[30:31], v[104:105], v[34:35] neg_lo:[1,0,0] neg_hi:[1,0,0]
	s_nop 0
	s_waitcnt lgkmcnt(0)
	v_mul_f32_e32 v0, v0, v33
	v_fma_f32 v33, -v106, v32, v34
	v_add_f32_e32 v33, v35, v33
	v_mov_b32_e32 v34, 0x1a900
	ds_read_b128 v[70:73], v34
	v_mov_b32_e32 v34, 0x1a910
	ds_read_b128 v[74:77], v34
	v_mov_b32_e32 v34, 0x1a920
	ds_read_b128 v[78:81], v34
	v_mov_b32_e32 v34, 0x1a930
	ds_read_b128 v[88:91], v34
	v_mov_b32_e32 v34, 0x1a940
	ds_read_b128 v[96:99], v34
	v_mov_b32_e32 v34, 0x1a950
	ds_read_b128 v[100:103], v34
	v_or_b32_e32 v34, 0x1c884, v67
	v_mov_b32_e32 v35, 0x1a980
	ds_read_b128 v[104:107], v35
	ds_read_b32 v34, v34
	ds_read_b32 v35, v66 offset:16896
	v_mov_b32_e32 v36, 0x1a960
	s_waitcnt lgkmcnt(0)
	ds_read_b128 v[106:109], v36
	v_mov_b32_e32 v36, 0x1a970
	ds_read_b128 v[110:113], v36
	v_mul_f32_e32 v64, v34, v35
	v_pk_fma_f32 v[34:35], v[2:3], v[38:39], v[0:1] neg_lo:[1,0,0] neg_hi:[1,0,0]
	s_nop 0
	v_pk_fma_f32 v[34:35], v[4:5], v[40:41], v[34:35] neg_lo:[1,0,0] neg_hi:[1,0,0]
	s_nop 0
	v_pk_fma_f32 v[34:35], v[6:7], v[42:43], v[34:35] neg_lo:[1,0,0] neg_hi:[1,0,0]
	s_nop 0
	v_pk_fma_f32 v[34:35], v[8:9], v[44:45], v[34:35] neg_lo:[1,0,0] neg_hi:[1,0,0]
	s_nop 0
	v_pk_fma_f32 v[34:35], v[10:11], v[46:47], v[34:35] neg_lo:[1,0,0] neg_hi:[1,0,0]
	s_nop 0
	v_pk_fma_f32 v[34:35], v[12:13], v[48:49], v[34:35] neg_lo:[1,0,0] neg_hi:[1,0,0]
	s_nop 0
	v_pk_fma_f32 v[34:35], v[14:15], v[52:53], v[34:35] neg_lo:[1,0,0] neg_hi:[1,0,0]
	s_nop 0
	v_pk_fma_f32 v[34:35], v[16:17], v[54:55], v[34:35] neg_lo:[1,0,0] neg_hi:[1,0,0]
	s_nop 0
	v_pk_fma_f32 v[34:35], v[18:19], v[56:57], v[34:35] neg_lo:[1,0,0] neg_hi:[1,0,0]
	s_nop 0
	v_pk_fma_f32 v[34:35], v[20:21], v[58:59], v[34:35] neg_lo:[1,0,0] neg_hi:[1,0,0]
	s_nop 0
	v_pk_fma_f32 v[34:35], v[22:23], v[60:61], v[34:35] neg_lo:[1,0,0] neg_hi:[1,0,0]
	s_nop 0
	v_pk_fma_f32 v[34:35], v[24:25], v[62:63], v[34:35] neg_lo:[1,0,0] neg_hi:[1,0,0]
	s_nop 0
	v_pk_fma_f32 v[34:35], v[26:27], v[84:85], v[34:35] neg_lo:[1,0,0] neg_hi:[1,0,0]
	s_nop 0
	v_pk_fma_f32 v[34:35], v[28:29], v[86:87], v[34:35] neg_lo:[1,0,0] neg_hi:[1,0,0]
	s_nop 0
	v_pk_fma_f32 v[34:35], v[30:31], v[92:93], v[34:35] neg_lo:[1,0,0] neg_hi:[1,0,0]
	s_nop 0
	v_pk_fma_f32 v[34:35], v[94:95], v[32:33], v[34:35] neg_lo:[1,0,0] neg_hi:[1,0,0]
	s_nop 0
; DI void gdn_prep_item(const Params& P, int l, int n, int hh, char* smem) {
;     ...
;     for (int i = 1; i < 64; ++i) {
;       f32x4 (&CUR)[16] = (i & 1) ? LA : LB; f32x4 (&NXT)[16] = (i & 1) ? LB : LA;
;       if (i + 1 < 64) {
; #pragma unroll
;         for (int c = 0; c < (i + 4) / 4; ++c) NXT[c] = *(const f32x4*)(Lm + (i + 1) * 64 + 4 * c);
;         rh[(i + 1) & 1] = sp[i + 1] * rp[(i + 1) * 128];
;       }
;       __builtin_amdgcn_sched_barrier(0);
;       f32x2 acc = {rh[i & 1], 0.f};
; #pragma unroll
;       for (int p = 0; p < i / 2; ++p) { const f32x2 lp = (p & 1) ? (f32x2){CUR[p >> 1].z, CUR[p >> 1].w} : (f32x2){CUR[p >> 1].x, CUR[p >> 1].y}; acc = acc - lp * xx[p]; }
;       if (i & 1) { const int j = i - 1; const float lj = ((j & 3) == 0) ? CUR[j >> 2].x : CUR[j >> 2].z; acc.x = fmaf(-lj, xx[j >> 1].x, acc.x); }
;       const float xi = acc.x + acc.y;
;       if (i & 1) xx[i >> 1].y = xi; else xx[i >> 1].x = xi;
;       __builtin_amdgcn_sched_barrier(0);
;     }
	v_pk_add_f32 v[34:35], v[34:35], v[34:35] op_sel:[0,1] op_sel_hi:[1,0]
	v_mov_b32_e32 v0, 0x1aa00
	ds_read_b128 v[36:39], v0
	v_mov_b32_e32 v0, 0x1aa10
	ds_read_b128 v[40:43], v0
	v_mov_b32_e32 v0, 0x1aa20
	ds_read_b128 v[44:47], v0
	v_mov_b32_e32 v0, 0x1aa30
	ds_read_b128 v[52:55], v0
	v_mov_b32_e32 v0, 0x1aa40
	ds_read_b128 v[56:59], v0
	v_mov_b32_e32 v0, 0x1aa50
	ds_read_b128 v[60:63], v0
	v_or_b32_e32 v0, 0x1c888, v67
	v_mov_b32_e32 v35, 0x1aa80
	v_mov_b32_e32 v65, 0x1aa60
	ds_read_b64 v[48:49], v35
	ds_read_b32 v0, v0
	ds_read_b32 v35, v66 offset:17408
	ds_read_b128 v[84:87], v65
	v_mov_b32_e32 v65, 0x1aa70
	ds_read_b128 v[92:95], v65
	v_mov_b32_e32 v65, v1
	v_pk_fma_f32 v[64:65], v[2:3], v[70:71], v[64:65] neg_lo:[1,0,0] neg_hi:[1,0,0]
	s_nop 0
	v_pk_fma_f32 v[64:65], v[4:5], v[72:73], v[64:65] neg_lo:[1,0,0] neg_hi:[1,0,0]
	s_nop 0
	v_pk_fma_f32 v[64:65], v[6:7], v[74:75], v[64:65] neg_lo:[1,0,0] neg_hi:[1,0,0]
	s_nop 0
	v_pk_fma_f32 v[64:65], v[8:9], v[76:77], v[64:65] neg_lo:[1,0,0] neg_hi:[1,0,0]
	s_nop 0
	v_pk_fma_f32 v[64:65], v[10:11], v[78:79], v[64:65] neg_lo:[1,0,0] neg_hi:[1,0,0]
	s_nop 0
	v_pk_fma_f32 v[64:65], v[12:13], v[80:81], v[64:65] neg_lo:[1,0,0] neg_hi:[1,0,0]
	s_nop 0
	v_pk_fma_f32 v[64:65], v[14:15], v[88:89], v[64:65] neg_lo:[1,0,0] neg_hi:[1,0,0]
	s_nop 0
	v_pk_fma_f32 v[64:65], v[16:17], v[90:91], v[64:65] neg_lo:[1,0,0] neg_hi:[1,0,0]
	s_nop 0
	v_pk_fma_f32 v[64:65], v[18:19], v[96:97], v[64:65] neg_lo:[1,0,0] neg_hi:[1,0,0]
	s_nop 0
	v_pk_fma_f32 v[64:65], v[20:21], v[98:99], v[64:65] neg_lo:[1,0,0] neg_hi:[1,0,0]
	s_nop 0
	v_pk_fma_f32 v[64:65], v[22:23], v[100:101], v[64:65] neg_lo:[1,0,0] neg_hi:[1,0,0]
	s_nop 0
	v_pk_fma_f32 v[64:65], v[24:25], v[102:103], v[64:65] neg_lo:[1,0,0] neg_hi:[1,0,0]
	s_nop 0
	s_waitcnt lgkmcnt(0)
	v_mul_f32_e32 v0, v0, v35
	v_pk_fma_f32 v[64:65], v[26:27], v[106:107], v[64:65] neg_lo:[1,0,0] neg_hi:[1,0,0]
	s_nop 0
	v_pk_fma_f32 v[64:65], v[28:29], v[108:109], v[64:65] neg_lo:[1,0,0] neg_hi:[1,0,0]
	s_nop 0
	v_pk_fma_f32 v[64:65], v[30:31], v[110:111], v[64:65] neg_lo:[1,0,0] neg_hi:[1,0,0]
	s_nop 0
	v_pk_fma_f32 v[64:65], v[32:33], v[112:113], v[64:65] neg_lo:[1,0,0] neg_hi:[1,0,0]
	s_nop 0
	v_fma_f32 v35, -v104, v34, v64
	v_add_f32_e32 v35, v65, v35
	v_mov_b32_e32 v64, 0x1ab00
	ds_read_b128 v[70:73], v64
	v_mov_b32_e32 v64, 0x1ab10
	ds_read_b128 v[74:77], v64
	v_mov_b32_e32 v64, 0x1ab20
	ds_read_b128 v[78:81], v64
	v_mov_b32_e32 v64, 0x1ab30
	ds_read_b128 v[88:91], v64
	v_mov_b32_e32 v64, 0x1ab40
	ds_read_b128 v[96:99], v64
	v_mov_b32_e32 v64, 0x1ab50
	ds_read_b128 v[100:103], v64
	v_or_b32_e32 v64, 0x1c88c, v67
	v_mov_b32_e32 v65, 0x1ab80
	ds_read_b128 v[104:107], v65
	ds_read_b32 v64, v64
	ds_read_b32 v65, v66 offset:17920
	v_mov_b32_e32 v83, 0x1ab60
	ds_read_b128 v[108:111], v83
	v_mov_b32_e32 v83, 0x1ab70
	ds_read_b128 v[112:115], v83
	v_pk_fma_f32 v[36:37], v[2:3], v[36:37], v[0:1] neg_lo:[1,0,0] neg_hi:[1,0,0]
	s_nop 0
	v_pk_fma_f32 v[36:37], v[4:5], v[38:39], v[36:37] neg_lo:[1,0,0] neg_hi:[1,0,0]
	s_nop 0
	v_pk_fma_f32 v[36:37], v[6:7], v[40:41], v[36:37] neg_lo:[1,0,0] neg_hi:[1,0,0]
	s_nop 0
	v_pk_fma_f32 v[36:37], v[8:9], v[42:43], v[36:37] neg_lo:[1,0,0] neg_hi:[1,0,0]
	s_nop 0
	v_pk_fma_f32 v[36:37], v[10:11], v[44:45], v[36:37] neg_lo:[1,0,0] neg_hi:[1,0,0]
	s_nop 0
	v_pk_fma_f32 v[36:37], v[12:13], v[46:47], v[36:37] neg_lo:[1,0,0] neg_hi:[1,0,0]
	s_nop 0
	v_pk_fma_f32 v[36:37], v[14:15], v[52:53], v[36:37] neg_lo:[1,0,0] neg_hi:[1,0,0]
	s_nop 0
	v_pk_fma_f32 v[36:37], v[16:17], v[54:55], v[36:37] neg_lo:[1,0,0] neg_hi:[1,0,0]
	s_nop 0
	v_pk_fma_f32 v[36:37], v[18:19], v[56:57], v[36:37] neg_lo:[1,0,0] neg_hi:[1,0,0]
	s_nop 0
	v_pk_fma_f32 v[36:37], v[20:21], v[58:59], v[36:37] neg_lo:[1,0,0] neg_hi:[1,0,0]
	s_nop 0
	v_pk_fma_f32 v[36:37], v[22:23], v[60:61], v[36:37] neg_lo:[1,0,0] neg_hi:[1,0,0]
	s_nop 0
	v_pk_fma_f32 v[36:37], v[24:25], v[62:63], v[36:37] neg_lo:[1,0,0] neg_hi:[1,0,0]
	s_nop 0
	v_pk_fma_f32 v[36:37], v[26:27], v[84:85], v[36:37] neg_lo:[1,0,0] neg_hi:[1,0,0]
	s_nop 0
	v_pk_fma_f32 v[36:37], v[28:29], v[86:87], v[36:37] neg_lo:[1,0,0] neg_hi:[1,0,0]
	s_nop 0
	v_pk_fma_f32 v[36:37], v[30:31], v[92:93], v[36:37] neg_lo:[1,0,0] neg_hi:[1,0,0]
	s_nop 0
	v_pk_fma_f32 v[36:37], v[32:33], v[94:95], v[36:37] neg_lo:[1,0,0] neg_hi:[1,0,0]
	s_nop 0
	v_pk_fma_f32 v[36:37], v[48:49], v[34:35], v[36:37] neg_lo:[1,0,0] neg_hi:[1,0,0]
	s_nop 0
	v_pk_add_f32 v[36:37], v[36:37], v[36:37] op_sel:[0,1] op_sel_hi:[1,0]
	s_waitcnt lgkmcnt(0)
	v_mul_f32_e32 v64, v64, v65
	v_mov_b32_e32 v0, 0x1ac00
	ds_read_b128 v[38:41], v0
	v_mov_b32_e32 v0, 0x1ac10
	ds_read_b128 v[42:45], v0
	v_mov_b32_e32 v0, 0x1ac20
	ds_read_b128 v[46:49], v0
	v_mov_b32_e32 v0, 0x1ac30
	ds_read_b128 v[52:55], v0
	v_mov_b32_e32 v0, 0x1ac40
	ds_read_b128 v[56:59], v0
	v_mov_b32_e32 v0, 0x1ac50
	ds_read_b128 v[60:63], v0
	v_or_b32_e32 v0, 0x1c890, v67
	v_mov_b32_e32 v37, 0x1ac80
	v_mov_b32_e32 v65, 0x1ac60
	ds_read_b128 v[84:87], v37
	ds_read_b32 v0, v0
	ds_read_b32 v37, v66 offset:18432
	ds_read_b128 v[92:95], v65
	v_mov_b32_e32 v65, 0x1ac70
	ds_read_b128 v[116:119], v65
	v_mov_b32_e32 v65, v1
	v_pk_fma_f32 v[64:65], v[2:3], v[70:71], v[64:65] neg_lo:[1,0,0] neg_hi:[1,0,0]
	s_nop 0
	v_pk_fma_f32 v[64:65], v[4:5], v[72:73], v[64:65] neg_lo:[1,0,0] neg_hi:[1,0,0]
	s_nop 0
	v_pk_fma_f32 v[64:65], v[6:7], v[74:75], v[64:65] neg_lo:[1,0,0] neg_hi:[1,0,0]
	s_nop 0
	v_pk_fma_f32 v[64:65], v[8:9], v[76:77], v[64:65] neg_lo:[1,0,0] neg_hi:[1,0,0]
	s_nop 0
	v_pk_fma_f32 v[64:65], v[10:11], v[78:79], v[64:65] neg_lo:[1,0,0] neg_hi:[1,0,0]
	s_nop 0
	v_pk_fma_f32 v[64:65], v[12:13], v[80:81], v[64:65] neg_lo:[1,0,0] neg_hi:[1,0,0]
	s_nop 0
	v_pk_fma_f32 v[64:65], v[14:15], v[88:89], v[64:65] neg_lo:[1,0,0] neg_hi:[1,0,0]
	s_nop 0
	v_pk_fma_f32 v[64:65], v[16:17], v[90:91], v[64:65] neg_lo:[1,0,0] neg_hi:[1,0,0]
	s_nop 0
	v_pk_fma_f32 v[64:65], v[18:19], v[96:97], v[64:65] neg_lo:[1,0,0] neg_hi:[1,0,0]
	s_nop 0
	v_pk_fma_f32 v[64:65], v[20:21], v[98:99], v[64:65] neg_lo:[1,0,0] neg_hi:[1,0,0]
	s_nop 0
	v_pk_fma_f32 v[64:65], v[22:23], v[100:101], v[64:65] neg_lo:[1,0,0] neg_hi:[1,0,0]
	s_nop 0
	v_pk_fma_f32 v[64:65], v[24:25], v[102:103], v[64:65] neg_lo:[1,0,0] neg_hi:[1,0,0]
	s_nop 0
	v_pk_fma_f32 v[64:65], v[26:27], v[108:109], v[64:65] neg_lo:[1,0,0] neg_hi:[1,0,0]
	s_nop 0
	v_pk_fma_f32 v[64:65], v[28:29], v[110:111], v[64:65] neg_lo:[1,0,0] neg_hi:[1,0,0]
	s_nop 0
	v_pk_fma_f32 v[64:65], v[30:31], v[112:113], v[64:65] neg_lo:[1,0,0] neg_hi:[1,0,0]
	s_nop 0
	v_pk_fma_f32 v[64:65], v[32:33], v[114:115], v[64:65] neg_lo:[1,0,0] neg_hi:[1,0,0]
	s_nop 0
	v_pk_fma_f32 v[64:65], v[34:35], v[104:105], v[64:65] neg_lo:[1,0,0] neg_hi:[1,0,0]
	s_nop 0
	s_waitcnt lgkmcnt(0)
; DI void gdn_prep_item(const Params& P, int l, int n, int hh, char* smem) {
;     ...
;     for (int i = 1; i < 64; ++i) {
;       f32x4 (&CUR)[16] = (i & 1) ? LA : LB; f32x4 (&NXT)[16] = (i & 1) ? LB : LA;
;       if (i + 1 < 64) {
; #pragma unroll
;         for (int c = 0; c < (i + 4) / 4; ++c) NXT[c] = *(const f32x4*)(Lm + (i + 1) * 64 + 4 * c);
;         rh[(i + 1) & 1] = sp[i + 1] * rp[(i + 1) * 128];
;       }
;       __builtin_amdgcn_sched_barrier(0);
;       f32x2 acc = {rh[i & 1], 0.f};
; #pragma unroll
;       for (int p = 0; p < i / 2; ++p) { const f32x2 lp = (p & 1) ? (f32x2){CUR[p >> 1].z, CUR[p >> 1].w} : (f32x2){CUR[p >> 1].x, CUR[p >> 1].y}; acc = acc - lp * xx[p]; }
;       if (i & 1) { const int j = i - 1; const float lj = ((j & 3) == 0) ? CUR[j >> 2].x : CUR[j >> 2].z; acc.x = fmaf(-lj, xx[j >> 1].x, acc.x); }
;       const float xi = acc.x + acc.y;
;       if (i & 1) xx[i >> 1].y = xi; else xx[i >> 1].x = xi;
;       __builtin_amdgcn_sched_barrier(0);
;     }
	v_mul_f32_e32 v0, v0, v37
	v_fma_f32 v37, -v106, v36, v64
	v_add_f32_e32 v37, v65, v37
	v_mov_b32_e32 v64, 0x1ad00
	ds_read_b128 v[70:73], v64
	v_mov_b32_e32 v64, 0x1ad10
	ds_read_b128 v[74:77], v64
	v_mov_b32_e32 v64, 0x1ad20
	ds_read_b128 v[78:81], v64
	v_mov_b32_e32 v64, 0x1ad30
	ds_read_b128 v[88:91], v64
	v_mov_b32_e32 v64, 0x1ad40
	ds_read_b128 v[96:99], v64
	v_mov_b32_e32 v64, 0x1ad50
	ds_read_b128 v[100:103], v64
	v_mov_b32_e32 v64, 0x1ad60
	ds_read_b128 v[104:107], v64
	v_mov_b32_e32 v64, 0x1ad70
	ds_read_b128 v[108:111], v64
	v_mov_b32_e32 v64, 0x1ad80
	ds_read_b128 v[112:115], v64
	v_mov_b32_e32 v64, 0x1ad90
	ds_read_b128 v[120:123], v64
	v_or_b32_e32 v64, 0x1c894, v67
	ds_read_b32 v64, v64
	ds_read_b32 v65, v66 offset:18944
	v_pk_fma_f32 v[38:39], v[2:3], v[38:39], v[0:1] neg_lo:[1,0,0] neg_hi:[1,0,0]
	s_nop 0
	v_pk_fma_f32 v[38:39], v[4:5], v[40:41], v[38:39] neg_lo:[1,0,0] neg_hi:[1,0,0]
	s_nop 0
	v_pk_fma_f32 v[38:39], v[6:7], v[42:43], v[38:39] neg_lo:[1,0,0] neg_hi:[1,0,0]
	s_nop 0
	v_pk_fma_f32 v[38:39], v[8:9], v[44:45], v[38:39] neg_lo:[1,0,0] neg_hi:[1,0,0]
	s_nop 0
	v_pk_fma_f32 v[38:39], v[10:11], v[46:47], v[38:39] neg_lo:[1,0,0] neg_hi:[1,0,0]
	s_nop 0
	v_pk_fma_f32 v[38:39], v[12:13], v[48:49], v[38:39] neg_lo:[1,0,0] neg_hi:[1,0,0]
	s_nop 0
	v_pk_fma_f32 v[38:39], v[14:15], v[52:53], v[38:39] neg_lo:[1,0,0] neg_hi:[1,0,0]
	s_nop 0
	v_pk_fma_f32 v[38:39], v[16:17], v[54:55], v[38:39] neg_lo:[1,0,0] neg_hi:[1,0,0]
	s_nop 0
	v_pk_fma_f32 v[38:39], v[18:19], v[56:57], v[38:39] neg_lo:[1,0,0] neg_hi:[1,0,0]
	s_nop 0
	v_pk_fma_f32 v[38:39], v[20:21], v[58:59], v[38:39] neg_lo:[1,0,0] neg_hi:[1,0,0]
	s_nop 0
	v_pk_fma_f32 v[38:39], v[22:23], v[60:61], v[38:39] neg_lo:[1,0,0] neg_hi:[1,0,0]
	s_nop 0
	v_pk_fma_f32 v[38:39], v[24:25], v[62:63], v[38:39] neg_lo:[1,0,0] neg_hi:[1,0,0]
	s_nop 0
	v_pk_fma_f32 v[38:39], v[26:27], v[92:93], v[38:39] neg_lo:[1,0,0] neg_hi:[1,0,0]
	s_nop 0
	v_pk_fma_f32 v[38:39], v[28:29], v[94:95], v[38:39] neg_lo:[1,0,0] neg_hi:[1,0,0]
	s_nop 0
	v_pk_fma_f32 v[38:39], v[30:31], v[116:117], v[38:39] neg_lo:[1,0,0] neg_hi:[1,0,0]
	s_nop 0
	v_pk_fma_f32 v[38:39], v[32:33], v[118:119], v[38:39] neg_lo:[1,0,0] neg_hi:[1,0,0]
	s_nop 0
	v_pk_fma_f32 v[38:39], v[34:35], v[84:85], v[38:39] neg_lo:[1,0,0] neg_hi:[1,0,0]
	s_nop 0
	v_pk_fma_f32 v[38:39], v[86:87], v[36:37], v[38:39] neg_lo:[1,0,0] neg_hi:[1,0,0]
	s_nop 0
	v_pk_add_f32 v[38:39], v[38:39], v[38:39] op_sel:[0,1] op_sel_hi:[1,0]
	s_waitcnt lgkmcnt(0)
	v_mul_f32_e32 v64, v64, v65
	v_mov_b32_e32 v0, 0x1ae00
	ds_read_b128 v[40:43], v0
	v_mov_b32_e32 v0, 0x1ae10
	ds_read_b128 v[44:47], v0
	v_mov_b32_e32 v0, 0x1ae20
	ds_read_b128 v[52:55], v0
	v_mov_b32_e32 v0, 0x1ae30
	ds_read_b128 v[56:59], v0
	v_mov_b32_e32 v0, 0x1ae40
	ds_read_b128 v[60:63], v0
	v_mov_b32_e32 v0, 0x1ae50
	ds_read_b128 v[84:87], v0
	v_mov_b32_e32 v0, 0x1ae60
	ds_read_b128 v[92:95], v0
	v_mov_b32_e32 v0, 0x1ae70
	ds_read_b128 v[116:119], v0
	v_or_b32_e32 v0, 0x1c898, v67
	v_mov_b32_e32 v48, 0x1ae80
	ds_read_b32 v0, v0
	ds_read_b32 v39, v66 offset:19456
	ds_read_b128 v[122:125], v48
	v_mov_b32_e32 v48, 0x1ae90
	ds_read_b64 v[48:49], v48
	v_mov_b32_e32 v65, v1
	v_pk_fma_f32 v[64:65], v[2:3], v[70:71], v[64:65] neg_lo:[1,0,0] neg_hi:[1,0,0]
	s_nop 0
	v_pk_fma_f32 v[64:65], v[4:5], v[72:73], v[64:65] neg_lo:[1,0,0] neg_hi:[1,0,0]
	s_nop 0
	v_pk_fma_f32 v[64:65], v[6:7], v[74:75], v[64:65] neg_lo:[1,0,0] neg_hi:[1,0,0]
	s_nop 0
	v_pk_fma_f32 v[64:65], v[8:9], v[76:77], v[64:65] neg_lo:[1,0,0] neg_hi:[1,0,0]
	s_nop 0
	v_pk_fma_f32 v[64:65], v[10:11], v[78:79], v[64:65] neg_lo:[1,0,0] neg_hi:[1,0,0]
	s_nop 0
	v_pk_fma_f32 v[64:65], v[12:13], v[80:81], v[64:65] neg_lo:[1,0,0] neg_hi:[1,0,0]
	s_nop 0
	v_pk_fma_f32 v[64:65], v[14:15], v[88:89], v[64:65] neg_lo:[1,0,0] neg_hi:[1,0,0]
	s_nop 0
	v_pk_fma_f32 v[64:65], v[16:17], v[90:91], v[64:65] neg_lo:[1,0,0] neg_hi:[1,0,0]
	s_nop 0
	v_pk_fma_f32 v[64:65], v[18:19], v[96:97], v[64:65] neg_lo:[1,0,0] neg_hi:[1,0,0]
	s_nop 0
	v_pk_fma_f32 v[64:65], v[20:21], v[98:99], v[64:65] neg_lo:[1,0,0] neg_hi:[1,0,0]
	s_nop 0
	v_pk_fma_f32 v[64:65], v[22:23], v[100:101], v[64:65] neg_lo:[1,0,0] neg_hi:[1,0,0]
	s_nop 0
	v_pk_fma_f32 v[64:65], v[24:25], v[102:103], v[64:65] neg_lo:[1,0,0] neg_hi:[1,0,0]
	s_nop 0
	v_pk_fma_f32 v[64:65], v[26:27], v[104:105], v[64:65] neg_lo:[1,0,0] neg_hi:[1,0,0]
	s_nop 0
	v_pk_fma_f32 v[64:65], v[28:29], v[106:107], v[64:65] neg_lo:[1,0,0] neg_hi:[1,0,0]
	s_nop 0
	v_pk_fma_f32 v[64:65], v[30:31], v[108:109], v[64:65] neg_lo:[1,0,0] neg_hi:[1,0,0]
	s_nop 0
	v_pk_fma_f32 v[64:65], v[32:33], v[110:111], v[64:65] neg_lo:[1,0,0] neg_hi:[1,0,0]
	s_nop 0
	v_pk_fma_f32 v[64:65], v[34:35], v[112:113], v[64:65] neg_lo:[1,0,0] neg_hi:[1,0,0]
	s_nop 0
	v_pk_fma_f32 v[64:65], v[36:37], v[114:115], v[64:65] neg_lo:[1,0,0] neg_hi:[1,0,0]
	s_nop 0
	s_waitcnt lgkmcnt(0)
; DI void gdn_prep_item(const Params& P, int l, int n, int hh, char* smem) {
;     ...
;     for (int i = 1; i < 64; ++i) {
;       f32x4 (&CUR)[16] = (i & 1) ? LA : LB; f32x4 (&NXT)[16] = (i & 1) ? LB : LA;
;       if (i + 1 < 64) {
; #pragma unroll
;         for (int c = 0; c < (i + 4) / 4; ++c) NXT[c] = *(const f32x4*)(Lm + (i + 1) * 64 + 4 * c);
;         rh[(i + 1) & 1] = sp[i + 1] * rp[(i + 1) * 128];
;       }
;       __builtin_amdgcn_sched_barrier(0);
;       f32x2 acc = {rh[i & 1], 0.f};
; #pragma unroll
;       for (int p = 0; p < i / 2; ++p) { const f32x2 lp = (p & 1) ? (f32x2){CUR[p >> 1].z, CUR[p >> 1].w} : (f32x2){CUR[p >> 1].x, CUR[p >> 1].y}; acc = acc - lp * xx[p]; }
;       if (i & 1) { const int j = i - 1; const float lj = ((j & 3) == 0) ? CUR[j >> 2].x : CUR[j >> 2].z; acc.x = fmaf(-lj, xx[j >> 1].x, acc.x); }
;       const float xi = acc.x + acc.y;
;       if (i & 1) xx[i >> 1].y = xi; else xx[i >> 1].x = xi;
;       __builtin_amdgcn_sched_barrier(0);
;     }
	v_mul_f32_e32 v0, v0, v39
	v_fma_f32 v39, -v120, v38, v64
	v_add_f32_e32 v39, v65, v39
	v_mov_b32_e32 v64, 0x1af00
	ds_read_b128 v[70:73], v64
	v_mov_b32_e32 v64, 0x1af10
	ds_read_b128 v[74:77], v64
	v_mov_b32_e32 v64, 0x1af20
	ds_read_b128 v[78:81], v64
	v_mov_b32_e32 v64, 0x1af30
	ds_read_b128 v[88:91], v64
	v_mov_b32_e32 v64, 0x1af40
	ds_read_b128 v[96:99], v64
	v_mov_b32_e32 v64, 0x1af50
	ds_read_b128 v[100:103], v64
	v_mov_b32_e32 v64, 0x1af60
	ds_read_b128 v[104:107], v64
	v_mov_b32_e32 v64, 0x1af70
	ds_read_b128 v[108:111], v64
	v_or_b32_e32 v64, 0x1c89c, v67
	ds_read_b32 v64, v64
	ds_read_b32 v65, v66 offset:19968
	v_mov_b32_e32 v83, 0x1af80
	ds_read_b128 v[112:115], v83
	v_mov_b32_e32 v83, 0x1af90
	ds_read_b128 v[126:129], v83
	v_pk_fma_f32 v[40:41], v[2:3], v[40:41], v[0:1] neg_lo:[1,0,0] neg_hi:[1,0,0]
	s_nop 0
	v_pk_fma_f32 v[40:41], v[4:5], v[42:43], v[40:41] neg_lo:[1,0,0] neg_hi:[1,0,0]
	s_nop 0
	v_pk_fma_f32 v[40:41], v[6:7], v[44:45], v[40:41] neg_lo:[1,0,0] neg_hi:[1,0,0]
	s_nop 0
	v_pk_fma_f32 v[40:41], v[8:9], v[46:47], v[40:41] neg_lo:[1,0,0] neg_hi:[1,0,0]
	s_nop 0
	v_pk_fma_f32 v[40:41], v[10:11], v[52:53], v[40:41] neg_lo:[1,0,0] neg_hi:[1,0,0]
	s_nop 0
	v_pk_fma_f32 v[40:41], v[12:13], v[54:55], v[40:41] neg_lo:[1,0,0] neg_hi:[1,0,0]
	s_nop 0
	v_pk_fma_f32 v[40:41], v[14:15], v[56:57], v[40:41] neg_lo:[1,0,0] neg_hi:[1,0,0]
	s_nop 0
	v_pk_fma_f32 v[40:41], v[16:17], v[58:59], v[40:41] neg_lo:[1,0,0] neg_hi:[1,0,0]
	s_nop 0
	v_pk_fma_f32 v[40:41], v[18:19], v[60:61], v[40:41] neg_lo:[1,0,0] neg_hi:[1,0,0]
	s_nop 0
	v_pk_fma_f32 v[40:41], v[20:21], v[62:63], v[40:41] neg_lo:[1,0,0] neg_hi:[1,0,0]
	s_nop 0
	v_pk_fma_f32 v[40:41], v[22:23], v[84:85], v[40:41] neg_lo:[1,0,0] neg_hi:[1,0,0]
	s_nop 0
	v_pk_fma_f32 v[40:41], v[24:25], v[86:87], v[40:41] neg_lo:[1,0,0] neg_hi:[1,0,0]
	s_nop 0
	v_pk_fma_f32 v[40:41], v[26:27], v[92:93], v[40:41] neg_lo:[1,0,0] neg_hi:[1,0,0]
	s_nop 0
	v_pk_fma_f32 v[40:41], v[28:29], v[94:95], v[40:41] neg_lo:[1,0,0] neg_hi:[1,0,0]
	s_nop 0
	v_pk_fma_f32 v[40:41], v[30:31], v[116:117], v[40:41] neg_lo:[1,0,0] neg_hi:[1,0,0]
	s_nop 0
	v_pk_fma_f32 v[40:41], v[32:33], v[118:119], v[40:41] neg_lo:[1,0,0] neg_hi:[1,0,0]
	s_nop 0
	v_pk_fma_f32 v[40:41], v[34:35], v[122:123], v[40:41] neg_lo:[1,0,0] neg_hi:[1,0,0]
	s_nop 0
	v_pk_fma_f32 v[40:41], v[36:37], v[124:125], v[40:41] neg_lo:[1,0,0] neg_hi:[1,0,0]
	s_nop 0
	v_pk_fma_f32 v[40:41], v[48:49], v[38:39], v[40:41] neg_lo:[1,0,0] neg_hi:[1,0,0]
	s_nop 0
	v_pk_add_f32 v[40:41], v[40:41], v[40:41] op_sel:[0,1] op_sel_hi:[1,0]
	s_waitcnt lgkmcnt(0)
	v_mul_f32_e32 v64, v64, v65
	v_mov_b32_e32 v0, 0x1b000
	ds_read_b128 v[42:45], v0
	v_mov_b32_e32 v0, 0x1b010
	ds_read_b128 v[46:49], v0
	v_mov_b32_e32 v0, 0x1b020
	ds_read_b128 v[52:55], v0
	v_mov_b32_e32 v0, 0x1b030
	ds_read_b128 v[56:59], v0
	v_mov_b32_e32 v0, 0x1b040
	ds_read_b128 v[60:63], v0
	v_mov_b32_e32 v0, 0x1b050
	ds_read_b128 v[84:87], v0
	v_mov_b32_e32 v0, 0x1b060
	ds_read_b128 v[92:95], v0
	v_mov_b32_e32 v0, 0x1b070
	ds_read_b128 v[116:119], v0
	v_or_b32_e32 v0, 0x1c8a0, v67
	v_mov_b32_e32 v65, 0x1b080
	ds_read_b32 v0, v0
	ds_read_b32 v41, v66 offset:20480
	ds_read_b128 v[120:123], v65
	v_mov_b32_e32 v65, 0x1b090
	ds_read_b128 v[130:133], v65
	v_mov_b32_e32 v65, v1
	v_pk_fma_f32 v[64:65], v[2:3], v[70:71], v[64:65] neg_lo:[1,0,0] neg_hi:[1,0,0]
	s_nop 0
	v_pk_fma_f32 v[64:65], v[4:5], v[72:73], v[64:65] neg_lo:[1,0,0] neg_hi:[1,0,0]
	s_nop 0
	v_pk_fma_f32 v[64:65], v[6:7], v[74:75], v[64:65] neg_lo:[1,0,0] neg_hi:[1,0,0]
	s_nop 0
	v_pk_fma_f32 v[64:65], v[8:9], v[76:77], v[64:65] neg_lo:[1,0,0] neg_hi:[1,0,0]
	s_nop 0
	v_pk_fma_f32 v[64:65], v[10:11], v[78:79], v[64:65] neg_lo:[1,0,0] neg_hi:[1,0,0]
	s_nop 0
	v_pk_fma_f32 v[64:65], v[12:13], v[80:81], v[64:65] neg_lo:[1,0,0] neg_hi:[1,0,0]
	s_nop 0
	v_pk_fma_f32 v[64:65], v[14:15], v[88:89], v[64:65] neg_lo:[1,0,0] neg_hi:[1,0,0]
	s_nop 0
	v_pk_fma_f32 v[64:65], v[16:17], v[90:91], v[64:65] neg_lo:[1,0,0] neg_hi:[1,0,0]
	s_nop 0
	v_pk_fma_f32 v[64:65], v[18:19], v[96:97], v[64:65] neg_lo:[1,0,0] neg_hi:[1,0,0]
	s_nop 0
	v_pk_fma_f32 v[64:65], v[20:21], v[98:99], v[64:65] neg_lo:[1,0,0] neg_hi:[1,0,0]
	s_nop 0
	v_pk_fma_f32 v[64:65], v[22:23], v[100:101], v[64:65] neg_lo:[1,0,0] neg_hi:[1,0,0]
	s_nop 0
	v_pk_fma_f32 v[64:65], v[24:25], v[102:103], v[64:65] neg_lo:[1,0,0] neg_hi:[1,0,0]
	s_nop 0
	v_pk_fma_f32 v[64:65], v[26:27], v[104:105], v[64:65] neg_lo:[1,0,0] neg_hi:[1,0,0]
	s_nop 0
	v_pk_fma_f32 v[64:65], v[28:29], v[106:107], v[64:65] neg_lo:[1,0,0] neg_hi:[1,0,0]
	s_nop 0
	v_pk_fma_f32 v[64:65], v[30:31], v[108:109], v[64:65] neg_lo:[1,0,0] neg_hi:[1,0,0]
	s_nop 0
	v_pk_fma_f32 v[64:65], v[32:33], v[110:111], v[64:65] neg_lo:[1,0,0] neg_hi:[1,0,0]
	s_nop 0
	v_pk_fma_f32 v[64:65], v[34:35], v[112:113], v[64:65] neg_lo:[1,0,0] neg_hi:[1,0,0]
	s_nop 0
	v_pk_fma_f32 v[64:65], v[36:37], v[114:115], v[64:65] neg_lo:[1,0,0] neg_hi:[1,0,0]
	s_nop 0
	v_pk_fma_f32 v[64:65], v[38:39], v[126:127], v[64:65] neg_lo:[1,0,0] neg_hi:[1,0,0]
	s_nop 0
	s_waitcnt lgkmcnt(0)
; DI void gdn_prep_item(const Params& P, int l, int n, int hh, char* smem) {
;     ...
;     for (int i = 1; i < 64; ++i) {
;       f32x4 (&CUR)[16] = (i & 1) ? LA : LB; f32x4 (&NXT)[16] = (i & 1) ? LB : LA;
;       if (i + 1 < 64) {
; #pragma unroll
;         for (int c = 0; c < (i + 4) / 4; ++c) NXT[c] = *(const f32x4*)(Lm + (i + 1) * 64 + 4 * c);
;         rh[(i + 1) & 1] = sp[i + 1] * rp[(i + 1) * 128];
;       }
;       __builtin_amdgcn_sched_barrier(0);
;       f32x2 acc = {rh[i & 1], 0.f};
; #pragma unroll
;       for (int p = 0; p < i / 2; ++p) { const f32x2 lp = (p & 1) ? (f32x2){CUR[p >> 1].z, CUR[p >> 1].w} : (f32x2){CUR[p >> 1].x, CUR[p >> 1].y}; acc = acc - lp * xx[p]; }
;       if (i & 1) { const int j = i - 1; const float lj = ((j & 3) == 0) ? CUR[j >> 2].x : CUR[j >> 2].z; acc.x = fmaf(-lj, xx[j >> 1].x, acc.x); }
;       const float xi = acc.x + acc.y;
;       if (i & 1) xx[i >> 1].y = xi; else xx[i >> 1].x = xi;
;       __builtin_amdgcn_sched_barrier(0);
;     }
	v_mul_f32_e32 v0, v0, v41
	v_fma_f32 v41, -v128, v40, v64
	v_add_f32_e32 v41, v65, v41
	v_mov_b32_e32 v64, 0x1b100
	ds_read_b128 v[70:73], v64
	v_mov_b32_e32 v64, 0x1b110
	ds_read_b128 v[74:77], v64
	v_mov_b32_e32 v64, 0x1b120
	ds_read_b128 v[78:81], v64
	v_mov_b32_e32 v64, 0x1b130
	ds_read_b128 v[88:91], v64
	v_mov_b32_e32 v64, 0x1b140
	ds_read_b128 v[96:99], v64
	v_mov_b32_e32 v64, 0x1b150
	ds_read_b128 v[100:103], v64
	v_mov_b32_e32 v64, 0x1b160
	ds_read_b128 v[104:107], v64
	v_mov_b32_e32 v64, 0x1b170
	ds_read_b128 v[108:111], v64
	v_or_b32_e32 v64, 0x1c8a4, v67
	v_mov_b32_e32 v65, 0x1b1a0
	ds_read_b128 v[112:115], v65
	ds_read_b32 v64, v64
	ds_read_b32 v65, v66 offset:20992
	v_mov_b32_e32 v83, 0x1b180
	ds_read_b128 v[124:127], v83
	v_mov_b32_e32 v83, 0x1b190
	ds_read_b128 v[134:137], v83
	v_pk_fma_f32 v[42:43], v[2:3], v[42:43], v[0:1] neg_lo:[1,0,0] neg_hi:[1,0,0]
	s_nop 0
	v_pk_fma_f32 v[42:43], v[4:5], v[44:45], v[42:43] neg_lo:[1,0,0] neg_hi:[1,0,0]
	s_nop 0
	v_pk_fma_f32 v[42:43], v[6:7], v[46:47], v[42:43] neg_lo:[1,0,0] neg_hi:[1,0,0]
	s_nop 0
	v_pk_fma_f32 v[42:43], v[8:9], v[48:49], v[42:43] neg_lo:[1,0,0] neg_hi:[1,0,0]
	s_nop 0
	v_pk_fma_f32 v[42:43], v[10:11], v[52:53], v[42:43] neg_lo:[1,0,0] neg_hi:[1,0,0]
	s_nop 0
	v_pk_fma_f32 v[42:43], v[12:13], v[54:55], v[42:43] neg_lo:[1,0,0] neg_hi:[1,0,0]
	s_nop 0
	v_pk_fma_f32 v[42:43], v[14:15], v[56:57], v[42:43] neg_lo:[1,0,0] neg_hi:[1,0,0]
	s_nop 0
	v_pk_fma_f32 v[42:43], v[16:17], v[58:59], v[42:43] neg_lo:[1,0,0] neg_hi:[1,0,0]
	s_nop 0
	v_pk_fma_f32 v[42:43], v[18:19], v[60:61], v[42:43] neg_lo:[1,0,0] neg_hi:[1,0,0]
	s_nop 0
	v_pk_fma_f32 v[42:43], v[20:21], v[62:63], v[42:43] neg_lo:[1,0,0] neg_hi:[1,0,0]
	s_nop 0
	v_pk_fma_f32 v[42:43], v[22:23], v[84:85], v[42:43] neg_lo:[1,0,0] neg_hi:[1,0,0]
	s_nop 0
	v_pk_fma_f32 v[42:43], v[24:25], v[86:87], v[42:43] neg_lo:[1,0,0] neg_hi:[1,0,0]
	s_nop 0
	v_pk_fma_f32 v[42:43], v[26:27], v[92:93], v[42:43] neg_lo:[1,0,0] neg_hi:[1,0,0]
	s_nop 0
	v_pk_fma_f32 v[42:43], v[28:29], v[94:95], v[42:43] neg_lo:[1,0,0] neg_hi:[1,0,0]
	s_nop 0
	v_pk_fma_f32 v[42:43], v[30:31], v[116:117], v[42:43] neg_lo:[1,0,0] neg_hi:[1,0,0]
	s_nop 0
	v_pk_fma_f32 v[42:43], v[32:33], v[118:119], v[42:43] neg_lo:[1,0,0] neg_hi:[1,0,0]
	s_nop 0
	v_pk_fma_f32 v[42:43], v[34:35], v[120:121], v[42:43] neg_lo:[1,0,0] neg_hi:[1,0,0]
	s_nop 0
	v_pk_fma_f32 v[42:43], v[36:37], v[122:123], v[42:43] neg_lo:[1,0,0] neg_hi:[1,0,0]
	s_nop 0
	v_pk_fma_f32 v[42:43], v[38:39], v[130:131], v[42:43] neg_lo:[1,0,0] neg_hi:[1,0,0]
	s_nop 0
	v_pk_fma_f32 v[42:43], v[132:133], v[40:41], v[42:43] neg_lo:[1,0,0] neg_hi:[1,0,0]
	s_nop 0
	v_pk_add_f32 v[42:43], v[42:43], v[42:43] op_sel:[0,1] op_sel_hi:[1,0]
	s_waitcnt lgkmcnt(0)
	v_mul_f32_e32 v64, v64, v65
	v_mov_b32_e32 v0, 0x1b200
	ds_read_b128 v[44:47], v0
	v_mov_b32_e32 v0, 0x1b210
	ds_read_b128 v[52:55], v0
	v_mov_b32_e32 v0, 0x1b220
	ds_read_b128 v[56:59], v0
	v_mov_b32_e32 v0, 0x1b230
	ds_read_b128 v[60:63], v0
	v_mov_b32_e32 v0, 0x1b240
	ds_read_b128 v[84:87], v0
	v_mov_b32_e32 v0, 0x1b250
	ds_read_b128 v[92:95], v0
	v_mov_b32_e32 v0, 0x1b260
	ds_read_b128 v[114:117], v0
	v_mov_b32_e32 v0, 0x1b270
	ds_read_b128 v[118:121], v0
	v_or_b32_e32 v0, 0x1c8a8, v67
	v_mov_b32_e32 v43, 0x1b2a0
	v_mov_b32_e32 v65, 0x1b280
	ds_read_b64 v[48:49], v43
	ds_read_b32 v0, v0
	ds_read_b32 v43, v66 offset:21504
	ds_read_b128 v[128:131], v65
	v_mov_b32_e32 v65, 0x1b290
	ds_read_b128 v[138:141], v65
	v_mov_b32_e32 v65, v1
	v_pk_fma_f32 v[64:65], v[2:3], v[70:71], v[64:65] neg_lo:[1,0,0] neg_hi:[1,0,0]
	s_nop 0
	v_pk_fma_f32 v[64:65], v[4:5], v[72:73], v[64:65] neg_lo:[1,0,0] neg_hi:[1,0,0]
	s_nop 0
	v_pk_fma_f32 v[64:65], v[6:7], v[74:75], v[64:65] neg_lo:[1,0,0] neg_hi:[1,0,0]
	s_nop 0
	v_pk_fma_f32 v[64:65], v[8:9], v[76:77], v[64:65] neg_lo:[1,0,0] neg_hi:[1,0,0]
	s_nop 0
	v_pk_fma_f32 v[64:65], v[10:11], v[78:79], v[64:65] neg_lo:[1,0,0] neg_hi:[1,0,0]
	s_nop 0
	v_pk_fma_f32 v[64:65], v[12:13], v[80:81], v[64:65] neg_lo:[1,0,0] neg_hi:[1,0,0]
	s_nop 0
	v_pk_fma_f32 v[64:65], v[14:15], v[88:89], v[64:65] neg_lo:[1,0,0] neg_hi:[1,0,0]
	s_nop 0
	v_pk_fma_f32 v[64:65], v[16:17], v[90:91], v[64:65] neg_lo:[1,0,0] neg_hi:[1,0,0]
	s_nop 0
	v_pk_fma_f32 v[64:65], v[18:19], v[96:97], v[64:65] neg_lo:[1,0,0] neg_hi:[1,0,0]
	s_nop 0
	v_pk_fma_f32 v[64:65], v[20:21], v[98:99], v[64:65] neg_lo:[1,0,0] neg_hi:[1,0,0]
	s_nop 0
	v_pk_fma_f32 v[64:65], v[22:23], v[100:101], v[64:65] neg_lo:[1,0,0] neg_hi:[1,0,0]
	s_nop 0
	v_pk_fma_f32 v[64:65], v[24:25], v[102:103], v[64:65] neg_lo:[1,0,0] neg_hi:[1,0,0]
	s_nop 0
	v_pk_fma_f32 v[64:65], v[26:27], v[104:105], v[64:65] neg_lo:[1,0,0] neg_hi:[1,0,0]
	s_nop 0
	v_pk_fma_f32 v[64:65], v[28:29], v[106:107], v[64:65] neg_lo:[1,0,0] neg_hi:[1,0,0]
	s_nop 0
	v_pk_fma_f32 v[64:65], v[30:31], v[108:109], v[64:65] neg_lo:[1,0,0] neg_hi:[1,0,0]
	s_nop 0
	v_pk_fma_f32 v[64:65], v[32:33], v[110:111], v[64:65] neg_lo:[1,0,0] neg_hi:[1,0,0]
	s_nop 0
	v_pk_fma_f32 v[64:65], v[34:35], v[124:125], v[64:65] neg_lo:[1,0,0] neg_hi:[1,0,0]
	s_nop 0
	v_pk_fma_f32 v[64:65], v[36:37], v[126:127], v[64:65] neg_lo:[1,0,0] neg_hi:[1,0,0]
	s_nop 0
	v_pk_fma_f32 v[64:65], v[38:39], v[134:135], v[64:65] neg_lo:[1,0,0] neg_hi:[1,0,0]
	s_nop 0
	v_pk_fma_f32 v[64:65], v[40:41], v[136:137], v[64:65] neg_lo:[1,0,0] neg_hi:[1,0,0]
	s_nop 0
	s_waitcnt lgkmcnt(0)
; DI void gdn_prep_item(const Params& P, int l, int n, int hh, char* smem) {
;     ...
;     for (int i = 1; i < 64; ++i) {
;       f32x4 (&CUR)[16] = (i & 1) ? LA : LB; f32x4 (&NXT)[16] = (i & 1) ? LB : LA;
;       if (i + 1 < 64) {
; #pragma unroll
;         for (int c = 0; c < (i + 4) / 4; ++c) NXT[c] = *(const f32x4*)(Lm + (i + 1) * 64 + 4 * c);
;         rh[(i + 1) & 1] = sp[i + 1] * rp[(i + 1) * 128];
;       }
;       __builtin_amdgcn_sched_barrier(0);
;       f32x2 acc = {rh[i & 1], 0.f};
; #pragma unroll
;       for (int p = 0; p < i / 2; ++p) { const f32x2 lp = (p & 1) ? (f32x2){CUR[p >> 1].z, CUR[p >> 1].w} : (f32x2){CUR[p >> 1].x, CUR[p >> 1].y}; acc = acc - lp * xx[p]; }
;       if (i & 1) { const int j = i - 1; const float lj = ((j & 3) == 0) ? CUR[j >> 2].x : CUR[j >> 2].z; acc.x = fmaf(-lj, xx[j >> 1].x, acc.x); }
;       const float xi = acc.x + acc.y;
;       if (i & 1) xx[i >> 1].y = xi; else xx[i >> 1].x = xi;
;       __builtin_amdgcn_sched_barrier(0);
;     }
	v_mul_f32_e32 v0, v0, v43
	v_fma_f32 v43, -v112, v42, v64
	v_add_f32_e32 v43, v65, v43
	v_mov_b32_e32 v64, 0x1b300
	ds_read_b128 v[70:73], v64
	v_mov_b32_e32 v64, 0x1b310
	ds_read_b128 v[74:77], v64
	v_mov_b32_e32 v64, 0x1b320
	ds_read_b128 v[78:81], v64
	v_mov_b32_e32 v64, 0x1b330
	ds_read_b128 v[88:91], v64
	v_mov_b32_e32 v64, 0x1b340
	ds_read_b128 v[96:99], v64
	v_mov_b32_e32 v64, 0x1b350
	ds_read_b128 v[100:103], v64
	v_mov_b32_e32 v64, 0x1b360
	ds_read_b128 v[104:107], v64
	v_mov_b32_e32 v64, 0x1b370
	ds_read_b128 v[108:111], v64
	v_or_b32_e32 v64, 0x1c8ac, v67
	v_mov_b32_e32 v65, 0x1b3a0
	ds_read_b128 v[122:125], v65
	ds_read_b32 v64, v64
	ds_read_b32 v65, v66 offset:22016
	v_mov_b32_e32 v83, 0x1b380
	ds_read_b128 v[132:135], v83
	v_mov_b32_e32 v83, 0x1b390
	ds_read_b128 v[142:145], v83
	v_pk_fma_f32 v[44:45], v[2:3], v[44:45], v[0:1] neg_lo:[1,0,0] neg_hi:[1,0,0]
	s_nop 0
	v_pk_fma_f32 v[44:45], v[4:5], v[46:47], v[44:45] neg_lo:[1,0,0] neg_hi:[1,0,0]
	s_nop 0
	v_pk_fma_f32 v[44:45], v[6:7], v[52:53], v[44:45] neg_lo:[1,0,0] neg_hi:[1,0,0]
	s_nop 0
	v_pk_fma_f32 v[44:45], v[8:9], v[54:55], v[44:45] neg_lo:[1,0,0] neg_hi:[1,0,0]
	s_nop 0
	v_pk_fma_f32 v[44:45], v[10:11], v[56:57], v[44:45] neg_lo:[1,0,0] neg_hi:[1,0,0]
	s_nop 0
	v_pk_fma_f32 v[44:45], v[12:13], v[58:59], v[44:45] neg_lo:[1,0,0] neg_hi:[1,0,0]
	s_nop 0
	v_pk_fma_f32 v[44:45], v[14:15], v[60:61], v[44:45] neg_lo:[1,0,0] neg_hi:[1,0,0]
	s_nop 0
	v_pk_fma_f32 v[44:45], v[16:17], v[62:63], v[44:45] neg_lo:[1,0,0] neg_hi:[1,0,0]
	s_nop 0
	v_pk_fma_f32 v[44:45], v[18:19], v[84:85], v[44:45] neg_lo:[1,0,0] neg_hi:[1,0,0]
	s_nop 0
	v_pk_fma_f32 v[44:45], v[20:21], v[86:87], v[44:45] neg_lo:[1,0,0] neg_hi:[1,0,0]
	s_nop 0
	v_pk_fma_f32 v[44:45], v[22:23], v[92:93], v[44:45] neg_lo:[1,0,0] neg_hi:[1,0,0]
	s_nop 0
	v_pk_fma_f32 v[44:45], v[24:25], v[94:95], v[44:45] neg_lo:[1,0,0] neg_hi:[1,0,0]
	s_nop 0
	v_pk_fma_f32 v[44:45], v[26:27], v[114:115], v[44:45] neg_lo:[1,0,0] neg_hi:[1,0,0]
	s_nop 0
	v_pk_fma_f32 v[44:45], v[28:29], v[116:117], v[44:45] neg_lo:[1,0,0] neg_hi:[1,0,0]
	s_nop 0
	v_pk_fma_f32 v[44:45], v[30:31], v[118:119], v[44:45] neg_lo:[1,0,0] neg_hi:[1,0,0]
	s_nop 0
	v_pk_fma_f32 v[44:45], v[32:33], v[120:121], v[44:45] neg_lo:[1,0,0] neg_hi:[1,0,0]
	s_nop 0
	v_pk_fma_f32 v[44:45], v[34:35], v[128:129], v[44:45] neg_lo:[1,0,0] neg_hi:[1,0,0]
	s_nop 0
	v_pk_fma_f32 v[44:45], v[36:37], v[130:131], v[44:45] neg_lo:[1,0,0] neg_hi:[1,0,0]
	s_nop 0
	v_pk_fma_f32 v[44:45], v[38:39], v[138:139], v[44:45] neg_lo:[1,0,0] neg_hi:[1,0,0]
	s_nop 0
	v_pk_fma_f32 v[44:45], v[40:41], v[140:141], v[44:45] neg_lo:[1,0,0] neg_hi:[1,0,0]
	s_nop 0
	v_pk_fma_f32 v[44:45], v[48:49], v[42:43], v[44:45] neg_lo:[1,0,0] neg_hi:[1,0,0]
	s_nop 0
	v_pk_add_f32 v[44:45], v[44:45], v[44:45] op_sel:[0,1] op_sel_hi:[1,0]
	s_waitcnt lgkmcnt(0)
	v_mul_f32_e32 v64, v64, v65
	v_mov_b32_e32 v0, 0x1b400
	ds_read_b128 v[46:49], v0
	v_mov_b32_e32 v0, 0x1b410
	ds_read_b128 v[52:55], v0
	v_mov_b32_e32 v0, 0x1b420
	ds_read_b128 v[56:59], v0
	v_mov_b32_e32 v0, 0x1b430
	ds_read_b128 v[60:63], v0
	v_mov_b32_e32 v0, 0x1b440
	ds_read_b128 v[84:87], v0
	v_mov_b32_e32 v0, 0x1b450
	ds_read_b128 v[92:95], v0
	v_mov_b32_e32 v0, 0x1b460
	ds_read_b128 v[112:115], v0
	v_mov_b32_e32 v0, 0x1b470
	ds_read_b128 v[116:119], v0
	v_or_b32_e32 v0, 0x1c8b0, v67
	v_mov_b32_e32 v45, 0x1b4a0
	v_mov_b32_e32 v65, 0x1b480
	ds_read_b128 v[126:129], v45
	ds_read_b32 v0, v0
	ds_read_b32 v45, v66 offset:22528
	ds_read_b128 v[136:139], v65
	v_mov_b32_e32 v65, 0x1b490
	ds_read_b128 v[146:149], v65
	v_mov_b32_e32 v65, v1
	v_pk_fma_f32 v[64:65], v[2:3], v[70:71], v[64:65] neg_lo:[1,0,0] neg_hi:[1,0,0]
	s_nop 0
	v_pk_fma_f32 v[64:65], v[4:5], v[72:73], v[64:65] neg_lo:[1,0,0] neg_hi:[1,0,0]
	s_nop 0
	v_pk_fma_f32 v[64:65], v[6:7], v[74:75], v[64:65] neg_lo:[1,0,0] neg_hi:[1,0,0]
	s_nop 0
	v_pk_fma_f32 v[64:65], v[8:9], v[76:77], v[64:65] neg_lo:[1,0,0] neg_hi:[1,0,0]
	s_nop 0
	v_pk_fma_f32 v[64:65], v[10:11], v[78:79], v[64:65] neg_lo:[1,0,0] neg_hi:[1,0,0]
	s_nop 0
	v_pk_fma_f32 v[64:65], v[12:13], v[80:81], v[64:65] neg_lo:[1,0,0] neg_hi:[1,0,0]
	s_nop 0
	v_pk_fma_f32 v[64:65], v[14:15], v[88:89], v[64:65] neg_lo:[1,0,0] neg_hi:[1,0,0]
	s_nop 0
	v_pk_fma_f32 v[64:65], v[16:17], v[90:91], v[64:65] neg_lo:[1,0,0] neg_hi:[1,0,0]
	s_nop 0
	v_pk_fma_f32 v[64:65], v[18:19], v[96:97], v[64:65] neg_lo:[1,0,0] neg_hi:[1,0,0]
	s_nop 0
	v_pk_fma_f32 v[64:65], v[20:21], v[98:99], v[64:65] neg_lo:[1,0,0] neg_hi:[1,0,0]
	s_nop 0
	v_pk_fma_f32 v[64:65], v[22:23], v[100:101], v[64:65] neg_lo:[1,0,0] neg_hi:[1,0,0]
	s_nop 0
	v_pk_fma_f32 v[64:65], v[24:25], v[102:103], v[64:65] neg_lo:[1,0,0] neg_hi:[1,0,0]
	s_nop 0
	v_pk_fma_f32 v[64:65], v[26:27], v[104:105], v[64:65] neg_lo:[1,0,0] neg_hi:[1,0,0]
	s_nop 0
	v_pk_fma_f32 v[64:65], v[28:29], v[106:107], v[64:65] neg_lo:[1,0,0] neg_hi:[1,0,0]
	s_nop 0
	v_pk_fma_f32 v[64:65], v[30:31], v[108:109], v[64:65] neg_lo:[1,0,0] neg_hi:[1,0,0]
	s_nop 0
	v_pk_fma_f32 v[64:65], v[32:33], v[110:111], v[64:65] neg_lo:[1,0,0] neg_hi:[1,0,0]
	s_nop 0
	v_pk_fma_f32 v[64:65], v[34:35], v[132:133], v[64:65] neg_lo:[1,0,0] neg_hi:[1,0,0]
	s_nop 0
	v_pk_fma_f32 v[64:65], v[36:37], v[134:135], v[64:65] neg_lo:[1,0,0] neg_hi:[1,0,0]
	s_nop 0
	v_pk_fma_f32 v[64:65], v[38:39], v[142:143], v[64:65] neg_lo:[1,0,0] neg_hi:[1,0,0]
	s_nop 0
	v_pk_fma_f32 v[64:65], v[40:41], v[144:145], v[64:65] neg_lo:[1,0,0] neg_hi:[1,0,0]
	s_nop 0
	v_pk_fma_f32 v[64:65], v[42:43], v[122:123], v[64:65] neg_lo:[1,0,0] neg_hi:[1,0,0]
	s_nop 0
	s_waitcnt lgkmcnt(0)
; DI void gdn_prep_item(const Params& P, int l, int n, int hh, char* smem) {
;     ...
;     for (int i = 1; i < 64; ++i) {
;       f32x4 (&CUR)[16] = (i & 1) ? LA : LB; f32x4 (&NXT)[16] = (i & 1) ? LB : LA;
;       if (i + 1 < 64) {
; #pragma unroll
;         for (int c = 0; c < (i + 4) / 4; ++c) NXT[c] = *(const f32x4*)(Lm + (i + 1) * 64 + 4 * c);
;         rh[(i + 1) & 1] = sp[i + 1] * rp[(i + 1) * 128];
;       }
;       __builtin_amdgcn_sched_barrier(0);
;       f32x2 acc = {rh[i & 1], 0.f};
; #pragma unroll
;       for (int p = 0; p < i / 2; ++p) { const f32x2 lp = (p & 1) ? (f32x2){CUR[p >> 1].z, CUR[p >> 1].w} : (f32x2){CUR[p >> 1].x, CUR[p >> 1].y}; acc = acc - lp * xx[p]; }
;       if (i & 1) { const int j = i - 1; const float lj = ((j & 3) == 0) ? CUR[j >> 2].x : CUR[j >> 2].z; acc.x = fmaf(-lj, xx[j >> 1].x, acc.x); }
;       const float xi = acc.x + acc.y;
;       if (i & 1) xx[i >> 1].y = xi; else xx[i >> 1].x = xi;
;       __builtin_amdgcn_sched_barrier(0);
;     }
	v_mul_f32_e32 v0, v0, v45
	v_fma_f32 v45, -v124, v44, v64
	v_add_f32_e32 v45, v65, v45
	v_mov_b32_e32 v64, 0x1b500
	ds_read_b128 v[70:73], v64
	v_mov_b32_e32 v64, 0x1b510
	ds_read_b128 v[74:77], v64
	v_mov_b32_e32 v64, 0x1b520
	ds_read_b128 v[78:81], v64
	v_mov_b32_e32 v64, 0x1b530
	ds_read_b128 v[88:91], v64
	v_mov_b32_e32 v64, 0x1b540
	ds_read_b128 v[96:99], v64
	v_mov_b32_e32 v64, 0x1b550
	ds_read_b128 v[100:103], v64
	v_mov_b32_e32 v64, 0x1b560
	ds_read_b128 v[104:107], v64
	v_mov_b32_e32 v64, 0x1b570
	ds_read_b128 v[108:111], v64
	v_mov_b32_e32 v64, 0x1b580
	ds_read_b128 v[120:123], v64
	v_mov_b32_e32 v64, 0x1b590
	ds_read_b128 v[130:133], v64
	v_mov_b32_e32 v64, 0x1b5a0
	ds_read_b128 v[140:143], v64
	v_mov_b32_e32 v64, 0x1b5b0
	ds_read_b128 v[150:153], v64
	v_or_b32_e32 v64, 0x1c8b4, v67
	ds_read_b32 v64, v64
	ds_read_b32 v65, v66 offset:23040
	v_pk_fma_f32 v[46:47], v[2:3], v[46:47], v[0:1] neg_lo:[1,0,0] neg_hi:[1,0,0]
	s_nop 0
	v_pk_fma_f32 v[46:47], v[4:5], v[48:49], v[46:47] neg_lo:[1,0,0] neg_hi:[1,0,0]
	s_nop 0
	v_pk_fma_f32 v[46:47], v[6:7], v[52:53], v[46:47] neg_lo:[1,0,0] neg_hi:[1,0,0]
	s_nop 0
	v_pk_fma_f32 v[46:47], v[8:9], v[54:55], v[46:47] neg_lo:[1,0,0] neg_hi:[1,0,0]
	s_nop 0
	v_pk_fma_f32 v[46:47], v[10:11], v[56:57], v[46:47] neg_lo:[1,0,0] neg_hi:[1,0,0]
	s_nop 0
	v_pk_fma_f32 v[46:47], v[12:13], v[58:59], v[46:47] neg_lo:[1,0,0] neg_hi:[1,0,0]
	s_nop 0
	v_pk_fma_f32 v[46:47], v[14:15], v[60:61], v[46:47] neg_lo:[1,0,0] neg_hi:[1,0,0]
	s_nop 0
	v_pk_fma_f32 v[46:47], v[16:17], v[62:63], v[46:47] neg_lo:[1,0,0] neg_hi:[1,0,0]
	s_nop 0
	v_pk_fma_f32 v[46:47], v[18:19], v[84:85], v[46:47] neg_lo:[1,0,0] neg_hi:[1,0,0]
	s_nop 0
	v_pk_fma_f32 v[46:47], v[20:21], v[86:87], v[46:47] neg_lo:[1,0,0] neg_hi:[1,0,0]
	s_nop 0
	v_pk_fma_f32 v[46:47], v[22:23], v[92:93], v[46:47] neg_lo:[1,0,0] neg_hi:[1,0,0]
	s_nop 0
	v_pk_fma_f32 v[46:47], v[24:25], v[94:95], v[46:47] neg_lo:[1,0,0] neg_hi:[1,0,0]
	s_nop 0
	v_pk_fma_f32 v[46:47], v[26:27], v[112:113], v[46:47] neg_lo:[1,0,0] neg_hi:[1,0,0]
	s_nop 0
	v_pk_fma_f32 v[46:47], v[28:29], v[114:115], v[46:47] neg_lo:[1,0,0] neg_hi:[1,0,0]
	s_nop 0
	v_pk_fma_f32 v[46:47], v[30:31], v[116:117], v[46:47] neg_lo:[1,0,0] neg_hi:[1,0,0]
	s_nop 0
	v_pk_fma_f32 v[46:47], v[32:33], v[118:119], v[46:47] neg_lo:[1,0,0] neg_hi:[1,0,0]
	s_nop 0
	v_pk_fma_f32 v[46:47], v[34:35], v[136:137], v[46:47] neg_lo:[1,0,0] neg_hi:[1,0,0]
	s_nop 0
	v_pk_fma_f32 v[46:47], v[36:37], v[138:139], v[46:47] neg_lo:[1,0,0] neg_hi:[1,0,0]
	s_nop 0
	v_pk_fma_f32 v[46:47], v[38:39], v[146:147], v[46:47] neg_lo:[1,0,0] neg_hi:[1,0,0]
	s_nop 0
	v_pk_fma_f32 v[46:47], v[40:41], v[148:149], v[46:47] neg_lo:[1,0,0] neg_hi:[1,0,0]
	s_nop 0
	v_pk_fma_f32 v[46:47], v[42:43], v[126:127], v[46:47] neg_lo:[1,0,0] neg_hi:[1,0,0]
	s_nop 0
	v_pk_fma_f32 v[46:47], v[128:129], v[44:45], v[46:47] neg_lo:[1,0,0] neg_hi:[1,0,0]
	s_nop 0
	v_pk_add_f32 v[46:47], v[46:47], v[46:47] op_sel:[0,1] op_sel_hi:[1,0]
	s_waitcnt lgkmcnt(0)
	v_mul_f32_e32 v64, v64, v65
	v_mov_b32_e32 v0, 0x1b600
	ds_read_b128 v[52:55], v0
	v_mov_b32_e32 v0, 0x1b610
	ds_read_b128 v[56:59], v0
	v_mov_b32_e32 v0, 0x1b620
	ds_read_b128 v[60:63], v0
	v_mov_b32_e32 v0, 0x1b630
	ds_read_b128 v[84:87], v0
	v_mov_b32_e32 v0, 0x1b640
	ds_read_b128 v[92:95], v0
	v_mov_b32_e32 v0, 0x1b650
	ds_read_b128 v[112:115], v0
	v_mov_b32_e32 v0, 0x1b660
	ds_read_b128 v[116:119], v0
	v_mov_b32_e32 v0, 0x1b670
	ds_read_b128 v[124:127], v0
	v_mov_b32_e32 v0, 0x1b680
	ds_read_b128 v[134:137], v0
	v_mov_b32_e32 v0, 0x1b690
	ds_read_b128 v[144:147], v0
	v_or_b32_e32 v0, 0x1c8b8, v67
	v_mov_b32_e32 v48, 0x1b6a0
	ds_read_b32 v0, v0
	ds_read_b32 v47, v66 offset:23552
	ds_read_b128 v[152:155], v48
	v_mov_b32_e32 v48, 0x1b6b0
	ds_read_b64 v[48:49], v48
	v_mov_b32_e32 v65, v1
	v_pk_fma_f32 v[64:65], v[2:3], v[70:71], v[64:65] neg_lo:[1,0,0] neg_hi:[1,0,0]
	s_nop 0
	v_pk_fma_f32 v[64:65], v[4:5], v[72:73], v[64:65] neg_lo:[1,0,0] neg_hi:[1,0,0]
	s_nop 0
	v_pk_fma_f32 v[64:65], v[6:7], v[74:75], v[64:65] neg_lo:[1,0,0] neg_hi:[1,0,0]
	s_nop 0
	v_pk_fma_f32 v[64:65], v[8:9], v[76:77], v[64:65] neg_lo:[1,0,0] neg_hi:[1,0,0]
	s_nop 0
	v_pk_fma_f32 v[64:65], v[10:11], v[78:79], v[64:65] neg_lo:[1,0,0] neg_hi:[1,0,0]
	s_nop 0
	v_pk_fma_f32 v[64:65], v[12:13], v[80:81], v[64:65] neg_lo:[1,0,0] neg_hi:[1,0,0]
	s_nop 0
	v_pk_fma_f32 v[64:65], v[14:15], v[88:89], v[64:65] neg_lo:[1,0,0] neg_hi:[1,0,0]
	s_nop 0
	v_pk_fma_f32 v[64:65], v[16:17], v[90:91], v[64:65] neg_lo:[1,0,0] neg_hi:[1,0,0]
	s_nop 0
	v_pk_fma_f32 v[64:65], v[18:19], v[96:97], v[64:65] neg_lo:[1,0,0] neg_hi:[1,0,0]
	s_nop 0
	v_pk_fma_f32 v[64:65], v[20:21], v[98:99], v[64:65] neg_lo:[1,0,0] neg_hi:[1,0,0]
	s_nop 0
	v_pk_fma_f32 v[64:65], v[22:23], v[100:101], v[64:65] neg_lo:[1,0,0] neg_hi:[1,0,0]
	s_nop 0
	v_pk_fma_f32 v[64:65], v[24:25], v[102:103], v[64:65] neg_lo:[1,0,0] neg_hi:[1,0,0]
	s_nop 0
	v_pk_fma_f32 v[64:65], v[26:27], v[104:105], v[64:65] neg_lo:[1,0,0] neg_hi:[1,0,0]
	s_nop 0
	v_pk_fma_f32 v[64:65], v[28:29], v[106:107], v[64:65] neg_lo:[1,0,0] neg_hi:[1,0,0]
	s_nop 0
	v_pk_fma_f32 v[64:65], v[30:31], v[108:109], v[64:65] neg_lo:[1,0,0] neg_hi:[1,0,0]
	s_nop 0
	v_pk_fma_f32 v[64:65], v[32:33], v[110:111], v[64:65] neg_lo:[1,0,0] neg_hi:[1,0,0]
	s_nop 0
	v_pk_fma_f32 v[64:65], v[34:35], v[120:121], v[64:65] neg_lo:[1,0,0] neg_hi:[1,0,0]
	s_nop 0
	v_pk_fma_f32 v[64:65], v[36:37], v[122:123], v[64:65] neg_lo:[1,0,0] neg_hi:[1,0,0]
	s_nop 0
	v_pk_fma_f32 v[64:65], v[38:39], v[130:131], v[64:65] neg_lo:[1,0,0] neg_hi:[1,0,0]
	s_nop 0
	v_pk_fma_f32 v[64:65], v[40:41], v[132:133], v[64:65] neg_lo:[1,0,0] neg_hi:[1,0,0]
	s_nop 0
	v_pk_fma_f32 v[64:65], v[42:43], v[140:141], v[64:65] neg_lo:[1,0,0] neg_hi:[1,0,0]
	s_nop 0
	v_pk_fma_f32 v[64:65], v[44:45], v[142:143], v[64:65] neg_lo:[1,0,0] neg_hi:[1,0,0]
	s_nop 0
	s_waitcnt lgkmcnt(0)
; DI void gdn_prep_item(const Params& P, int l, int n, int hh, char* smem) {
;     ...
;     for (int i = 1; i < 64; ++i) {
;       f32x4 (&CUR)[16] = (i & 1) ? LA : LB; f32x4 (&NXT)[16] = (i & 1) ? LB : LA;
;       if (i + 1 < 64) {
; #pragma unroll
;         for (int c = 0; c < (i + 4) / 4; ++c) NXT[c] = *(const f32x4*)(Lm + (i + 1) * 64 + 4 * c);
;         rh[(i + 1) & 1] = sp[i + 1] * rp[(i + 1) * 128];
;       }
;       __builtin_amdgcn_sched_barrier(0);
;       f32x2 acc = {rh[i & 1], 0.f};
; #pragma unroll
;       for (int p = 0; p < i / 2; ++p) { const f32x2 lp = (p & 1) ? (f32x2){CUR[p >> 1].z, CUR[p >> 1].w} : (f32x2){CUR[p >> 1].x, CUR[p >> 1].y}; acc = acc - lp * xx[p]; }
;       if (i & 1) { const int j = i - 1; const float lj = ((j & 3) == 0) ? CUR[j >> 2].x : CUR[j >> 2].z; acc.x = fmaf(-lj, xx[j >> 1].x, acc.x); }
;       const float xi = acc.x + acc.y;
;       if (i & 1) xx[i >> 1].y = xi; else xx[i >> 1].x = xi;
;       __builtin_amdgcn_sched_barrier(0);
;     }
	v_mul_f32_e32 v0, v0, v47
	v_fma_f32 v47, -v150, v46, v64
	v_add_f32_e32 v47, v65, v47
	v_mov_b32_e32 v64, 0x1b700
	ds_read_b128 v[70:73], v64
	v_mov_b32_e32 v64, 0x1b710
	ds_read_b128 v[74:77], v64
	v_mov_b32_e32 v64, 0x1b720
	ds_read_b128 v[78:81], v64
	v_mov_b32_e32 v64, 0x1b730
	ds_read_b128 v[88:91], v64
	v_mov_b32_e32 v64, 0x1b740
	ds_read_b128 v[96:99], v64
	v_mov_b32_e32 v64, 0x1b750
	ds_read_b128 v[100:103], v64
	v_mov_b32_e32 v64, 0x1b760
	ds_read_b128 v[104:107], v64
	v_mov_b32_e32 v64, 0x1b770
	ds_read_b128 v[108:111], v64
	v_mov_b32_e32 v64, 0x1b780
	ds_read_b128 v[120:123], v64
	v_mov_b32_e32 v64, 0x1b790
	ds_read_b128 v[128:131], v64
	v_or_b32_e32 v64, 0x1c8bc, v67
	ds_read_b32 v64, v64
	ds_read_b32 v65, v66 offset:24064
	v_mov_b32_e32 v83, 0x1b7a0
	ds_read_b128 v[138:141], v83
	v_mov_b32_e32 v83, 0x1b7b0
	ds_read_b128 v[148:151], v83
	v_pk_fma_f32 v[52:53], v[2:3], v[52:53], v[0:1] neg_lo:[1,0,0] neg_hi:[1,0,0]
	s_nop 0
	v_pk_fma_f32 v[52:53], v[4:5], v[54:55], v[52:53] neg_lo:[1,0,0] neg_hi:[1,0,0]
	s_nop 0
	v_pk_fma_f32 v[52:53], v[6:7], v[56:57], v[52:53] neg_lo:[1,0,0] neg_hi:[1,0,0]
	s_nop 0
	v_pk_fma_f32 v[52:53], v[8:9], v[58:59], v[52:53] neg_lo:[1,0,0] neg_hi:[1,0,0]
	s_nop 0
	v_pk_fma_f32 v[52:53], v[10:11], v[60:61], v[52:53] neg_lo:[1,0,0] neg_hi:[1,0,0]
	s_nop 0
	v_pk_fma_f32 v[52:53], v[12:13], v[62:63], v[52:53] neg_lo:[1,0,0] neg_hi:[1,0,0]
	s_nop 0
	v_pk_fma_f32 v[52:53], v[14:15], v[84:85], v[52:53] neg_lo:[1,0,0] neg_hi:[1,0,0]
	s_nop 0
	v_pk_fma_f32 v[52:53], v[16:17], v[86:87], v[52:53] neg_lo:[1,0,0] neg_hi:[1,0,0]
	s_nop 0
	v_pk_fma_f32 v[52:53], v[18:19], v[92:93], v[52:53] neg_lo:[1,0,0] neg_hi:[1,0,0]
	s_nop 0
	v_pk_fma_f32 v[52:53], v[20:21], v[94:95], v[52:53] neg_lo:[1,0,0] neg_hi:[1,0,0]
	s_nop 0
	v_pk_fma_f32 v[52:53], v[22:23], v[112:113], v[52:53] neg_lo:[1,0,0] neg_hi:[1,0,0]
	s_nop 0
	v_pk_fma_f32 v[52:53], v[24:25], v[114:115], v[52:53] neg_lo:[1,0,0] neg_hi:[1,0,0]
	s_nop 0
	v_pk_fma_f32 v[52:53], v[26:27], v[116:117], v[52:53] neg_lo:[1,0,0] neg_hi:[1,0,0]
	s_nop 0
	v_pk_fma_f32 v[52:53], v[28:29], v[118:119], v[52:53] neg_lo:[1,0,0] neg_hi:[1,0,0]
	s_nop 0
	v_pk_fma_f32 v[52:53], v[30:31], v[124:125], v[52:53] neg_lo:[1,0,0] neg_hi:[1,0,0]
	s_nop 0
	v_pk_fma_f32 v[52:53], v[32:33], v[126:127], v[52:53] neg_lo:[1,0,0] neg_hi:[1,0,0]
	s_nop 0
	v_pk_fma_f32 v[52:53], v[34:35], v[134:135], v[52:53] neg_lo:[1,0,0] neg_hi:[1,0,0]
	s_nop 0
	v_pk_fma_f32 v[52:53], v[36:37], v[136:137], v[52:53] neg_lo:[1,0,0] neg_hi:[1,0,0]
	s_nop 0
	v_pk_fma_f32 v[52:53], v[38:39], v[144:145], v[52:53] neg_lo:[1,0,0] neg_hi:[1,0,0]
	s_nop 0
	v_pk_fma_f32 v[52:53], v[40:41], v[146:147], v[52:53] neg_lo:[1,0,0] neg_hi:[1,0,0]
	s_nop 0
	v_pk_fma_f32 v[52:53], v[42:43], v[152:153], v[52:53] neg_lo:[1,0,0] neg_hi:[1,0,0]
	s_nop 0
	v_pk_fma_f32 v[52:53], v[44:45], v[154:155], v[52:53] neg_lo:[1,0,0] neg_hi:[1,0,0]
	s_nop 0
	v_pk_fma_f32 v[48:49], v[48:49], v[46:47], v[52:53] neg_lo:[1,0,0] neg_hi:[1,0,0]
	s_nop 0
	v_pk_add_f32 v[48:49], v[48:49], v[48:49] op_sel:[0,1] op_sel_hi:[1,0]
	s_waitcnt lgkmcnt(0)
	v_mul_f32_e32 v64, v64, v65
	v_mov_b32_e32 v0, 0x1b800
	ds_read_b128 v[52:55], v0
	v_mov_b32_e32 v0, 0x1b810
	ds_read_b128 v[56:59], v0
	v_mov_b32_e32 v0, 0x1b820
	ds_read_b128 v[60:63], v0
	v_mov_b32_e32 v0, 0x1b830
	ds_read_b128 v[84:87], v0
	v_mov_b32_e32 v0, 0x1b840
	ds_read_b128 v[92:95], v0
	v_mov_b32_e32 v0, 0x1b850
	ds_read_b128 v[112:115], v0
	v_mov_b32_e32 v0, 0x1b860
	ds_read_b128 v[116:119], v0
	v_mov_b32_e32 v0, 0x1b870
	ds_read_b128 v[124:127], v0
	v_mov_b32_e32 v0, 0x1b880
	ds_read_b128 v[132:135], v0
	v_mov_b32_e32 v0, 0x1b890
	ds_read_b128 v[142:145], v0
	v_or_b32_e32 v0, 0x1c8c0, v67
	v_mov_b32_e32 v65, 0x1b8a0
	ds_read_b32 v0, v0
	ds_read_b32 v49, v66 offset:24576
	ds_read_b128 v[152:155], v65
	v_mov_b32_e32 v65, 0x1b8b0
	ds_read_b128 v[156:159], v65
	v_mov_b32_e32 v65, v1
	v_pk_fma_f32 v[64:65], v[2:3], v[70:71], v[64:65] neg_lo:[1,0,0] neg_hi:[1,0,0]
	s_nop 0
	v_pk_fma_f32 v[64:65], v[4:5], v[72:73], v[64:65] neg_lo:[1,0,0] neg_hi:[1,0,0]
	s_nop 0
	v_pk_fma_f32 v[64:65], v[6:7], v[74:75], v[64:65] neg_lo:[1,0,0] neg_hi:[1,0,0]
	s_nop 0
	v_pk_fma_f32 v[64:65], v[8:9], v[76:77], v[64:65] neg_lo:[1,0,0] neg_hi:[1,0,0]
	s_nop 0
	v_pk_fma_f32 v[64:65], v[10:11], v[78:79], v[64:65] neg_lo:[1,0,0] neg_hi:[1,0,0]
	s_nop 0
	v_pk_fma_f32 v[64:65], v[12:13], v[80:81], v[64:65] neg_lo:[1,0,0] neg_hi:[1,0,0]
	s_nop 0
	v_pk_fma_f32 v[64:65], v[14:15], v[88:89], v[64:65] neg_lo:[1,0,0] neg_hi:[1,0,0]
	s_nop 0
	v_pk_fma_f32 v[64:65], v[16:17], v[90:91], v[64:65] neg_lo:[1,0,0] neg_hi:[1,0,0]
	s_nop 0
	v_pk_fma_f32 v[64:65], v[18:19], v[96:97], v[64:65] neg_lo:[1,0,0] neg_hi:[1,0,0]
	s_nop 0
	v_pk_fma_f32 v[64:65], v[20:21], v[98:99], v[64:65] neg_lo:[1,0,0] neg_hi:[1,0,0]
	s_nop 0
	v_pk_fma_f32 v[64:65], v[22:23], v[100:101], v[64:65] neg_lo:[1,0,0] neg_hi:[1,0,0]
	s_nop 0
	v_pk_fma_f32 v[64:65], v[24:25], v[102:103], v[64:65] neg_lo:[1,0,0] neg_hi:[1,0,0]
	s_nop 0
	v_pk_fma_f32 v[64:65], v[26:27], v[104:105], v[64:65] neg_lo:[1,0,0] neg_hi:[1,0,0]
	s_nop 0
	v_pk_fma_f32 v[64:65], v[28:29], v[106:107], v[64:65] neg_lo:[1,0,0] neg_hi:[1,0,0]
	s_nop 0
	v_pk_fma_f32 v[64:65], v[30:31], v[108:109], v[64:65] neg_lo:[1,0,0] neg_hi:[1,0,0]
	s_nop 0
	v_pk_fma_f32 v[64:65], v[32:33], v[110:111], v[64:65] neg_lo:[1,0,0] neg_hi:[1,0,0]
	s_nop 0
	v_pk_fma_f32 v[64:65], v[34:35], v[120:121], v[64:65] neg_lo:[1,0,0] neg_hi:[1,0,0]
	s_nop 0
	v_pk_fma_f32 v[64:65], v[36:37], v[122:123], v[64:65] neg_lo:[1,0,0] neg_hi:[1,0,0]
	s_nop 0
	v_pk_fma_f32 v[64:65], v[38:39], v[128:129], v[64:65] neg_lo:[1,0,0] neg_hi:[1,0,0]
	s_nop 0
	v_pk_fma_f32 v[64:65], v[40:41], v[130:131], v[64:65] neg_lo:[1,0,0] neg_hi:[1,0,0]
	s_nop 0
	v_pk_fma_f32 v[64:65], v[42:43], v[138:139], v[64:65] neg_lo:[1,0,0] neg_hi:[1,0,0]
	s_nop 0
	v_pk_fma_f32 v[64:65], v[44:45], v[140:141], v[64:65] neg_lo:[1,0,0] neg_hi:[1,0,0]
	s_nop 0
	v_pk_fma_f32 v[64:65], v[46:47], v[148:149], v[64:65] neg_lo:[1,0,0] neg_hi:[1,0,0]
	s_nop 0
	s_waitcnt lgkmcnt(0)
; DI void gdn_prep_item(const Params& P, int l, int n, int hh, char* smem) {
;     ...
;     for (int i = 1; i < 64; ++i) {
;       f32x4 (&CUR)[16] = (i & 1) ? LA : LB; f32x4 (&NXT)[16] = (i & 1) ? LB : LA;
;       if (i + 1 < 64) {
; #pragma unroll
;         for (int c = 0; c < (i + 4) / 4; ++c) NXT[c] = *(const f32x4*)(Lm + (i + 1) * 64 + 4 * c);
;         rh[(i + 1) & 1] = sp[i + 1] * rp[(i + 1) * 128];
;       }
;       __builtin_amdgcn_sched_barrier(0);
;       f32x2 acc = {rh[i & 1], 0.f};
; #pragma unroll
;       for (int p = 0; p < i / 2; ++p) { const f32x2 lp = (p & 1) ? (f32x2){CUR[p >> 1].z, CUR[p >> 1].w} : (f32x2){CUR[p >> 1].x, CUR[p >> 1].y}; acc = acc - lp * xx[p]; }
;       if (i & 1) { const int j = i - 1; const float lj = ((j & 3) == 0) ? CUR[j >> 2].x : CUR[j >> 2].z; acc.x = fmaf(-lj, xx[j >> 1].x, acc.x); }
;       const float xi = acc.x + acc.y;
;       if (i & 1) xx[i >> 1].y = xi; else xx[i >> 1].x = xi;
;       __builtin_amdgcn_sched_barrier(0);
;     }
	v_mul_f32_e32 v0, v0, v49
	v_fma_f32 v49, -v150, v48, v64
	v_add_f32_e32 v49, v65, v49
	v_mov_b32_e32 v64, 0x1b900
	ds_read_b128 v[70:73], v64
	v_mov_b32_e32 v64, 0x1b910
	ds_read_b128 v[74:77], v64
	v_mov_b32_e32 v64, 0x1b920
	ds_read_b128 v[78:81], v64
	v_mov_b32_e32 v64, 0x1b930
	ds_read_b128 v[88:91], v64
	v_mov_b32_e32 v64, 0x1b940
	ds_read_b128 v[96:99], v64
	v_mov_b32_e32 v64, 0x1b950
	ds_read_b128 v[100:103], v64
	v_mov_b32_e32 v64, 0x1b960
	ds_read_b128 v[104:107], v64
	v_mov_b32_e32 v64, 0x1b970
	ds_read_b128 v[108:111], v64
	v_mov_b32_e32 v64, 0x1b980
	ds_read_b128 v[120:123], v64
	v_mov_b32_e32 v64, 0x1b990
	ds_read_b128 v[128:131], v64
	v_or_b32_e32 v64, 0x1c8c4, v67
	v_mov_b32_e32 v65, 0x1b9c0
	ds_read_b128 v[136:139], v65
	ds_read_b32 v64, v64
	ds_read_b32 v65, v66 offset:25088
	v_mov_b32_e32 v83, 0x1b9a0
	s_waitcnt lgkmcnt(0)
	ds_read_b128 v[138:141], v83
	v_mov_b32_e32 v83, 0x1b9b0
	ds_read_b128 v[146:149], v83
	v_mul_f32_e32 v160, v64, v65
	v_pk_fma_f32 v[52:53], v[2:3], v[52:53], v[0:1] neg_lo:[1,0,0] neg_hi:[1,0,0]
	s_nop 0
	v_pk_fma_f32 v[52:53], v[4:5], v[54:55], v[52:53] neg_lo:[1,0,0] neg_hi:[1,0,0]
	s_nop 0
	v_pk_fma_f32 v[52:53], v[6:7], v[56:57], v[52:53] neg_lo:[1,0,0] neg_hi:[1,0,0]
	s_nop 0
	v_pk_fma_f32 v[52:53], v[8:9], v[58:59], v[52:53] neg_lo:[1,0,0] neg_hi:[1,0,0]
	s_nop 0
	v_pk_fma_f32 v[52:53], v[10:11], v[60:61], v[52:53] neg_lo:[1,0,0] neg_hi:[1,0,0]
	s_nop 0
	v_pk_fma_f32 v[52:53], v[12:13], v[62:63], v[52:53] neg_lo:[1,0,0] neg_hi:[1,0,0]
	s_nop 0
	v_pk_fma_f32 v[52:53], v[14:15], v[84:85], v[52:53] neg_lo:[1,0,0] neg_hi:[1,0,0]
	s_nop 0
	v_pk_fma_f32 v[52:53], v[16:17], v[86:87], v[52:53] neg_lo:[1,0,0] neg_hi:[1,0,0]
	s_nop 0
	v_pk_fma_f32 v[52:53], v[18:19], v[92:93], v[52:53] neg_lo:[1,0,0] neg_hi:[1,0,0]
	s_nop 0
	v_pk_fma_f32 v[52:53], v[20:21], v[94:95], v[52:53] neg_lo:[1,0,0] neg_hi:[1,0,0]
	s_nop 0
	v_pk_fma_f32 v[52:53], v[22:23], v[112:113], v[52:53] neg_lo:[1,0,0] neg_hi:[1,0,0]
	s_nop 0
	v_pk_fma_f32 v[52:53], v[24:25], v[114:115], v[52:53] neg_lo:[1,0,0] neg_hi:[1,0,0]
	s_nop 0
	v_pk_fma_f32 v[52:53], v[26:27], v[116:117], v[52:53] neg_lo:[1,0,0] neg_hi:[1,0,0]
	s_nop 0
	v_pk_fma_f32 v[52:53], v[28:29], v[118:119], v[52:53] neg_lo:[1,0,0] neg_hi:[1,0,0]
	s_nop 0
	v_pk_fma_f32 v[52:53], v[30:31], v[124:125], v[52:53] neg_lo:[1,0,0] neg_hi:[1,0,0]
	s_nop 0
	v_pk_fma_f32 v[52:53], v[32:33], v[126:127], v[52:53] neg_lo:[1,0,0] neg_hi:[1,0,0]
	s_nop 0
	v_pk_fma_f32 v[52:53], v[34:35], v[132:133], v[52:53] neg_lo:[1,0,0] neg_hi:[1,0,0]
	s_nop 0
	v_pk_fma_f32 v[52:53], v[36:37], v[134:135], v[52:53] neg_lo:[1,0,0] neg_hi:[1,0,0]
	s_nop 0
	v_pk_fma_f32 v[52:53], v[38:39], v[142:143], v[52:53] neg_lo:[1,0,0] neg_hi:[1,0,0]
	s_nop 0
	v_pk_fma_f32 v[52:53], v[40:41], v[144:145], v[52:53] neg_lo:[1,0,0] neg_hi:[1,0,0]
	s_nop 0
	v_pk_fma_f32 v[52:53], v[42:43], v[152:153], v[52:53] neg_lo:[1,0,0] neg_hi:[1,0,0]
	s_nop 0
	v_pk_fma_f32 v[52:53], v[44:45], v[154:155], v[52:53] neg_lo:[1,0,0] neg_hi:[1,0,0]
	s_nop 0
	v_pk_fma_f32 v[52:53], v[46:47], v[156:157], v[52:53] neg_lo:[1,0,0] neg_hi:[1,0,0]
	s_nop 0
	v_pk_fma_f32 v[52:53], v[158:159], v[48:49], v[52:53] neg_lo:[1,0,0] neg_hi:[1,0,0]
	s_nop 0
	v_pk_add_f32 v[52:53], v[52:53], v[52:53] op_sel:[0,1] op_sel_hi:[1,0]
	v_mov_b32_e32 v0, 0x1ba00
	ds_read_b128 v[54:57], v0
	v_mov_b32_e32 v0, 0x1ba10
	ds_read_b128 v[58:61], v0
	v_mov_b32_e32 v0, 0x1ba20
	ds_read_b128 v[62:65], v0
	v_mov_b32_e32 v0, 0x1ba30
	ds_read_b128 v[84:87], v0
	v_mov_b32_e32 v0, 0x1ba40
	ds_read_b128 v[92:95], v0
	v_mov_b32_e32 v0, 0x1ba50
	ds_read_b128 v[112:115], v0
	v_mov_b32_e32 v0, 0x1ba60
	ds_read_b128 v[116:119], v0
	v_mov_b32_e32 v0, 0x1ba70
	ds_read_b128 v[124:127], v0
	v_mov_b32_e32 v0, 0x1ba80
	ds_read_b128 v[132:135], v0
	v_mov_b32_e32 v0, 0x1ba90
	ds_read_b128 v[142:145], v0
	v_or_b32_e32 v0, 0x1c8c8, v67
	v_mov_b32_e32 v53, 0x1bac0
	v_mov_b32_e32 v83, 0x1baa0
	ds_read_b64 v[162:163], v53
	ds_read_b32 v0, v0
	ds_read_b32 v53, v66 offset:25600
	ds_read_b128 v[150:153], v83
	v_mov_b32_e32 v83, 0x1bab0
	ds_read_b128 v[154:157], v83
	v_mov_b32_e32 v161, v1
	v_pk_fma_f32 v[70:71], v[2:3], v[70:71], v[160:161] neg_lo:[1,0,0] neg_hi:[1,0,0]
	s_nop 0
	v_pk_fma_f32 v[70:71], v[4:5], v[72:73], v[70:71] neg_lo:[1,0,0] neg_hi:[1,0,0]
	s_nop 0
	v_pk_fma_f32 v[70:71], v[6:7], v[74:75], v[70:71] neg_lo:[1,0,0] neg_hi:[1,0,0]
	s_nop 0
	v_pk_fma_f32 v[70:71], v[8:9], v[76:77], v[70:71] neg_lo:[1,0,0] neg_hi:[1,0,0]
	s_nop 0
	v_pk_fma_f32 v[70:71], v[10:11], v[78:79], v[70:71] neg_lo:[1,0,0] neg_hi:[1,0,0]
	s_nop 0
	v_pk_fma_f32 v[70:71], v[12:13], v[80:81], v[70:71] neg_lo:[1,0,0] neg_hi:[1,0,0]
	s_nop 0
	v_pk_fma_f32 v[70:71], v[14:15], v[88:89], v[70:71] neg_lo:[1,0,0] neg_hi:[1,0,0]
	s_nop 0
	v_pk_fma_f32 v[70:71], v[16:17], v[90:91], v[70:71] neg_lo:[1,0,0] neg_hi:[1,0,0]
	s_nop 0
	v_pk_fma_f32 v[70:71], v[18:19], v[96:97], v[70:71] neg_lo:[1,0,0] neg_hi:[1,0,0]
	s_nop 0
	v_pk_fma_f32 v[70:71], v[20:21], v[98:99], v[70:71] neg_lo:[1,0,0] neg_hi:[1,0,0]
	s_nop 0
	v_pk_fma_f32 v[70:71], v[22:23], v[100:101], v[70:71] neg_lo:[1,0,0] neg_hi:[1,0,0]
	s_nop 0
	v_pk_fma_f32 v[70:71], v[24:25], v[102:103], v[70:71] neg_lo:[1,0,0] neg_hi:[1,0,0]
	s_nop 0
	v_pk_fma_f32 v[70:71], v[26:27], v[104:105], v[70:71] neg_lo:[1,0,0] neg_hi:[1,0,0]
	s_nop 0
	v_pk_fma_f32 v[70:71], v[28:29], v[106:107], v[70:71] neg_lo:[1,0,0] neg_hi:[1,0,0]
	s_nop 0
	v_pk_fma_f32 v[70:71], v[30:31], v[108:109], v[70:71] neg_lo:[1,0,0] neg_hi:[1,0,0]
	s_nop 0
	v_pk_fma_f32 v[70:71], v[32:33], v[110:111], v[70:71] neg_lo:[1,0,0] neg_hi:[1,0,0]
	s_nop 0
	v_pk_fma_f32 v[70:71], v[34:35], v[120:121], v[70:71] neg_lo:[1,0,0] neg_hi:[1,0,0]
	s_nop 0
	v_pk_fma_f32 v[70:71], v[36:37], v[122:123], v[70:71] neg_lo:[1,0,0] neg_hi:[1,0,0]
	s_nop 0
	v_pk_fma_f32 v[70:71], v[38:39], v[128:129], v[70:71] neg_lo:[1,0,0] neg_hi:[1,0,0]
	s_nop 0
	v_pk_fma_f32 v[70:71], v[40:41], v[130:131], v[70:71] neg_lo:[1,0,0] neg_hi:[1,0,0]
	s_nop 0
	s_waitcnt lgkmcnt(0)
; DI void gdn_prep_item(const Params& P, int l, int n, int hh, char* smem) {
;     ...
;     for (int i = 1; i < 64; ++i) {
;       f32x4 (&CUR)[16] = (i & 1) ? LA : LB; f32x4 (&NXT)[16] = (i & 1) ? LB : LA;
;       if (i + 1 < 64) {
; #pragma unroll
;         for (int c = 0; c < (i + 4) / 4; ++c) NXT[c] = *(const f32x4*)(Lm + (i + 1) * 64 + 4 * c);
;         rh[(i + 1) & 1] = sp[i + 1] * rp[(i + 1) * 128];
;       }
;       __builtin_amdgcn_sched_barrier(0);
;       f32x2 acc = {rh[i & 1], 0.f};
; #pragma unroll
;       for (int p = 0; p < i / 2; ++p) { const f32x2 lp = (p & 1) ? (f32x2){CUR[p >> 1].z, CUR[p >> 1].w} : (f32x2){CUR[p >> 1].x, CUR[p >> 1].y}; acc = acc - lp * xx[p]; }
;       if (i & 1) { const int j = i - 1; const float lj = ((j & 3) == 0) ? CUR[j >> 2].x : CUR[j >> 2].z; acc.x = fmaf(-lj, xx[j >> 1].x, acc.x); }
;       const float xi = acc.x + acc.y;
;       if (i & 1) xx[i >> 1].y = xi; else xx[i >> 1].x = xi;
;       __builtin_amdgcn_sched_barrier(0);
;     }
	v_mul_f32_e32 v0, v0, v53
	v_pk_fma_f32 v[70:71], v[42:43], v[138:139], v[70:71] neg_lo:[1,0,0] neg_hi:[1,0,0]
	s_nop 0
	v_pk_fma_f32 v[70:71], v[44:45], v[140:141], v[70:71] neg_lo:[1,0,0] neg_hi:[1,0,0]
	s_nop 0
	v_pk_fma_f32 v[70:71], v[46:47], v[146:147], v[70:71] neg_lo:[1,0,0] neg_hi:[1,0,0]
	s_nop 0
	v_pk_fma_f32 v[70:71], v[48:49], v[148:149], v[70:71] neg_lo:[1,0,0] neg_hi:[1,0,0]
	s_nop 0
	v_fma_f32 v53, -v136, v52, v70
	v_add_f32_e32 v53, v71, v53
	v_mov_b32_e32 v78, 0x1bb20
	v_mov_b32_e32 v83, 0x1bb30
	ds_read_b128 v[78:81], v78
	ds_read_b128 v[88:91], v83
	v_mov_b32_e32 v83, 0x1bb40
	ds_read_b128 v[96:99], v83
	v_mov_b32_e32 v83, 0x1bb50
	ds_read_b128 v[100:103], v83
	v_mov_b32_e32 v83, 0x1bb60
	ds_read_b128 v[104:107], v83
	v_mov_b32_e32 v83, 0x1bb70
	ds_read_b128 v[108:111], v83
	v_mov_b32_e32 v83, 0x1bb80
	ds_read_b128 v[120:123], v83
	v_mov_b32_e32 v83, 0x1bb90
	v_mov_b32_e32 v70, 0x1bb00
	v_mov_b32_e32 v74, 0x1bb10
	ds_read_b128 v[128:131], v83
	v_or_b32_e32 v83, 0x1c8cc, v67
	v_mov_b32_e32 v136, 0x1bbc0
	ds_read_b128 v[70:73], v70
	ds_read_b128 v[74:77], v74
	ds_read_b128 v[136:139], v136
	ds_read_b32 v83, v83
	v_mov_b32_e32 v140, 0x1bba0
	s_waitcnt lgkmcnt(0)
	ds_read_b32 v139, v66 offset:26112
	ds_read_b128 v[146:149], v140
	v_mov_b32_e32 v140, 0x1bbb0
	ds_read_b128 v[158:161], v140
	v_pk_fma_f32 v[54:55], v[2:3], v[54:55], v[0:1] neg_lo:[1,0,0] neg_hi:[1,0,0]
	s_nop 0
	v_pk_fma_f32 v[54:55], v[4:5], v[56:57], v[54:55] neg_lo:[1,0,0] neg_hi:[1,0,0]
	s_nop 0
	v_pk_fma_f32 v[54:55], v[6:7], v[58:59], v[54:55] neg_lo:[1,0,0] neg_hi:[1,0,0]
	s_nop 0
	v_pk_fma_f32 v[54:55], v[8:9], v[60:61], v[54:55] neg_lo:[1,0,0] neg_hi:[1,0,0]
	s_nop 0
	v_pk_fma_f32 v[54:55], v[10:11], v[62:63], v[54:55] neg_lo:[1,0,0] neg_hi:[1,0,0]
	s_nop 0
	v_pk_fma_f32 v[54:55], v[12:13], v[64:65], v[54:55] neg_lo:[1,0,0] neg_hi:[1,0,0]
	s_nop 0
	v_pk_fma_f32 v[54:55], v[14:15], v[84:85], v[54:55] neg_lo:[1,0,0] neg_hi:[1,0,0]
	s_nop 0
	v_pk_fma_f32 v[54:55], v[16:17], v[86:87], v[54:55] neg_lo:[1,0,0] neg_hi:[1,0,0]
	s_nop 0
	v_pk_fma_f32 v[54:55], v[18:19], v[92:93], v[54:55] neg_lo:[1,0,0] neg_hi:[1,0,0]
	s_nop 0
	v_pk_fma_f32 v[54:55], v[20:21], v[94:95], v[54:55] neg_lo:[1,0,0] neg_hi:[1,0,0]
	s_nop 0
	v_pk_fma_f32 v[54:55], v[22:23], v[112:113], v[54:55] neg_lo:[1,0,0] neg_hi:[1,0,0]
	s_nop 0
	v_pk_fma_f32 v[54:55], v[24:25], v[114:115], v[54:55] neg_lo:[1,0,0] neg_hi:[1,0,0]
	s_nop 0
	v_pk_fma_f32 v[54:55], v[26:27], v[116:117], v[54:55] neg_lo:[1,0,0] neg_hi:[1,0,0]
	s_nop 0
	v_pk_fma_f32 v[54:55], v[28:29], v[118:119], v[54:55] neg_lo:[1,0,0] neg_hi:[1,0,0]
	s_nop 0
	v_pk_fma_f32 v[54:55], v[30:31], v[124:125], v[54:55] neg_lo:[1,0,0] neg_hi:[1,0,0]
	s_nop 0
	v_pk_fma_f32 v[54:55], v[32:33], v[126:127], v[54:55] neg_lo:[1,0,0] neg_hi:[1,0,0]
	s_nop 0
	v_pk_fma_f32 v[54:55], v[34:35], v[132:133], v[54:55] neg_lo:[1,0,0] neg_hi:[1,0,0]
	s_nop 0
	v_pk_fma_f32 v[54:55], v[36:37], v[134:135], v[54:55] neg_lo:[1,0,0] neg_hi:[1,0,0]
	s_nop 0
	v_pk_fma_f32 v[54:55], v[38:39], v[142:143], v[54:55] neg_lo:[1,0,0] neg_hi:[1,0,0]
	s_nop 0
	v_pk_fma_f32 v[54:55], v[40:41], v[144:145], v[54:55] neg_lo:[1,0,0] neg_hi:[1,0,0]
	s_nop 0
	v_pk_fma_f32 v[54:55], v[42:43], v[150:151], v[54:55] neg_lo:[1,0,0] neg_hi:[1,0,0]
	s_nop 0
	v_pk_fma_f32 v[54:55], v[44:45], v[152:153], v[54:55] neg_lo:[1,0,0] neg_hi:[1,0,0]
	s_nop 0
	v_pk_fma_f32 v[54:55], v[46:47], v[154:155], v[54:55] neg_lo:[1,0,0] neg_hi:[1,0,0]
	s_nop 0
	v_pk_fma_f32 v[54:55], v[48:49], v[156:157], v[54:55] neg_lo:[1,0,0] neg_hi:[1,0,0]
	s_nop 0
	v_pk_fma_f32 v[54:55], v[162:163], v[52:53], v[54:55] neg_lo:[1,0,0] neg_hi:[1,0,0]
	s_nop 0
	v_pk_add_f32 v[54:55], v[54:55], v[54:55] op_sel:[0,1] op_sel_hi:[1,0]
	s_waitcnt lgkmcnt(0)
	v_mul_f32_e32 v170, v83, v139
	v_mov_b32_e32 v0, 0x1bc00
	ds_read_b128 v[56:59], v0
	v_mov_b32_e32 v0, 0x1bc10
	ds_read_b128 v[60:63], v0
	v_mov_b32_e32 v0, 0x1bc20
	ds_read_b128 v[84:87], v0
	v_mov_b32_e32 v0, 0x1bc30
	ds_read_b128 v[92:95], v0
	v_mov_b32_e32 v0, 0x1bc40
	ds_read_b128 v[112:115], v0
	v_mov_b32_e32 v0, 0x1bc50
	ds_read_b128 v[116:119], v0
	v_mov_b32_e32 v0, 0x1bc60
	ds_read_b128 v[124:127], v0
	v_mov_b32_e32 v0, 0x1bc70
	ds_read_b128 v[132:135], v0
	v_mov_b32_e32 v0, 0x1bc80
	ds_read_b128 v[140:143], v0
	v_mov_b32_e32 v0, 0x1bc90
	ds_read_b128 v[150:153], v0
	v_or_b32_e32 v0, 0x1c8d0, v67
	v_mov_b32_e32 v55, 0x1bcc0
	v_mov_b32_e32 v64, 0x1bca0
	ds_read_b128 v[154:157], v55
	ds_read_b32 v0, v0
	ds_read_b32 v55, v66 offset:26624
	ds_read_b128 v[162:165], v64
	v_mov_b32_e32 v64, 0x1bcb0
	ds_read_b128 v[166:169], v64
	v_mov_b32_e32 v171, v1
	v_pk_fma_f32 v[64:65], v[2:3], v[70:71], v[170:171] neg_lo:[1,0,0] neg_hi:[1,0,0]
	s_nop 0
	v_pk_fma_f32 v[64:65], v[4:5], v[72:73], v[64:65] neg_lo:[1,0,0] neg_hi:[1,0,0]
	s_nop 0
	v_pk_fma_f32 v[64:65], v[6:7], v[74:75], v[64:65] neg_lo:[1,0,0] neg_hi:[1,0,0]
	s_nop 0
	v_pk_fma_f32 v[64:65], v[8:9], v[76:77], v[64:65] neg_lo:[1,0,0] neg_hi:[1,0,0]
	s_nop 0
	v_pk_fma_f32 v[64:65], v[10:11], v[78:79], v[64:65] neg_lo:[1,0,0] neg_hi:[1,0,0]
	s_nop 0
	v_pk_fma_f32 v[64:65], v[12:13], v[80:81], v[64:65] neg_lo:[1,0,0] neg_hi:[1,0,0]
	s_nop 0
	v_pk_fma_f32 v[64:65], v[14:15], v[88:89], v[64:65] neg_lo:[1,0,0] neg_hi:[1,0,0]
	s_nop 0
	v_pk_fma_f32 v[64:65], v[16:17], v[90:91], v[64:65] neg_lo:[1,0,0] neg_hi:[1,0,0]
	s_nop 0
	v_pk_fma_f32 v[64:65], v[18:19], v[96:97], v[64:65] neg_lo:[1,0,0] neg_hi:[1,0,0]
	s_nop 0
	v_pk_fma_f32 v[64:65], v[20:21], v[98:99], v[64:65] neg_lo:[1,0,0] neg_hi:[1,0,0]
	s_nop 0
	v_pk_fma_f32 v[64:65], v[22:23], v[100:101], v[64:65] neg_lo:[1,0,0] neg_hi:[1,0,0]
	s_nop 0
	v_pk_fma_f32 v[64:65], v[24:25], v[102:103], v[64:65] neg_lo:[1,0,0] neg_hi:[1,0,0]
	s_nop 0
	v_pk_fma_f32 v[64:65], v[26:27], v[104:105], v[64:65] neg_lo:[1,0,0] neg_hi:[1,0,0]
	s_nop 0
	v_pk_fma_f32 v[64:65], v[28:29], v[106:107], v[64:65] neg_lo:[1,0,0] neg_hi:[1,0,0]
	s_nop 0
	v_pk_fma_f32 v[64:65], v[30:31], v[108:109], v[64:65] neg_lo:[1,0,0] neg_hi:[1,0,0]
	s_nop 0
	v_pk_fma_f32 v[64:65], v[32:33], v[110:111], v[64:65] neg_lo:[1,0,0] neg_hi:[1,0,0]
	s_nop 0
	v_pk_fma_f32 v[64:65], v[34:35], v[120:121], v[64:65] neg_lo:[1,0,0] neg_hi:[1,0,0]
	s_nop 0
	v_pk_fma_f32 v[64:65], v[36:37], v[122:123], v[64:65] neg_lo:[1,0,0] neg_hi:[1,0,0]
	s_nop 0
	v_pk_fma_f32 v[64:65], v[38:39], v[128:129], v[64:65] neg_lo:[1,0,0] neg_hi:[1,0,0]
	s_nop 0
	v_pk_fma_f32 v[64:65], v[40:41], v[130:131], v[64:65] neg_lo:[1,0,0] neg_hi:[1,0,0]
	s_nop 0
	v_pk_fma_f32 v[64:65], v[42:43], v[146:147], v[64:65] neg_lo:[1,0,0] neg_hi:[1,0,0]
	s_nop 0
	v_pk_fma_f32 v[64:65], v[44:45], v[148:149], v[64:65] neg_lo:[1,0,0] neg_hi:[1,0,0]
	s_nop 0
	v_pk_fma_f32 v[64:65], v[46:47], v[158:159], v[64:65] neg_lo:[1,0,0] neg_hi:[1,0,0]
	s_nop 0
	v_pk_fma_f32 v[64:65], v[48:49], v[160:161], v[64:65] neg_lo:[1,0,0] neg_hi:[1,0,0]
	s_nop 0
	v_pk_fma_f32 v[64:65], v[52:53], v[136:137], v[64:65] neg_lo:[1,0,0] neg_hi:[1,0,0]
	s_nop 0
	s_waitcnt lgkmcnt(0)
; DI void gdn_prep_item(const Params& P, int l, int n, int hh, char* smem) {
;     ...
;     for (int i = 1; i < 64; ++i) {
;       f32x4 (&CUR)[16] = (i & 1) ? LA : LB; f32x4 (&NXT)[16] = (i & 1) ? LB : LA;
;       if (i + 1 < 64) {
; #pragma unroll
;         for (int c = 0; c < (i + 4) / 4; ++c) NXT[c] = *(const f32x4*)(Lm + (i + 1) * 64 + 4 * c);
;         rh[(i + 1) & 1] = sp[i + 1] * rp[(i + 1) * 128];
;       }
;       __builtin_amdgcn_sched_barrier(0);
;       f32x2 acc = {rh[i & 1], 0.f};
; #pragma unroll
;       for (int p = 0; p < i / 2; ++p) { const f32x2 lp = (p & 1) ? (f32x2){CUR[p >> 1].z, CUR[p >> 1].w} : (f32x2){CUR[p >> 1].x, CUR[p >> 1].y}; acc = acc - lp * xx[p]; }
;       if (i & 1) { const int j = i - 1; const float lj = ((j & 3) == 0) ? CUR[j >> 2].x : CUR[j >> 2].z; acc.x = fmaf(-lj, xx[j >> 1].x, acc.x); }
;       const float xi = acc.x + acc.y;
;       if (i & 1) xx[i >> 1].y = xi; else xx[i >> 1].x = xi;
;       __builtin_amdgcn_sched_barrier(0);
;     }
	v_mul_f32_e32 v0, v0, v55
	v_fma_f32 v55, -v138, v54, v64
	v_add_f32_e32 v55, v65, v55
	v_mov_b32_e32 v64, 0x1bd00
	ds_read_b128 v[70:73], v64
	v_mov_b32_e32 v64, 0x1bd10
	ds_read_b128 v[74:77], v64
	v_mov_b32_e32 v64, 0x1bd20
	ds_read_b128 v[78:81], v64
	v_mov_b32_e32 v64, 0x1bd30
	ds_read_b128 v[88:91], v64
	v_mov_b32_e32 v64, 0x1bd40
	ds_read_b128 v[96:99], v64
	v_mov_b32_e32 v64, 0x1bd50
	ds_read_b128 v[100:103], v64
	v_mov_b32_e32 v64, 0x1bd60
	ds_read_b128 v[104:107], v64
	v_mov_b32_e32 v64, 0x1bd70
	ds_read_b128 v[108:111], v64
	v_mov_b32_e32 v64, 0x1bd80
	ds_read_b128 v[120:123], v64
	v_mov_b32_e32 v64, 0x1bd90
	ds_read_b128 v[128:131], v64
	v_mov_b32_e32 v64, 0x1bda0
	ds_read_b128 v[136:139], v64
	v_mov_b32_e32 v64, 0x1bdb0
	ds_read_b128 v[144:147], v64
	v_mov_b32_e32 v64, 0x1bdc0
	ds_read_b128 v[158:161], v64
	v_mov_b32_e32 v64, 0x1bdd0
	ds_read_b128 v[170:173], v64
	v_or_b32_e32 v64, 0x1c8d4, v67
	ds_read_b32 v64, v64
	ds_read_b32 v65, v66 offset:27136
	v_pk_fma_f32 v[56:57], v[2:3], v[56:57], v[0:1] neg_lo:[1,0,0] neg_hi:[1,0,0]
	s_nop 0
	v_pk_fma_f32 v[56:57], v[4:5], v[58:59], v[56:57] neg_lo:[1,0,0] neg_hi:[1,0,0]
	s_nop 0
	v_pk_fma_f32 v[56:57], v[6:7], v[60:61], v[56:57] neg_lo:[1,0,0] neg_hi:[1,0,0]
	s_nop 0
	v_pk_fma_f32 v[56:57], v[8:9], v[62:63], v[56:57] neg_lo:[1,0,0] neg_hi:[1,0,0]
	s_nop 0
	v_pk_fma_f32 v[56:57], v[10:11], v[84:85], v[56:57] neg_lo:[1,0,0] neg_hi:[1,0,0]
	s_nop 0
	v_pk_fma_f32 v[56:57], v[12:13], v[86:87], v[56:57] neg_lo:[1,0,0] neg_hi:[1,0,0]
	s_nop 0
	v_pk_fma_f32 v[56:57], v[14:15], v[92:93], v[56:57] neg_lo:[1,0,0] neg_hi:[1,0,0]
	s_nop 0
	v_pk_fma_f32 v[56:57], v[16:17], v[94:95], v[56:57] neg_lo:[1,0,0] neg_hi:[1,0,0]
	s_nop 0
	v_pk_fma_f32 v[56:57], v[18:19], v[112:113], v[56:57] neg_lo:[1,0,0] neg_hi:[1,0,0]
	s_nop 0
	v_pk_fma_f32 v[56:57], v[20:21], v[114:115], v[56:57] neg_lo:[1,0,0] neg_hi:[1,0,0]
	s_nop 0
	v_pk_fma_f32 v[56:57], v[22:23], v[116:117], v[56:57] neg_lo:[1,0,0] neg_hi:[1,0,0]
	s_nop 0
	v_pk_fma_f32 v[56:57], v[24:25], v[118:119], v[56:57] neg_lo:[1,0,0] neg_hi:[1,0,0]
	s_nop 0
	v_pk_fma_f32 v[56:57], v[26:27], v[124:125], v[56:57] neg_lo:[1,0,0] neg_hi:[1,0,0]
	s_nop 0
	v_pk_fma_f32 v[56:57], v[28:29], v[126:127], v[56:57] neg_lo:[1,0,0] neg_hi:[1,0,0]
	s_nop 0
	v_pk_fma_f32 v[56:57], v[30:31], v[132:133], v[56:57] neg_lo:[1,0,0] neg_hi:[1,0,0]
	s_nop 0
	v_pk_fma_f32 v[56:57], v[32:33], v[134:135], v[56:57] neg_lo:[1,0,0] neg_hi:[1,0,0]
	s_nop 0
	v_pk_fma_f32 v[56:57], v[34:35], v[140:141], v[56:57] neg_lo:[1,0,0] neg_hi:[1,0,0]
	s_nop 0
	v_pk_fma_f32 v[56:57], v[36:37], v[142:143], v[56:57] neg_lo:[1,0,0] neg_hi:[1,0,0]
	s_nop 0
	v_pk_fma_f32 v[56:57], v[38:39], v[150:151], v[56:57] neg_lo:[1,0,0] neg_hi:[1,0,0]
	s_nop 0
	v_pk_fma_f32 v[56:57], v[40:41], v[152:153], v[56:57] neg_lo:[1,0,0] neg_hi:[1,0,0]
	s_nop 0
	v_pk_fma_f32 v[56:57], v[42:43], v[162:163], v[56:57] neg_lo:[1,0,0] neg_hi:[1,0,0]
	s_nop 0
	v_pk_fma_f32 v[56:57], v[44:45], v[164:165], v[56:57] neg_lo:[1,0,0] neg_hi:[1,0,0]
	s_nop 0
	v_pk_fma_f32 v[56:57], v[46:47], v[166:167], v[56:57] neg_lo:[1,0,0] neg_hi:[1,0,0]
	s_nop 0
	v_pk_fma_f32 v[56:57], v[48:49], v[168:169], v[56:57] neg_lo:[1,0,0] neg_hi:[1,0,0]
	s_nop 0
	v_pk_fma_f32 v[56:57], v[52:53], v[154:155], v[56:57] neg_lo:[1,0,0] neg_hi:[1,0,0]
	s_nop 0
	v_pk_fma_f32 v[56:57], v[156:157], v[54:55], v[56:57] neg_lo:[1,0,0] neg_hi:[1,0,0]
	s_nop 0
	v_pk_add_f32 v[56:57], v[56:57], v[56:57] op_sel:[0,1] op_sel_hi:[1,0]
	s_waitcnt lgkmcnt(0)
	v_mul_f32_e32 v172, v64, v65
	v_mov_b32_e32 v0, 0x1be00
	ds_read_b128 v[58:61], v0
	v_mov_b32_e32 v0, 0x1be10
	ds_read_b128 v[62:65], v0
	v_mov_b32_e32 v0, 0x1be20
	ds_read_b128 v[84:87], v0
	v_mov_b32_e32 v0, 0x1be30
	ds_read_b128 v[92:95], v0
	v_mov_b32_e32 v0, 0x1be40
	ds_read_b128 v[112:115], v0
	v_mov_b32_e32 v0, 0x1be50
	ds_read_b128 v[116:119], v0
	v_mov_b32_e32 v0, 0x1be60
	ds_read_b128 v[124:127], v0
	v_mov_b32_e32 v0, 0x1be70
	ds_read_b128 v[132:135], v0
	v_mov_b32_e32 v0, 0x1be80
	ds_read_b128 v[140:143], v0
	v_mov_b32_e32 v0, 0x1be90
	ds_read_b128 v[148:151], v0
	v_mov_b32_e32 v0, 0x1bea0
	ds_read_b128 v[152:155], v0
	v_mov_b32_e32 v0, 0x1beb0
	ds_read_b128 v[162:165], v0
	v_or_b32_e32 v0, 0x1c8d8, v67
	v_mov_b32_e32 v83, 0x1bec0
	ds_read_b32 v0, v0
	ds_read_b32 v57, v66 offset:27648
	ds_read_b128 v[166:169], v83
	v_mov_b32_e32 v83, 0x1bed0
	ds_read_b64 v[174:175], v83
	v_mov_b32_e32 v173, v1
	v_pk_fma_f32 v[70:71], v[2:3], v[70:71], v[172:173] neg_lo:[1,0,0] neg_hi:[1,0,0]
	s_nop 0
	v_pk_fma_f32 v[70:71], v[4:5], v[72:73], v[70:71] neg_lo:[1,0,0] neg_hi:[1,0,0]
	s_nop 0
	v_pk_fma_f32 v[70:71], v[6:7], v[74:75], v[70:71] neg_lo:[1,0,0] neg_hi:[1,0,0]
	s_nop 0
	v_pk_fma_f32 v[70:71], v[8:9], v[76:77], v[70:71] neg_lo:[1,0,0] neg_hi:[1,0,0]
	s_nop 0
	v_pk_fma_f32 v[70:71], v[10:11], v[78:79], v[70:71] neg_lo:[1,0,0] neg_hi:[1,0,0]
	s_nop 0
	v_pk_fma_f32 v[70:71], v[12:13], v[80:81], v[70:71] neg_lo:[1,0,0] neg_hi:[1,0,0]
	s_nop 0
	v_pk_fma_f32 v[70:71], v[14:15], v[88:89], v[70:71] neg_lo:[1,0,0] neg_hi:[1,0,0]
	s_nop 0
	v_pk_fma_f32 v[70:71], v[16:17], v[90:91], v[70:71] neg_lo:[1,0,0] neg_hi:[1,0,0]
	s_nop 0
	v_pk_fma_f32 v[70:71], v[18:19], v[96:97], v[70:71] neg_lo:[1,0,0] neg_hi:[1,0,0]
	s_nop 0
	v_pk_fma_f32 v[70:71], v[20:21], v[98:99], v[70:71] neg_lo:[1,0,0] neg_hi:[1,0,0]
	s_nop 0
	v_pk_fma_f32 v[70:71], v[22:23], v[100:101], v[70:71] neg_lo:[1,0,0] neg_hi:[1,0,0]
	s_nop 0
	v_pk_fma_f32 v[70:71], v[24:25], v[102:103], v[70:71] neg_lo:[1,0,0] neg_hi:[1,0,0]
	s_nop 0
	v_pk_fma_f32 v[70:71], v[26:27], v[104:105], v[70:71] neg_lo:[1,0,0] neg_hi:[1,0,0]
	s_nop 0
	v_pk_fma_f32 v[70:71], v[28:29], v[106:107], v[70:71] neg_lo:[1,0,0] neg_hi:[1,0,0]
	s_nop 0
	v_pk_fma_f32 v[70:71], v[30:31], v[108:109], v[70:71] neg_lo:[1,0,0] neg_hi:[1,0,0]
	s_nop 0
	v_pk_fma_f32 v[70:71], v[32:33], v[110:111], v[70:71] neg_lo:[1,0,0] neg_hi:[1,0,0]
	s_nop 0
	v_pk_fma_f32 v[70:71], v[34:35], v[120:121], v[70:71] neg_lo:[1,0,0] neg_hi:[1,0,0]
	s_nop 0
	v_pk_fma_f32 v[70:71], v[36:37], v[122:123], v[70:71] neg_lo:[1,0,0] neg_hi:[1,0,0]
	s_nop 0
	v_pk_fma_f32 v[70:71], v[38:39], v[128:129], v[70:71] neg_lo:[1,0,0] neg_hi:[1,0,0]
	s_nop 0
	v_pk_fma_f32 v[70:71], v[40:41], v[130:131], v[70:71] neg_lo:[1,0,0] neg_hi:[1,0,0]
	s_nop 0
	v_pk_fma_f32 v[70:71], v[42:43], v[136:137], v[70:71] neg_lo:[1,0,0] neg_hi:[1,0,0]
	s_nop 0
	v_pk_fma_f32 v[70:71], v[44:45], v[138:139], v[70:71] neg_lo:[1,0,0] neg_hi:[1,0,0]
	s_nop 0
	v_pk_fma_f32 v[70:71], v[46:47], v[144:145], v[70:71] neg_lo:[1,0,0] neg_hi:[1,0,0]
	s_nop 0
	v_pk_fma_f32 v[70:71], v[48:49], v[146:147], v[70:71] neg_lo:[1,0,0] neg_hi:[1,0,0]
	s_nop 0
	v_pk_fma_f32 v[70:71], v[52:53], v[158:159], v[70:71] neg_lo:[1,0,0] neg_hi:[1,0,0]
	s_nop 0
	v_pk_fma_f32 v[70:71], v[54:55], v[160:161], v[70:71] neg_lo:[1,0,0] neg_hi:[1,0,0]
	s_nop 0
	s_waitcnt lgkmcnt(0)
; DI void gdn_prep_item(const Params& P, int l, int n, int hh, char* smem) {
;     ...
;     for (int i = 1; i < 64; ++i) {
;       f32x4 (&CUR)[16] = (i & 1) ? LA : LB; f32x4 (&NXT)[16] = (i & 1) ? LB : LA;
;       if (i + 1 < 64) {
; #pragma unroll
;         for (int c = 0; c < (i + 4) / 4; ++c) NXT[c] = *(const f32x4*)(Lm + (i + 1) * 64 + 4 * c);
;         rh[(i + 1) & 1] = sp[i + 1] * rp[(i + 1) * 128];
;       }
;       __builtin_amdgcn_sched_barrier(0);
;       f32x2 acc = {rh[i & 1], 0.f};
; #pragma unroll
;       for (int p = 0; p < i / 2; ++p) { const f32x2 lp = (p & 1) ? (f32x2){CUR[p >> 1].z, CUR[p >> 1].w} : (f32x2){CUR[p >> 1].x, CUR[p >> 1].y}; acc = acc - lp * xx[p]; }
;       if (i & 1) { const int j = i - 1; const float lj = ((j & 3) == 0) ? CUR[j >> 2].x : CUR[j >> 2].z; acc.x = fmaf(-lj, xx[j >> 1].x, acc.x); }
;       const float xi = acc.x + acc.y;
;       if (i & 1) xx[i >> 1].y = xi; else xx[i >> 1].x = xi;
;       __builtin_amdgcn_sched_barrier(0);
;     }
	v_mul_f32_e32 v0, v0, v57
	v_fma_f32 v57, -v170, v56, v70
	v_add_f32_e32 v57, v71, v57
	v_mov_b32_e32 v78, 0x1bf20
	v_mov_b32_e32 v83, 0x1bf30
	ds_read_b128 v[78:81], v78
	ds_read_b128 v[88:91], v83
	v_mov_b32_e32 v83, 0x1bf40
	ds_read_b128 v[96:99], v83
	v_mov_b32_e32 v83, 0x1bf50
	ds_read_b128 v[100:103], v83
	v_mov_b32_e32 v83, 0x1bf60
	ds_read_b128 v[104:107], v83
	v_mov_b32_e32 v83, 0x1bf70
	ds_read_b128 v[108:111], v83
	v_mov_b32_e32 v83, 0x1bf80
	ds_read_b128 v[120:123], v83
	v_mov_b32_e32 v83, 0x1bf90
	ds_read_b128 v[128:131], v83
	v_mov_b32_e32 v83, 0x1bfa0
	ds_read_b128 v[136:139], v83
	v_mov_b32_e32 v83, 0x1bfb0
	v_mov_b32_e32 v70, 0x1bf00
	v_mov_b32_e32 v74, 0x1bf10
	ds_read_b128 v[144:147], v83
	v_or_b32_e32 v83, 0x1c8dc, v67
	ds_read_b128 v[70:73], v70
	ds_read_b128 v[74:77], v74
	ds_read_b32 v83, v83
	ds_read_b32 v160, v66 offset:28160
	v_mov_b32_e32 v156, 0x1bfc0
	v_mov_b32_e32 v161, 0x1bfd0
	ds_read_b128 v[156:159], v156
	ds_read_b128 v[170:173], v161
	v_pk_fma_f32 v[58:59], v[2:3], v[58:59], v[0:1] neg_lo:[1,0,0] neg_hi:[1,0,0]
	s_nop 0
	v_pk_fma_f32 v[58:59], v[4:5], v[60:61], v[58:59] neg_lo:[1,0,0] neg_hi:[1,0,0]
	s_nop 0
	v_pk_fma_f32 v[58:59], v[6:7], v[62:63], v[58:59] neg_lo:[1,0,0] neg_hi:[1,0,0]
	s_nop 0
	v_pk_fma_f32 v[58:59], v[8:9], v[64:65], v[58:59] neg_lo:[1,0,0] neg_hi:[1,0,0]
	s_nop 0
	v_pk_fma_f32 v[58:59], v[10:11], v[84:85], v[58:59] neg_lo:[1,0,0] neg_hi:[1,0,0]
	s_nop 0
	v_pk_fma_f32 v[58:59], v[12:13], v[86:87], v[58:59] neg_lo:[1,0,0] neg_hi:[1,0,0]
	s_nop 0
	v_pk_fma_f32 v[58:59], v[14:15], v[92:93], v[58:59] neg_lo:[1,0,0] neg_hi:[1,0,0]
	s_nop 0
	v_pk_fma_f32 v[58:59], v[16:17], v[94:95], v[58:59] neg_lo:[1,0,0] neg_hi:[1,0,0]
	s_nop 0
	v_pk_fma_f32 v[58:59], v[18:19], v[112:113], v[58:59] neg_lo:[1,0,0] neg_hi:[1,0,0]
	s_nop 0
	v_pk_fma_f32 v[58:59], v[20:21], v[114:115], v[58:59] neg_lo:[1,0,0] neg_hi:[1,0,0]
	s_nop 0
	v_pk_fma_f32 v[58:59], v[22:23], v[116:117], v[58:59] neg_lo:[1,0,0] neg_hi:[1,0,0]
	s_nop 0
	v_pk_fma_f32 v[58:59], v[24:25], v[118:119], v[58:59] neg_lo:[1,0,0] neg_hi:[1,0,0]
	s_nop 0
	v_pk_fma_f32 v[58:59], v[26:27], v[124:125], v[58:59] neg_lo:[1,0,0] neg_hi:[1,0,0]
	s_nop 0
	v_pk_fma_f32 v[58:59], v[28:29], v[126:127], v[58:59] neg_lo:[1,0,0] neg_hi:[1,0,0]
	s_nop 0
	v_pk_fma_f32 v[58:59], v[30:31], v[132:133], v[58:59] neg_lo:[1,0,0] neg_hi:[1,0,0]
	s_nop 0
	v_pk_fma_f32 v[58:59], v[32:33], v[134:135], v[58:59] neg_lo:[1,0,0] neg_hi:[1,0,0]
	s_nop 0
	v_pk_fma_f32 v[58:59], v[34:35], v[140:141], v[58:59] neg_lo:[1,0,0] neg_hi:[1,0,0]
	s_nop 0
	v_pk_fma_f32 v[58:59], v[36:37], v[142:143], v[58:59] neg_lo:[1,0,0] neg_hi:[1,0,0]
	s_nop 0
	v_pk_fma_f32 v[58:59], v[38:39], v[148:149], v[58:59] neg_lo:[1,0,0] neg_hi:[1,0,0]
	s_nop 0
	v_pk_fma_f32 v[58:59], v[40:41], v[150:151], v[58:59] neg_lo:[1,0,0] neg_hi:[1,0,0]
	s_nop 0
	v_pk_fma_f32 v[58:59], v[42:43], v[152:153], v[58:59] neg_lo:[1,0,0] neg_hi:[1,0,0]
	s_nop 0
	v_pk_fma_f32 v[58:59], v[44:45], v[154:155], v[58:59] neg_lo:[1,0,0] neg_hi:[1,0,0]
	s_nop 0
	v_pk_fma_f32 v[58:59], v[46:47], v[162:163], v[58:59] neg_lo:[1,0,0] neg_hi:[1,0,0]
	s_nop 0
	v_pk_fma_f32 v[58:59], v[48:49], v[164:165], v[58:59] neg_lo:[1,0,0] neg_hi:[1,0,0]
	s_nop 0
	v_pk_fma_f32 v[58:59], v[52:53], v[166:167], v[58:59] neg_lo:[1,0,0] neg_hi:[1,0,0]
	s_nop 0
	v_pk_fma_f32 v[58:59], v[54:55], v[168:169], v[58:59] neg_lo:[1,0,0] neg_hi:[1,0,0]
	s_nop 0
	v_pk_fma_f32 v[58:59], v[174:175], v[56:57], v[58:59] neg_lo:[1,0,0] neg_hi:[1,0,0]
	s_nop 0
	v_pk_add_f32 v[58:59], v[58:59], v[58:59] op_sel:[0,1] op_sel_hi:[1,0]
	s_waitcnt lgkmcnt(0)
	v_mul_f32_e32 v182, v83, v160
	v_mov_b32_e32 v0, 0x1c000
	ds_read_b128 v[60:63], v0
	v_mov_b32_e32 v0, 0x1c010
	ds_read_b128 v[84:87], v0
	v_mov_b32_e32 v0, 0x1c020
	ds_read_b128 v[92:95], v0
	v_mov_b32_e32 v0, 0x1c030
	ds_read_b128 v[112:115], v0
	v_mov_b32_e32 v0, 0x1c040
	ds_read_b128 v[116:119], v0
	v_mov_b32_e32 v0, 0x1c050
	ds_read_b128 v[124:127], v0
	v_mov_b32_e32 v0, 0x1c060
	ds_read_b128 v[132:135], v0
	v_mov_b32_e32 v0, 0x1c070
	ds_read_b128 v[140:143], v0
	v_mov_b32_e32 v0, 0x1c080
	ds_read_b128 v[148:151], v0
	v_mov_b32_e32 v0, 0x1c090
	ds_read_b128 v[152:155], v0
	v_mov_b32_e32 v0, 0x1c0a0
	ds_read_b128 v[160:163], v0
	v_mov_b32_e32 v0, 0x1c0b0
	ds_read_b128 v[164:167], v0
	v_or_b32_e32 v0, 0x1c8e0, v67
	v_mov_b32_e32 v64, 0x1c0c0
	ds_read_b32 v0, v0
	ds_read_b32 v59, v66 offset:28672
	ds_read_b128 v[174:177], v64
	v_mov_b32_e32 v64, 0x1c0d0
	ds_read_b128 v[178:181], v64
	v_mov_b32_e32 v183, v1
	v_pk_fma_f32 v[64:65], v[2:3], v[70:71], v[182:183] neg_lo:[1,0,0] neg_hi:[1,0,0]
	s_nop 0
	v_pk_fma_f32 v[64:65], v[4:5], v[72:73], v[64:65] neg_lo:[1,0,0] neg_hi:[1,0,0]
	s_nop 0
	v_pk_fma_f32 v[64:65], v[6:7], v[74:75], v[64:65] neg_lo:[1,0,0] neg_hi:[1,0,0]
	s_nop 0
	v_pk_fma_f32 v[64:65], v[8:9], v[76:77], v[64:65] neg_lo:[1,0,0] neg_hi:[1,0,0]
	s_nop 0
	v_pk_fma_f32 v[64:65], v[10:11], v[78:79], v[64:65] neg_lo:[1,0,0] neg_hi:[1,0,0]
	s_nop 0
	v_pk_fma_f32 v[64:65], v[12:13], v[80:81], v[64:65] neg_lo:[1,0,0] neg_hi:[1,0,0]
	s_nop 0
	v_pk_fma_f32 v[64:65], v[14:15], v[88:89], v[64:65] neg_lo:[1,0,0] neg_hi:[1,0,0]
	s_nop 0
	v_pk_fma_f32 v[64:65], v[16:17], v[90:91], v[64:65] neg_lo:[1,0,0] neg_hi:[1,0,0]
	s_nop 0
	v_pk_fma_f32 v[64:65], v[18:19], v[96:97], v[64:65] neg_lo:[1,0,0] neg_hi:[1,0,0]
	s_nop 0
	v_pk_fma_f32 v[64:65], v[20:21], v[98:99], v[64:65] neg_lo:[1,0,0] neg_hi:[1,0,0]
	s_nop 0
	v_pk_fma_f32 v[64:65], v[22:23], v[100:101], v[64:65] neg_lo:[1,0,0] neg_hi:[1,0,0]
	s_nop 0
	v_pk_fma_f32 v[64:65], v[24:25], v[102:103], v[64:65] neg_lo:[1,0,0] neg_hi:[1,0,0]
	s_nop 0
	v_pk_fma_f32 v[64:65], v[26:27], v[104:105], v[64:65] neg_lo:[1,0,0] neg_hi:[1,0,0]
	s_nop 0
	v_pk_fma_f32 v[64:65], v[28:29], v[106:107], v[64:65] neg_lo:[1,0,0] neg_hi:[1,0,0]
	s_nop 0
	v_pk_fma_f32 v[64:65], v[30:31], v[108:109], v[64:65] neg_lo:[1,0,0] neg_hi:[1,0,0]
	s_nop 0
	v_pk_fma_f32 v[64:65], v[32:33], v[110:111], v[64:65] neg_lo:[1,0,0] neg_hi:[1,0,0]
	s_nop 0
	v_pk_fma_f32 v[64:65], v[34:35], v[120:121], v[64:65] neg_lo:[1,0,0] neg_hi:[1,0,0]
	s_nop 0
	v_pk_fma_f32 v[64:65], v[36:37], v[122:123], v[64:65] neg_lo:[1,0,0] neg_hi:[1,0,0]
	s_nop 0
	v_pk_fma_f32 v[64:65], v[38:39], v[128:129], v[64:65] neg_lo:[1,0,0] neg_hi:[1,0,0]
	s_nop 0
	v_pk_fma_f32 v[64:65], v[40:41], v[130:131], v[64:65] neg_lo:[1,0,0] neg_hi:[1,0,0]
	s_nop 0
	v_pk_fma_f32 v[64:65], v[42:43], v[136:137], v[64:65] neg_lo:[1,0,0] neg_hi:[1,0,0]
	s_nop 0
	v_pk_fma_f32 v[64:65], v[44:45], v[138:139], v[64:65] neg_lo:[1,0,0] neg_hi:[1,0,0]
	s_nop 0
	v_pk_fma_f32 v[64:65], v[46:47], v[144:145], v[64:65] neg_lo:[1,0,0] neg_hi:[1,0,0]
	s_nop 0
	v_pk_fma_f32 v[64:65], v[48:49], v[146:147], v[64:65] neg_lo:[1,0,0] neg_hi:[1,0,0]
	s_nop 0
	v_pk_fma_f32 v[64:65], v[52:53], v[156:157], v[64:65] neg_lo:[1,0,0] neg_hi:[1,0,0]
	s_nop 0
	v_pk_fma_f32 v[64:65], v[54:55], v[158:159], v[64:65] neg_lo:[1,0,0] neg_hi:[1,0,0]
	s_nop 0
	v_pk_fma_f32 v[64:65], v[56:57], v[170:171], v[64:65] neg_lo:[1,0,0] neg_hi:[1,0,0]
	s_nop 0
	s_waitcnt lgkmcnt(0)
; DI void gdn_prep_item(const Params& P, int l, int n, int hh, char* smem) {
;     ...
;     for (int i = 1; i < 64; ++i) {
;       f32x4 (&CUR)[16] = (i & 1) ? LA : LB; f32x4 (&NXT)[16] = (i & 1) ? LB : LA;
;       if (i + 1 < 64) {
; #pragma unroll
;         for (int c = 0; c < (i + 4) / 4; ++c) NXT[c] = *(const f32x4*)(Lm + (i + 1) * 64 + 4 * c);
;         rh[(i + 1) & 1] = sp[i + 1] * rp[(i + 1) * 128];
;       }
;       __builtin_amdgcn_sched_barrier(0);
;       f32x2 acc = {rh[i & 1], 0.f};
; #pragma unroll
;       for (int p = 0; p < i / 2; ++p) { const f32x2 lp = (p & 1) ? (f32x2){CUR[p >> 1].z, CUR[p >> 1].w} : (f32x2){CUR[p >> 1].x, CUR[p >> 1].y}; acc = acc - lp * xx[p]; }
;       if (i & 1) { const int j = i - 1; const float lj = ((j & 3) == 0) ? CUR[j >> 2].x : CUR[j >> 2].z; acc.x = fmaf(-lj, xx[j >> 1].x, acc.x); }
;       const float xi = acc.x + acc.y;
;       if (i & 1) xx[i >> 1].y = xi; else xx[i >> 1].x = xi;
;       __builtin_amdgcn_sched_barrier(0);
;     }
	v_mul_f32_e32 v0, v0, v59
	v_fma_f32 v59, -v172, v58, v64
	v_add_f32_e32 v59, v65, v59
	v_mov_b32_e32 v64, 0x1c100
	ds_read_b128 v[70:73], v64
	v_mov_b32_e32 v64, 0x1c110
	ds_read_b128 v[74:77], v64
	v_mov_b32_e32 v64, 0x1c120
	ds_read_b128 v[78:81], v64
	v_mov_b32_e32 v64, 0x1c130
	ds_read_b128 v[88:91], v64
	v_mov_b32_e32 v64, 0x1c140
	ds_read_b128 v[96:99], v64
	v_mov_b32_e32 v64, 0x1c150
	ds_read_b128 v[100:103], v64
	v_mov_b32_e32 v64, 0x1c160
	ds_read_b128 v[104:107], v64
	v_mov_b32_e32 v64, 0x1c170
	ds_read_b128 v[108:111], v64
	v_mov_b32_e32 v64, 0x1c180
	ds_read_b128 v[120:123], v64
	v_mov_b32_e32 v64, 0x1c190
	ds_read_b128 v[128:131], v64
	v_mov_b32_e32 v64, 0x1c1a0
	ds_read_b128 v[136:139], v64
	v_mov_b32_e32 v64, 0x1c1b0
	ds_read_b128 v[144:147], v64
	v_or_b32_e32 v64, 0x1c8e4, v67
	v_mov_b32_e32 v65, 0x1c1e0
	v_mov_b32_e32 v83, 0x1c1c0
	ds_read_b128 v[156:159], v65
	ds_read_b32 v64, v64
	ds_read_b32 v65, v66 offset:29184
	ds_read_b128 v[168:171], v83
	v_mov_b32_e32 v83, 0x1c1d0
	ds_read_b128 v[182:185], v83
	v_pk_fma_f32 v[60:61], v[2:3], v[60:61], v[0:1] neg_lo:[1,0,0] neg_hi:[1,0,0]
	s_nop 0
	v_pk_fma_f32 v[60:61], v[4:5], v[62:63], v[60:61] neg_lo:[1,0,0] neg_hi:[1,0,0]
	s_nop 0
	v_pk_fma_f32 v[60:61], v[6:7], v[84:85], v[60:61] neg_lo:[1,0,0] neg_hi:[1,0,0]
	s_nop 0
	v_pk_fma_f32 v[60:61], v[8:9], v[86:87], v[60:61] neg_lo:[1,0,0] neg_hi:[1,0,0]
	s_nop 0
	v_pk_fma_f32 v[60:61], v[10:11], v[92:93], v[60:61] neg_lo:[1,0,0] neg_hi:[1,0,0]
	s_nop 0
	v_pk_fma_f32 v[60:61], v[12:13], v[94:95], v[60:61] neg_lo:[1,0,0] neg_hi:[1,0,0]
	s_nop 0
	v_pk_fma_f32 v[60:61], v[14:15], v[112:113], v[60:61] neg_lo:[1,0,0] neg_hi:[1,0,0]
	s_nop 0
	v_pk_fma_f32 v[60:61], v[16:17], v[114:115], v[60:61] neg_lo:[1,0,0] neg_hi:[1,0,0]
	s_nop 0
	v_pk_fma_f32 v[60:61], v[18:19], v[116:117], v[60:61] neg_lo:[1,0,0] neg_hi:[1,0,0]
	s_nop 0
	v_pk_fma_f32 v[60:61], v[20:21], v[118:119], v[60:61] neg_lo:[1,0,0] neg_hi:[1,0,0]
	s_nop 0
	v_pk_fma_f32 v[60:61], v[22:23], v[124:125], v[60:61] neg_lo:[1,0,0] neg_hi:[1,0,0]
	s_nop 0
	v_pk_fma_f32 v[60:61], v[24:25], v[126:127], v[60:61] neg_lo:[1,0,0] neg_hi:[1,0,0]
	s_nop 0
	v_pk_fma_f32 v[60:61], v[26:27], v[132:133], v[60:61] neg_lo:[1,0,0] neg_hi:[1,0,0]
	s_nop 0
	v_pk_fma_f32 v[60:61], v[28:29], v[134:135], v[60:61] neg_lo:[1,0,0] neg_hi:[1,0,0]
	s_nop 0
	v_pk_fma_f32 v[60:61], v[30:31], v[140:141], v[60:61] neg_lo:[1,0,0] neg_hi:[1,0,0]
	s_nop 0
	v_pk_fma_f32 v[60:61], v[32:33], v[142:143], v[60:61] neg_lo:[1,0,0] neg_hi:[1,0,0]
	s_nop 0
	v_pk_fma_f32 v[60:61], v[34:35], v[148:149], v[60:61] neg_lo:[1,0,0] neg_hi:[1,0,0]
	s_nop 0
	v_pk_fma_f32 v[60:61], v[36:37], v[150:151], v[60:61] neg_lo:[1,0,0] neg_hi:[1,0,0]
	s_nop 0
	v_pk_fma_f32 v[60:61], v[38:39], v[152:153], v[60:61] neg_lo:[1,0,0] neg_hi:[1,0,0]
	s_nop 0
	v_pk_fma_f32 v[60:61], v[40:41], v[154:155], v[60:61] neg_lo:[1,0,0] neg_hi:[1,0,0]
	s_nop 0
	v_pk_fma_f32 v[60:61], v[42:43], v[160:161], v[60:61] neg_lo:[1,0,0] neg_hi:[1,0,0]
	s_nop 0
	v_pk_fma_f32 v[60:61], v[44:45], v[162:163], v[60:61] neg_lo:[1,0,0] neg_hi:[1,0,0]
	s_nop 0
	v_pk_fma_f32 v[60:61], v[46:47], v[164:165], v[60:61] neg_lo:[1,0,0] neg_hi:[1,0,0]
	s_nop 0
	v_pk_fma_f32 v[60:61], v[48:49], v[166:167], v[60:61] neg_lo:[1,0,0] neg_hi:[1,0,0]
	s_nop 0
	v_pk_fma_f32 v[60:61], v[52:53], v[174:175], v[60:61] neg_lo:[1,0,0] neg_hi:[1,0,0]
	s_nop 0
	v_pk_fma_f32 v[60:61], v[54:55], v[176:177], v[60:61] neg_lo:[1,0,0] neg_hi:[1,0,0]
	s_nop 0
	v_pk_fma_f32 v[60:61], v[56:57], v[178:179], v[60:61] neg_lo:[1,0,0] neg_hi:[1,0,0]
	s_nop 0
	v_pk_fma_f32 v[60:61], v[180:181], v[58:59], v[60:61] neg_lo:[1,0,0] neg_hi:[1,0,0]
	s_nop 0
	v_pk_add_f32 v[60:61], v[60:61], v[60:61] op_sel:[0,1] op_sel_hi:[1,0]
	s_waitcnt lgkmcnt(0)
	v_mul_f32_e32 v186, v64, v65
	v_mov_b32_e32 v0, 0x1c200
	ds_read_b128 v[62:65], v0
	v_mov_b32_e32 v0, 0x1c210
	ds_read_b128 v[84:87], v0
	v_mov_b32_e32 v0, 0x1c220
	ds_read_b128 v[92:95], v0
	v_mov_b32_e32 v0, 0x1c230
	ds_read_b128 v[112:115], v0
	v_mov_b32_e32 v0, 0x1c240
	ds_read_b128 v[116:119], v0
	v_mov_b32_e32 v0, 0x1c250
	ds_read_b128 v[124:127], v0
	v_mov_b32_e32 v0, 0x1c260
	ds_read_b128 v[132:135], v0
	v_mov_b32_e32 v0, 0x1c270
	ds_read_b128 v[140:143], v0
	v_mov_b32_e32 v0, 0x1c280
	ds_read_b128 v[148:151], v0
	v_mov_b32_e32 v0, 0x1c290
	ds_read_b128 v[152:155], v0
	v_mov_b32_e32 v0, 0x1c2a0
	ds_read_b128 v[158:161], v0
	v_mov_b32_e32 v0, 0x1c2b0
	ds_read_b128 v[162:165], v0
	v_or_b32_e32 v0, 0x1c8e8, v67
	v_mov_b32_e32 v61, 0x1c2e0
	v_mov_b32_e32 v83, 0x1c2c0
	ds_read_b64 v[188:189], v61
	ds_read_b32 v0, v0
	ds_read_b32 v61, v66 offset:29696
	ds_read_b128 v[172:175], v83
	v_mov_b32_e32 v83, 0x1c2d0
	ds_read_b128 v[176:179], v83
	v_mov_b32_e32 v187, v1
	v_pk_fma_f32 v[70:71], v[2:3], v[70:71], v[186:187] neg_lo:[1,0,0] neg_hi:[1,0,0]
	s_nop 0
	v_pk_fma_f32 v[70:71], v[4:5], v[72:73], v[70:71] neg_lo:[1,0,0] neg_hi:[1,0,0]
	s_nop 0
	v_pk_fma_f32 v[70:71], v[6:7], v[74:75], v[70:71] neg_lo:[1,0,0] neg_hi:[1,0,0]
	s_nop 0
	v_pk_fma_f32 v[70:71], v[8:9], v[76:77], v[70:71] neg_lo:[1,0,0] neg_hi:[1,0,0]
	s_nop 0
	v_pk_fma_f32 v[70:71], v[10:11], v[78:79], v[70:71] neg_lo:[1,0,0] neg_hi:[1,0,0]
	s_nop 0
	v_pk_fma_f32 v[70:71], v[12:13], v[80:81], v[70:71] neg_lo:[1,0,0] neg_hi:[1,0,0]
	s_nop 0
	v_pk_fma_f32 v[70:71], v[14:15], v[88:89], v[70:71] neg_lo:[1,0,0] neg_hi:[1,0,0]
	s_nop 0
	v_pk_fma_f32 v[70:71], v[16:17], v[90:91], v[70:71] neg_lo:[1,0,0] neg_hi:[1,0,0]
	s_nop 0
	v_pk_fma_f32 v[70:71], v[18:19], v[96:97], v[70:71] neg_lo:[1,0,0] neg_hi:[1,0,0]
	s_nop 0
	v_pk_fma_f32 v[70:71], v[20:21], v[98:99], v[70:71] neg_lo:[1,0,0] neg_hi:[1,0,0]
	s_nop 0
; DI void gdn_prep_item(const Params& P, int l, int n, int hh, char* smem) {
;     ...
;     for (int i = 1; i < 64; ++i) {
;       f32x4 (&CUR)[16] = (i & 1) ? LA : LB; f32x4 (&NXT)[16] = (i & 1) ? LB : LA;
;       if (i + 1 < 64) {
; #pragma unroll
;         for (int c = 0; c < (i + 4) / 4; ++c) NXT[c] = *(const f32x4*)(Lm + (i + 1) * 64 + 4 * c);
;         rh[(i + 1) & 1] = sp[i + 1] * rp[(i + 1) * 128];
;       }
;       __builtin_amdgcn_sched_barrier(0);
;       f32x2 acc = {rh[i & 1], 0.f};
; #pragma unroll
;       for (int p = 0; p < i / 2; ++p) { const f32x2 lp = (p & 1) ? (f32x2){CUR[p >> 1].z, CUR[p >> 1].w} : (f32x2){CUR[p >> 1].x, CUR[p >> 1].y}; acc = acc - lp * xx[p]; }
;       if (i & 1) { const int j = i - 1; const float lj = ((j & 3) == 0) ? CUR[j >> 2].x : CUR[j >> 2].z; acc.x = fmaf(-lj, xx[j >> 1].x, acc.x); }
;       const float xi = acc.x + acc.y;
;       if (i & 1) xx[i >> 1].y = xi; else xx[i >> 1].x = xi;
;       __builtin_amdgcn_sched_barrier(0);
;     }
	v_pk_fma_f32 v[70:71], v[22:23], v[100:101], v[70:71] neg_lo:[1,0,0] neg_hi:[1,0,0]
	s_nop 0
	v_pk_fma_f32 v[70:71], v[24:25], v[102:103], v[70:71] neg_lo:[1,0,0] neg_hi:[1,0,0]
	s_nop 0
	v_pk_fma_f32 v[70:71], v[26:27], v[104:105], v[70:71] neg_lo:[1,0,0] neg_hi:[1,0,0]
	s_nop 0
	v_pk_fma_f32 v[70:71], v[28:29], v[106:107], v[70:71] neg_lo:[1,0,0] neg_hi:[1,0,0]
	s_nop 0
	v_pk_fma_f32 v[70:71], v[30:31], v[108:109], v[70:71] neg_lo:[1,0,0] neg_hi:[1,0,0]
	s_nop 0
	v_pk_fma_f32 v[70:71], v[32:33], v[110:111], v[70:71] neg_lo:[1,0,0] neg_hi:[1,0,0]
	s_nop 0
	v_pk_fma_f32 v[70:71], v[34:35], v[120:121], v[70:71] neg_lo:[1,0,0] neg_hi:[1,0,0]
	s_nop 0
	v_pk_fma_f32 v[70:71], v[36:37], v[122:123], v[70:71] neg_lo:[1,0,0] neg_hi:[1,0,0]
	s_nop 0
	v_pk_fma_f32 v[70:71], v[38:39], v[128:129], v[70:71] neg_lo:[1,0,0] neg_hi:[1,0,0]
	s_nop 0
	v_pk_fma_f32 v[70:71], v[40:41], v[130:131], v[70:71] neg_lo:[1,0,0] neg_hi:[1,0,0]
	s_nop 0
	v_pk_fma_f32 v[70:71], v[42:43], v[136:137], v[70:71] neg_lo:[1,0,0] neg_hi:[1,0,0]
	s_nop 0
	v_pk_fma_f32 v[70:71], v[44:45], v[138:139], v[70:71] neg_lo:[1,0,0] neg_hi:[1,0,0]
	s_nop 0
	v_pk_fma_f32 v[70:71], v[46:47], v[144:145], v[70:71] neg_lo:[1,0,0] neg_hi:[1,0,0]
	s_nop 0
	v_pk_fma_f32 v[70:71], v[48:49], v[146:147], v[70:71] neg_lo:[1,0,0] neg_hi:[1,0,0]
	s_nop 0
	v_pk_fma_f32 v[70:71], v[52:53], v[168:169], v[70:71] neg_lo:[1,0,0] neg_hi:[1,0,0]
	s_nop 0
	v_pk_fma_f32 v[70:71], v[54:55], v[170:171], v[70:71] neg_lo:[1,0,0] neg_hi:[1,0,0]
	s_nop 0
	v_pk_fma_f32 v[70:71], v[56:57], v[182:183], v[70:71] neg_lo:[1,0,0] neg_hi:[1,0,0]
	s_nop 0
	v_pk_fma_f32 v[70:71], v[58:59], v[184:185], v[70:71] neg_lo:[1,0,0] neg_hi:[1,0,0]
	s_nop 0
	s_waitcnt lgkmcnt(0)
	v_mul_f32_e32 v0, v0, v61
	v_fma_f32 v61, -v156, v60, v70
	v_add_f32_e32 v61, v71, v61
	v_mov_b32_e32 v78, 0x1c320
	v_mov_b32_e32 v83, 0x1c330
	ds_read_b128 v[78:81], v78
	ds_read_b128 v[88:91], v83
	v_mov_b32_e32 v83, 0x1c340
	ds_read_b128 v[96:99], v83
	v_mov_b32_e32 v83, 0x1c350
	ds_read_b128 v[100:103], v83
	v_mov_b32_e32 v83, 0x1c360
	ds_read_b128 v[104:107], v83
	v_mov_b32_e32 v83, 0x1c370
	ds_read_b128 v[108:111], v83
	v_mov_b32_e32 v83, 0x1c380
	ds_read_b128 v[120:123], v83
	v_mov_b32_e32 v83, 0x1c390
	ds_read_b128 v[128:131], v83
	v_mov_b32_e32 v83, 0x1c3a0
	ds_read_b128 v[136:139], v83
	v_mov_b32_e32 v83, 0x1c3b0
	v_mov_b32_e32 v70, 0x1c300
	v_mov_b32_e32 v74, 0x1c310
	ds_read_b128 v[144:147], v83
	v_or_b32_e32 v83, 0x1c8ec, v67
	v_mov_b32_e32 v156, 0x1c3e0
	v_mov_b32_e32 v157, 0x1c3c0
	ds_read_b128 v[70:73], v70
	ds_read_b128 v[74:77], v74
	ds_read_b128 v[166:169], v156
	ds_read_b32 v83, v83
	ds_read_b32 v156, v66 offset:30208
	ds_read_b128 v[180:183], v157
	v_mov_b32_e32 v157, 0x1c3d0
	ds_read_b128 v[184:187], v157
	v_pk_fma_f32 v[62:63], v[2:3], v[62:63], v[0:1] neg_lo:[1,0,0] neg_hi:[1,0,0]
	s_nop 0
	v_pk_fma_f32 v[62:63], v[4:5], v[64:65], v[62:63] neg_lo:[1,0,0] neg_hi:[1,0,0]
	s_nop 0
	v_pk_fma_f32 v[62:63], v[6:7], v[84:85], v[62:63] neg_lo:[1,0,0] neg_hi:[1,0,0]
	s_nop 0
	v_pk_fma_f32 v[62:63], v[8:9], v[86:87], v[62:63] neg_lo:[1,0,0] neg_hi:[1,0,0]
	s_nop 0
	v_pk_fma_f32 v[62:63], v[10:11], v[92:93], v[62:63] neg_lo:[1,0,0] neg_hi:[1,0,0]
	s_nop 0
	v_pk_fma_f32 v[62:63], v[12:13], v[94:95], v[62:63] neg_lo:[1,0,0] neg_hi:[1,0,0]
	s_nop 0
	v_pk_fma_f32 v[62:63], v[14:15], v[112:113], v[62:63] neg_lo:[1,0,0] neg_hi:[1,0,0]
	s_nop 0
	v_pk_fma_f32 v[62:63], v[16:17], v[114:115], v[62:63] neg_lo:[1,0,0] neg_hi:[1,0,0]
	s_nop 0
	v_pk_fma_f32 v[62:63], v[18:19], v[116:117], v[62:63] neg_lo:[1,0,0] neg_hi:[1,0,0]
	s_nop 0
	v_pk_fma_f32 v[62:63], v[20:21], v[118:119], v[62:63] neg_lo:[1,0,0] neg_hi:[1,0,0]
	s_nop 0
	v_pk_fma_f32 v[62:63], v[22:23], v[124:125], v[62:63] neg_lo:[1,0,0] neg_hi:[1,0,0]
	s_nop 0
	v_pk_fma_f32 v[62:63], v[24:25], v[126:127], v[62:63] neg_lo:[1,0,0] neg_hi:[1,0,0]
	s_nop 0
	v_pk_fma_f32 v[62:63], v[26:27], v[132:133], v[62:63] neg_lo:[1,0,0] neg_hi:[1,0,0]
	s_nop 0
	v_pk_fma_f32 v[62:63], v[28:29], v[134:135], v[62:63] neg_lo:[1,0,0] neg_hi:[1,0,0]
	s_nop 0
	v_pk_fma_f32 v[62:63], v[30:31], v[140:141], v[62:63] neg_lo:[1,0,0] neg_hi:[1,0,0]
	s_nop 0
	v_pk_fma_f32 v[62:63], v[32:33], v[142:143], v[62:63] neg_lo:[1,0,0] neg_hi:[1,0,0]
	s_nop 0
	v_pk_fma_f32 v[62:63], v[34:35], v[148:149], v[62:63] neg_lo:[1,0,0] neg_hi:[1,0,0]
	s_nop 0
	v_pk_fma_f32 v[62:63], v[36:37], v[150:151], v[62:63] neg_lo:[1,0,0] neg_hi:[1,0,0]
	s_nop 0
	v_pk_fma_f32 v[62:63], v[38:39], v[152:153], v[62:63] neg_lo:[1,0,0] neg_hi:[1,0,0]
	s_nop 0
	v_pk_fma_f32 v[62:63], v[40:41], v[154:155], v[62:63] neg_lo:[1,0,0] neg_hi:[1,0,0]
	s_nop 0
	v_pk_fma_f32 v[62:63], v[42:43], v[158:159], v[62:63] neg_lo:[1,0,0] neg_hi:[1,0,0]
	s_nop 0
	v_pk_fma_f32 v[62:63], v[44:45], v[160:161], v[62:63] neg_lo:[1,0,0] neg_hi:[1,0,0]
	s_nop 0
	v_pk_fma_f32 v[62:63], v[46:47], v[162:163], v[62:63] neg_lo:[1,0,0] neg_hi:[1,0,0]
	s_nop 0
	v_pk_fma_f32 v[62:63], v[48:49], v[164:165], v[62:63] neg_lo:[1,0,0] neg_hi:[1,0,0]
	s_nop 0
	v_pk_fma_f32 v[62:63], v[52:53], v[172:173], v[62:63] neg_lo:[1,0,0] neg_hi:[1,0,0]
	s_nop 0
	v_pk_fma_f32 v[62:63], v[54:55], v[174:175], v[62:63] neg_lo:[1,0,0] neg_hi:[1,0,0]
	s_nop 0
	v_pk_fma_f32 v[62:63], v[56:57], v[176:177], v[62:63] neg_lo:[1,0,0] neg_hi:[1,0,0]
	s_nop 0
	v_pk_fma_f32 v[62:63], v[58:59], v[178:179], v[62:63] neg_lo:[1,0,0] neg_hi:[1,0,0]
	s_nop 0
	v_pk_fma_f32 v[62:63], v[188:189], v[60:61], v[62:63] neg_lo:[1,0,0] neg_hi:[1,0,0]
	s_nop 0
	v_pk_add_f32 v[62:63], v[62:63], v[62:63] op_sel:[0,1] op_sel_hi:[1,0]
	s_waitcnt lgkmcnt(0)
; DI void gdn_prep_item(const Params& P, int l, int n, int hh, char* smem) {
;     ...
;     for (int i = 1; i < 64; ++i) {
;       f32x4 (&CUR)[16] = (i & 1) ? LA : LB; f32x4 (&NXT)[16] = (i & 1) ? LB : LA;
;       if (i + 1 < 64) {
; #pragma unroll
;         for (int c = 0; c < (i + 4) / 4; ++c) NXT[c] = *(const f32x4*)(Lm + (i + 1) * 64 + 4 * c);
;         rh[(i + 1) & 1] = sp[i + 1] * rp[(i + 1) * 128];
;       }
;       __builtin_amdgcn_sched_barrier(0);
;       f32x2 acc = {rh[i & 1], 0.f};
; #pragma unroll
;       for (int p = 0; p < i / 2; ++p) { const f32x2 lp = (p & 1) ? (f32x2){CUR[p >> 1].z, CUR[p >> 1].w} : (f32x2){CUR[p >> 1].x, CUR[p >> 1].y}; acc = acc - lp * xx[p]; }
;       if (i & 1) { const int j = i - 1; const float lj = ((j & 3) == 0) ? CUR[j >> 2].x : CUR[j >> 2].z; acc.x = fmaf(-lj, xx[j >> 1].x, acc.x); }
;       const float xi = acc.x + acc.y;
;       if (i & 1) xx[i >> 1].y = xi; else xx[i >> 1].x = xi;
;       __builtin_amdgcn_sched_barrier(0);
;     }
	v_mul_f32_e32 v196, v83, v156
	v_mov_b32_e32 v0, 0x1c400
	ds_read_b128 v[84:87], v0
	v_mov_b32_e32 v0, 0x1c410
	ds_read_b128 v[92:95], v0
	v_mov_b32_e32 v0, 0x1c420
	ds_read_b128 v[112:115], v0
	v_mov_b32_e32 v0, 0x1c430
	ds_read_b128 v[116:119], v0
	v_mov_b32_e32 v0, 0x1c440
	ds_read_b128 v[124:127], v0
	v_mov_b32_e32 v0, 0x1c450
	ds_read_b128 v[132:135], v0
	v_mov_b32_e32 v0, 0x1c460
	ds_read_b128 v[140:143], v0
	v_mov_b32_e32 v0, 0x1c470
	ds_read_b128 v[148:151], v0
	v_mov_b32_e32 v0, 0x1c480
	ds_read_b128 v[152:155], v0
	v_mov_b32_e32 v0, 0x1c490
	ds_read_b128 v[156:159], v0
	v_mov_b32_e32 v0, 0x1c4a0
	ds_read_b128 v[160:163], v0
	v_mov_b32_e32 v0, 0x1c4b0
	ds_read_b128 v[170:173], v0
	v_or_b32_e32 v0, 0x1c8f0, v67
	v_mov_b32_e32 v63, 0x1c4e0
	v_mov_b32_e32 v64, 0x1c4c0
	ds_read_b128 v[174:177], v63
	ds_read_b32 v0, v0
	ds_read_b32 v63, v66 offset:30720
	ds_read_b128 v[188:191], v64
	v_mov_b32_e32 v64, 0x1c4d0
	ds_read_b128 v[192:195], v64
	v_mov_b32_e32 v197, v1
	v_pk_fma_f32 v[64:65], v[2:3], v[70:71], v[196:197] neg_lo:[1,0,0] neg_hi:[1,0,0]
	s_nop 0
	v_pk_fma_f32 v[64:65], v[4:5], v[72:73], v[64:65] neg_lo:[1,0,0] neg_hi:[1,0,0]
	s_nop 0
	v_pk_fma_f32 v[64:65], v[6:7], v[74:75], v[64:65] neg_lo:[1,0,0] neg_hi:[1,0,0]
	s_nop 0
	v_pk_fma_f32 v[64:65], v[8:9], v[76:77], v[64:65] neg_lo:[1,0,0] neg_hi:[1,0,0]
	s_nop 0
	v_pk_fma_f32 v[64:65], v[10:11], v[78:79], v[64:65] neg_lo:[1,0,0] neg_hi:[1,0,0]
	s_nop 0
	v_pk_fma_f32 v[64:65], v[12:13], v[80:81], v[64:65] neg_lo:[1,0,0] neg_hi:[1,0,0]
	s_nop 0
	v_pk_fma_f32 v[64:65], v[14:15], v[88:89], v[64:65] neg_lo:[1,0,0] neg_hi:[1,0,0]
	s_nop 0
	v_pk_fma_f32 v[64:65], v[16:17], v[90:91], v[64:65] neg_lo:[1,0,0] neg_hi:[1,0,0]
	s_nop 0
	v_pk_fma_f32 v[64:65], v[18:19], v[96:97], v[64:65] neg_lo:[1,0,0] neg_hi:[1,0,0]
	s_nop 0
	v_pk_fma_f32 v[64:65], v[20:21], v[98:99], v[64:65] neg_lo:[1,0,0] neg_hi:[1,0,0]
	s_nop 0
	v_pk_fma_f32 v[64:65], v[22:23], v[100:101], v[64:65] neg_lo:[1,0,0] neg_hi:[1,0,0]
	s_nop 0
	v_pk_fma_f32 v[64:65], v[24:25], v[102:103], v[64:65] neg_lo:[1,0,0] neg_hi:[1,0,0]
	s_nop 0
	v_pk_fma_f32 v[64:65], v[26:27], v[104:105], v[64:65] neg_lo:[1,0,0] neg_hi:[1,0,0]
	s_nop 0
	v_pk_fma_f32 v[64:65], v[28:29], v[106:107], v[64:65] neg_lo:[1,0,0] neg_hi:[1,0,0]
	s_nop 0
	v_pk_fma_f32 v[64:65], v[30:31], v[108:109], v[64:65] neg_lo:[1,0,0] neg_hi:[1,0,0]
	s_nop 0
	v_pk_fma_f32 v[64:65], v[32:33], v[110:111], v[64:65] neg_lo:[1,0,0] neg_hi:[1,0,0]
	s_nop 0
	v_pk_fma_f32 v[64:65], v[34:35], v[120:121], v[64:65] neg_lo:[1,0,0] neg_hi:[1,0,0]
	s_nop 0
	v_pk_fma_f32 v[64:65], v[36:37], v[122:123], v[64:65] neg_lo:[1,0,0] neg_hi:[1,0,0]
	s_nop 0
	v_pk_fma_f32 v[64:65], v[38:39], v[128:129], v[64:65] neg_lo:[1,0,0] neg_hi:[1,0,0]
	s_nop 0
	v_pk_fma_f32 v[64:65], v[40:41], v[130:131], v[64:65] neg_lo:[1,0,0] neg_hi:[1,0,0]
	s_nop 0
	v_pk_fma_f32 v[64:65], v[42:43], v[136:137], v[64:65] neg_lo:[1,0,0] neg_hi:[1,0,0]
	s_nop 0
	v_pk_fma_f32 v[64:65], v[44:45], v[138:139], v[64:65] neg_lo:[1,0,0] neg_hi:[1,0,0]
	s_nop 0
	v_pk_fma_f32 v[64:65], v[46:47], v[144:145], v[64:65] neg_lo:[1,0,0] neg_hi:[1,0,0]
	s_nop 0
	v_pk_fma_f32 v[64:65], v[48:49], v[146:147], v[64:65] neg_lo:[1,0,0] neg_hi:[1,0,0]
	s_nop 0
	v_pk_fma_f32 v[64:65], v[52:53], v[180:181], v[64:65] neg_lo:[1,0,0] neg_hi:[1,0,0]
	s_nop 0
	v_pk_fma_f32 v[64:65], v[54:55], v[182:183], v[64:65] neg_lo:[1,0,0] neg_hi:[1,0,0]
	s_nop 0
	v_pk_fma_f32 v[64:65], v[56:57], v[184:185], v[64:65] neg_lo:[1,0,0] neg_hi:[1,0,0]
	s_nop 0
	v_pk_fma_f32 v[64:65], v[58:59], v[186:187], v[64:65] neg_lo:[1,0,0] neg_hi:[1,0,0]
	s_nop 0
	v_pk_fma_f32 v[64:65], v[60:61], v[166:167], v[64:65] neg_lo:[1,0,0] neg_hi:[1,0,0]
	s_nop 0
	s_waitcnt lgkmcnt(0)
	v_mul_f32_e32 v0, v0, v63
	v_fma_f32 v63, -v168, v62, v64
	v_add_f32_e32 v63, v65, v63
	v_mov_b32_e32 v64, 0x1c500
	ds_read_b128 v[70:73], v64
	v_mov_b32_e32 v64, 0x1c510
	ds_read_b128 v[74:77], v64
	v_mov_b32_e32 v64, 0x1c520
	ds_read_b128 v[78:81], v64
	v_mov_b32_e32 v64, 0x1c530
	ds_read_b128 v[88:91], v64
	v_mov_b32_e32 v64, 0x1c540
	ds_read_b128 v[96:99], v64
	v_mov_b32_e32 v64, 0x1c550
	ds_read_b128 v[100:103], v64
	v_mov_b32_e32 v64, 0x1c560
	ds_read_b128 v[104:107], v64
	v_mov_b32_e32 v64, 0x1c570
	ds_read_b128 v[108:111], v64
	v_mov_b32_e32 v64, 0x1c580
	ds_read_b128 v[120:123], v64
	v_mov_b32_e32 v64, 0x1c590
	ds_read_b128 v[128:131], v64
	v_mov_b32_e32 v64, 0x1c5a0
	ds_read_b128 v[136:139], v64
	v_mov_b32_e32 v64, 0x1c5b0
	ds_read_b128 v[144:147], v64
	v_mov_b32_e32 v64, 0x1c5c0
	ds_read_b128 v[164:167], v64
	v_mov_b32_e32 v64, 0x1c5d0
	ds_read_b128 v[178:181], v64
	v_mov_b32_e32 v64, 0x1c5e0
	ds_read_b128 v[182:185], v64
	v_mov_b32_e32 v64, 0x1c5f0
	ds_read_b128 v[196:199], v64
	v_or_b32_e32 v64, 0x1c8f4, v67
	ds_read_b32 v64, v64
	ds_read_b32 v65, v66 offset:31232
	s_waitcnt lgkmcnt(0)
; DI void gdn_prep_item(const Params& P, int l, int n, int hh, char* smem) {
;     ...
;     for (int i = 1; i < 64; ++i) {
;       f32x4 (&CUR)[16] = (i & 1) ? LA : LB; f32x4 (&NXT)[16] = (i & 1) ? LB : LA;
;       if (i + 1 < 64) {
; #pragma unroll
;         for (int c = 0; c < (i + 4) / 4; ++c) NXT[c] = *(const f32x4*)(Lm + (i + 1) * 64 + 4 * c);
;         rh[(i + 1) & 1] = sp[i + 1] * rp[(i + 1) * 128];
;       }
;       __builtin_amdgcn_sched_barrier(0);
;       f32x2 acc = {rh[i & 1], 0.f};
; #pragma unroll
;       for (int p = 0; p < i / 2; ++p) { const f32x2 lp = (p & 1) ? (f32x2){CUR[p >> 1].z, CUR[p >> 1].w} : (f32x2){CUR[p >> 1].x, CUR[p >> 1].y}; acc = acc - lp * xx[p]; }
;       if (i & 1) { const int j = i - 1; const float lj = ((j & 3) == 0) ? CUR[j >> 2].x : CUR[j >> 2].z; acc.x = fmaf(-lj, xx[j >> 1].x, acc.x); }
;       const float xi = acc.x + acc.y;
;       if (i & 1) xx[i >> 1].y = xi; else xx[i >> 1].x = xi;
;       __builtin_amdgcn_sched_barrier(0);
;     }
	v_mul_f32_e32 v198, v64, v65
	v_pk_fma_f32 v[64:65], v[2:3], v[84:85], v[0:1] neg_lo:[1,0,0] neg_hi:[1,0,0]
	s_nop 0
	v_pk_fma_f32 v[64:65], v[4:5], v[86:87], v[64:65] neg_lo:[1,0,0] neg_hi:[1,0,0]
	s_nop 0
	v_pk_fma_f32 v[64:65], v[6:7], v[92:93], v[64:65] neg_lo:[1,0,0] neg_hi:[1,0,0]
	s_nop 0
	v_pk_fma_f32 v[64:65], v[8:9], v[94:95], v[64:65] neg_lo:[1,0,0] neg_hi:[1,0,0]
	s_nop 0
	v_pk_fma_f32 v[64:65], v[10:11], v[112:113], v[64:65] neg_lo:[1,0,0] neg_hi:[1,0,0]
	s_nop 0
	v_pk_fma_f32 v[64:65], v[12:13], v[114:115], v[64:65] neg_lo:[1,0,0] neg_hi:[1,0,0]
	s_nop 0
	v_pk_fma_f32 v[64:65], v[14:15], v[116:117], v[64:65] neg_lo:[1,0,0] neg_hi:[1,0,0]
	s_nop 0
	v_pk_fma_f32 v[64:65], v[16:17], v[118:119], v[64:65] neg_lo:[1,0,0] neg_hi:[1,0,0]
	s_nop 0
	v_pk_fma_f32 v[64:65], v[18:19], v[124:125], v[64:65] neg_lo:[1,0,0] neg_hi:[1,0,0]
	s_nop 0
	v_pk_fma_f32 v[64:65], v[20:21], v[126:127], v[64:65] neg_lo:[1,0,0] neg_hi:[1,0,0]
	s_nop 0
	v_pk_fma_f32 v[64:65], v[22:23], v[132:133], v[64:65] neg_lo:[1,0,0] neg_hi:[1,0,0]
	s_nop 0
	v_pk_fma_f32 v[64:65], v[24:25], v[134:135], v[64:65] neg_lo:[1,0,0] neg_hi:[1,0,0]
	s_nop 0
	v_pk_fma_f32 v[64:65], v[26:27], v[140:141], v[64:65] neg_lo:[1,0,0] neg_hi:[1,0,0]
	s_nop 0
	v_pk_fma_f32 v[64:65], v[28:29], v[142:143], v[64:65] neg_lo:[1,0,0] neg_hi:[1,0,0]
	s_nop 0
	v_pk_fma_f32 v[64:65], v[30:31], v[148:149], v[64:65] neg_lo:[1,0,0] neg_hi:[1,0,0]
	s_nop 0
	v_pk_fma_f32 v[64:65], v[32:33], v[150:151], v[64:65] neg_lo:[1,0,0] neg_hi:[1,0,0]
	s_nop 0
	v_pk_fma_f32 v[64:65], v[34:35], v[152:153], v[64:65] neg_lo:[1,0,0] neg_hi:[1,0,0]
	s_nop 0
	v_pk_fma_f32 v[64:65], v[36:37], v[154:155], v[64:65] neg_lo:[1,0,0] neg_hi:[1,0,0]
	s_nop 0
	v_pk_fma_f32 v[64:65], v[38:39], v[156:157], v[64:65] neg_lo:[1,0,0] neg_hi:[1,0,0]
	s_nop 0
	v_pk_fma_f32 v[64:65], v[40:41], v[158:159], v[64:65] neg_lo:[1,0,0] neg_hi:[1,0,0]
	s_nop 0
	v_pk_fma_f32 v[64:65], v[42:43], v[160:161], v[64:65] neg_lo:[1,0,0] neg_hi:[1,0,0]
	s_nop 0
	v_pk_fma_f32 v[64:65], v[44:45], v[162:163], v[64:65] neg_lo:[1,0,0] neg_hi:[1,0,0]
	s_nop 0
	v_pk_fma_f32 v[64:65], v[46:47], v[170:171], v[64:65] neg_lo:[1,0,0] neg_hi:[1,0,0]
	s_nop 0
	v_pk_fma_f32 v[64:65], v[48:49], v[172:173], v[64:65] neg_lo:[1,0,0] neg_hi:[1,0,0]
	s_nop 0
	v_pk_fma_f32 v[64:65], v[52:53], v[188:189], v[64:65] neg_lo:[1,0,0] neg_hi:[1,0,0]
	s_nop 0
	v_pk_fma_f32 v[64:65], v[54:55], v[190:191], v[64:65] neg_lo:[1,0,0] neg_hi:[1,0,0]
	s_nop 0
	v_pk_fma_f32 v[64:65], v[56:57], v[192:193], v[64:65] neg_lo:[1,0,0] neg_hi:[1,0,0]
	s_nop 0
	v_pk_fma_f32 v[64:65], v[58:59], v[194:195], v[64:65] neg_lo:[1,0,0] neg_hi:[1,0,0]
	s_nop 0
	v_pk_fma_f32 v[64:65], v[60:61], v[174:175], v[64:65] neg_lo:[1,0,0] neg_hi:[1,0,0]
	s_nop 0
	v_pk_fma_f32 v[64:65], v[176:177], v[62:63], v[64:65] neg_lo:[1,0,0] neg_hi:[1,0,0]
	s_nop 0
	v_pk_add_f32 v[64:65], v[64:65], v[64:65] op_sel:[0,1] op_sel_hi:[1,0]
	v_mov_b32_e32 v0, 0x1c600
	ds_read_b128 v[84:87], v0
	v_mov_b32_e32 v0, 0x1c610
	ds_read_b128 v[92:95], v0
	v_mov_b32_e32 v0, 0x1c620
	ds_read_b128 v[112:115], v0
	v_mov_b32_e32 v0, 0x1c630
	ds_read_b128 v[116:119], v0
	v_mov_b32_e32 v0, 0x1c640
	ds_read_b128 v[124:127], v0
	v_mov_b32_e32 v0, 0x1c650
	ds_read_b128 v[132:135], v0
	v_mov_b32_e32 v0, 0x1c660
	ds_read_b128 v[140:143], v0
	v_mov_b32_e32 v0, 0x1c670
	ds_read_b128 v[148:151], v0
	v_mov_b32_e32 v0, 0x1c680
	ds_read_b128 v[152:155], v0
	v_mov_b32_e32 v0, 0x1c690
	ds_read_b128 v[156:159], v0
	v_mov_b32_e32 v0, 0x1c6a0
	ds_read_b128 v[160:163], v0
	v_mov_b32_e32 v0, 0x1c6b0
	ds_read_b128 v[168:171], v0
	v_mov_b32_e32 v0, 0x1c6c0
	ds_read_b128 v[172:175], v0
	v_mov_b32_e32 v0, 0x1c6d0
	ds_read_b128 v[186:189], v0
	v_or_b32_e32 v0, 0x1c8f8, v67
	v_mov_b32_e32 v83, 0x1c6e0
	ds_read_b32 v0, v0
	ds_read_b32 v65, v66 offset:31744
	ds_read_b128 v[190:193], v83
	v_mov_b32_e32 v83, 0x1c6f0
	ds_read_b64 v[200:201], v83
	v_mov_b32_e32 v199, v1
	v_pk_fma_f32 v[70:71], v[2:3], v[70:71], v[198:199] neg_lo:[1,0,0] neg_hi:[1,0,0]
	s_nop 0
	v_pk_fma_f32 v[70:71], v[4:5], v[72:73], v[70:71] neg_lo:[1,0,0] neg_hi:[1,0,0]
	s_nop 0
	v_pk_fma_f32 v[70:71], v[6:7], v[74:75], v[70:71] neg_lo:[1,0,0] neg_hi:[1,0,0]
	s_nop 0
	v_pk_fma_f32 v[70:71], v[8:9], v[76:77], v[70:71] neg_lo:[1,0,0] neg_hi:[1,0,0]
	s_nop 0
	v_pk_fma_f32 v[70:71], v[10:11], v[78:79], v[70:71] neg_lo:[1,0,0] neg_hi:[1,0,0]
	s_nop 0
	v_pk_fma_f32 v[70:71], v[12:13], v[80:81], v[70:71] neg_lo:[1,0,0] neg_hi:[1,0,0]
	s_nop 0
	v_pk_fma_f32 v[70:71], v[14:15], v[88:89], v[70:71] neg_lo:[1,0,0] neg_hi:[1,0,0]
	s_nop 0
	v_pk_fma_f32 v[70:71], v[16:17], v[90:91], v[70:71] neg_lo:[1,0,0] neg_hi:[1,0,0]
	s_nop 0
	v_pk_fma_f32 v[70:71], v[18:19], v[96:97], v[70:71] neg_lo:[1,0,0] neg_hi:[1,0,0]
	s_nop 0
	v_pk_fma_f32 v[70:71], v[20:21], v[98:99], v[70:71] neg_lo:[1,0,0] neg_hi:[1,0,0]
	s_nop 0
	v_pk_fma_f32 v[70:71], v[22:23], v[100:101], v[70:71] neg_lo:[1,0,0] neg_hi:[1,0,0]
	s_nop 0
	v_pk_fma_f32 v[70:71], v[24:25], v[102:103], v[70:71] neg_lo:[1,0,0] neg_hi:[1,0,0]
	s_nop 0
	v_pk_fma_f32 v[70:71], v[26:27], v[104:105], v[70:71] neg_lo:[1,0,0] neg_hi:[1,0,0]
	s_nop 0
	v_pk_fma_f32 v[70:71], v[28:29], v[106:107], v[70:71] neg_lo:[1,0,0] neg_hi:[1,0,0]
	s_nop 0
	v_pk_fma_f32 v[70:71], v[30:31], v[108:109], v[70:71] neg_lo:[1,0,0] neg_hi:[1,0,0]
	s_nop 0
	v_pk_fma_f32 v[70:71], v[32:33], v[110:111], v[70:71] neg_lo:[1,0,0] neg_hi:[1,0,0]
	s_nop 0
	v_pk_fma_f32 v[70:71], v[34:35], v[120:121], v[70:71] neg_lo:[1,0,0] neg_hi:[1,0,0]
	s_nop 0
	v_pk_fma_f32 v[70:71], v[36:37], v[122:123], v[70:71] neg_lo:[1,0,0] neg_hi:[1,0,0]
	s_nop 0
	v_pk_fma_f32 v[70:71], v[38:39], v[128:129], v[70:71] neg_lo:[1,0,0] neg_hi:[1,0,0]
	s_nop 0
	v_pk_fma_f32 v[70:71], v[40:41], v[130:131], v[70:71] neg_lo:[1,0,0] neg_hi:[1,0,0]
	s_nop 0
	v_pk_fma_f32 v[70:71], v[42:43], v[136:137], v[70:71] neg_lo:[1,0,0] neg_hi:[1,0,0]
	s_nop 0
	v_pk_fma_f32 v[70:71], v[44:45], v[138:139], v[70:71] neg_lo:[1,0,0] neg_hi:[1,0,0]
	s_nop 0
	v_pk_fma_f32 v[70:71], v[46:47], v[144:145], v[70:71] neg_lo:[1,0,0] neg_hi:[1,0,0]
	s_nop 0
	v_pk_fma_f32 v[70:71], v[48:49], v[146:147], v[70:71] neg_lo:[1,0,0] neg_hi:[1,0,0]
	s_nop 0
	v_pk_fma_f32 v[70:71], v[52:53], v[164:165], v[70:71] neg_lo:[1,0,0] neg_hi:[1,0,0]
	s_nop 0
	v_pk_fma_f32 v[70:71], v[54:55], v[166:167], v[70:71] neg_lo:[1,0,0] neg_hi:[1,0,0]
	s_nop 0
	v_pk_fma_f32 v[70:71], v[56:57], v[178:179], v[70:71] neg_lo:[1,0,0] neg_hi:[1,0,0]
	s_nop 0
	v_pk_fma_f32 v[70:71], v[58:59], v[180:181], v[70:71] neg_lo:[1,0,0] neg_hi:[1,0,0]
	s_nop 0
	v_pk_fma_f32 v[70:71], v[60:61], v[182:183], v[70:71] neg_lo:[1,0,0] neg_hi:[1,0,0]
	s_nop 0
	v_pk_fma_f32 v[70:71], v[62:63], v[184:185], v[70:71] neg_lo:[1,0,0] neg_hi:[1,0,0]
	s_nop 0
	s_waitcnt lgkmcnt(0)
; DI void gdn_prep_item(const Params& P, int l, int n, int hh, char* smem) {
;     ...
;     for (int i = 1; i < 64; ++i) {
;       f32x4 (&CUR)[16] = (i & 1) ? LA : LB; f32x4 (&NXT)[16] = (i & 1) ? LB : LA;
;       if (i + 1 < 64) {
; #pragma unroll
;         for (int c = 0; c < (i + 4) / 4; ++c) NXT[c] = *(const f32x4*)(Lm + (i + 1) * 64 + 4 * c);
;         rh[(i + 1) & 1] = sp[i + 1] * rp[(i + 1) * 128];
;       }
;       __builtin_amdgcn_sched_barrier(0);
;       f32x2 acc = {rh[i & 1], 0.f};
; #pragma unroll
;       for (int p = 0; p < i / 2; ++p) { const f32x2 lp = (p & 1) ? (f32x2){CUR[p >> 1].z, CUR[p >> 1].w} : (f32x2){CUR[p >> 1].x, CUR[p >> 1].y}; acc = acc - lp * xx[p]; }
;       if (i & 1) { const int j = i - 1; const float lj = ((j & 3) == 0) ? CUR[j >> 2].x : CUR[j >> 2].z; acc.x = fmaf(-lj, xx[j >> 1].x, acc.x); }
;       const float xi = acc.x + acc.y;
;       if (i & 1) xx[i >> 1].y = xi; else xx[i >> 1].x = xi;
;       __builtin_amdgcn_sched_barrier(0);
;     }
	v_mul_f32_e32 v0, v0, v65
	v_fma_f32 v65, -v196, v64, v70
	v_add_f32_e32 v65, v71, v65
	v_mov_b32_e32 v78, 0x1c720
	v_mov_b32_e32 v83, 0x1c730
	ds_read_b128 v[78:81], v78
	ds_read_b128 v[88:91], v83
	v_mov_b32_e32 v83, 0x1c740
	ds_read_b128 v[96:99], v83
	v_mov_b32_e32 v83, 0x1c750
	ds_read_b128 v[100:103], v83
	v_mov_b32_e32 v83, 0x1c760
	ds_read_b128 v[104:107], v83
	v_mov_b32_e32 v83, 0x1c770
	ds_read_b128 v[108:111], v83
	v_mov_b32_e32 v83, 0x1c780
	ds_read_b128 v[120:123], v83
	v_mov_b32_e32 v83, 0x1c790
	ds_read_b128 v[128:131], v83
	v_mov_b32_e32 v83, 0x1c7a0
	ds_read_b128 v[136:139], v83
	v_mov_b32_e32 v83, 0x1c7b0
	ds_read_b128 v[144:147], v83
	v_mov_b32_e32 v83, 0x1c7c0
	ds_read_b128 v[164:167], v83
	v_mov_b32_e32 v83, 0x1c7d0
	v_mov_b32_e32 v70, 0x1c700
	v_mov_b32_e32 v74, 0x1c710
	ds_read_b128 v[176:179], v83
	v_or_b32_e32 v67, 0x1c8fc, v67
	v_mov_b32_e32 v83, 0x1c7e0
	ds_read_b128 v[70:73], v70
	ds_read_b128 v[74:77], v74
	ds_read_b32 v67, v67
	ds_read_b32 v66, v66 offset:32256
	ds_read_b128 v[180:183], v83
	v_mov_b32_e32 v83, 0x1c7f0
	ds_read_b128 v[194:197], v83
	s_waitcnt lgkmcnt(0)
	v_mul_f32_e32 v184, v67, v66
	v_pk_fma_f32 v[66:67], v[2:3], v[84:85], v[0:1] neg_lo:[1,0,0] neg_hi:[1,0,0]
	s_nop 0
	v_pk_fma_f32 v[66:67], v[4:5], v[86:87], v[66:67] neg_lo:[1,0,0] neg_hi:[1,0,0]
	s_nop 0
	v_pk_fma_f32 v[66:67], v[6:7], v[92:93], v[66:67] neg_lo:[1,0,0] neg_hi:[1,0,0]
	s_nop 0
	v_pk_fma_f32 v[66:67], v[8:9], v[94:95], v[66:67] neg_lo:[1,0,0] neg_hi:[1,0,0]
	s_nop 0
	v_pk_fma_f32 v[66:67], v[10:11], v[112:113], v[66:67] neg_lo:[1,0,0] neg_hi:[1,0,0]
	s_nop 0
	v_pk_fma_f32 v[66:67], v[12:13], v[114:115], v[66:67] neg_lo:[1,0,0] neg_hi:[1,0,0]
	s_nop 0
	v_pk_fma_f32 v[66:67], v[14:15], v[116:117], v[66:67] neg_lo:[1,0,0] neg_hi:[1,0,0]
	s_nop 0
	v_pk_fma_f32 v[66:67], v[16:17], v[118:119], v[66:67] neg_lo:[1,0,0] neg_hi:[1,0,0]
	s_nop 0
	v_pk_fma_f32 v[66:67], v[18:19], v[124:125], v[66:67] neg_lo:[1,0,0] neg_hi:[1,0,0]
	s_nop 0
	v_pk_fma_f32 v[66:67], v[20:21], v[126:127], v[66:67] neg_lo:[1,0,0] neg_hi:[1,0,0]
	s_nop 0
	v_pk_fma_f32 v[66:67], v[22:23], v[132:133], v[66:67] neg_lo:[1,0,0] neg_hi:[1,0,0]
	s_nop 0
	v_pk_fma_f32 v[66:67], v[24:25], v[134:135], v[66:67] neg_lo:[1,0,0] neg_hi:[1,0,0]
	s_nop 0
	v_pk_fma_f32 v[66:67], v[26:27], v[140:141], v[66:67] neg_lo:[1,0,0] neg_hi:[1,0,0]
	s_nop 0
	v_pk_fma_f32 v[66:67], v[28:29], v[142:143], v[66:67] neg_lo:[1,0,0] neg_hi:[1,0,0]
	s_nop 0
	v_pk_fma_f32 v[66:67], v[30:31], v[148:149], v[66:67] neg_lo:[1,0,0] neg_hi:[1,0,0]
	s_nop 0
	v_pk_fma_f32 v[66:67], v[32:33], v[150:151], v[66:67] neg_lo:[1,0,0] neg_hi:[1,0,0]
	s_nop 0
	v_pk_fma_f32 v[66:67], v[34:35], v[152:153], v[66:67] neg_lo:[1,0,0] neg_hi:[1,0,0]
	s_nop 0
	v_pk_fma_f32 v[66:67], v[36:37], v[154:155], v[66:67] neg_lo:[1,0,0] neg_hi:[1,0,0]
	s_nop 0
	v_pk_fma_f32 v[66:67], v[38:39], v[156:157], v[66:67] neg_lo:[1,0,0] neg_hi:[1,0,0]
	s_nop 0
	v_pk_fma_f32 v[66:67], v[40:41], v[158:159], v[66:67] neg_lo:[1,0,0] neg_hi:[1,0,0]
	s_nop 0
	v_pk_fma_f32 v[66:67], v[42:43], v[160:161], v[66:67] neg_lo:[1,0,0] neg_hi:[1,0,0]
	s_nop 0
	v_pk_fma_f32 v[66:67], v[44:45], v[162:163], v[66:67] neg_lo:[1,0,0] neg_hi:[1,0,0]
	s_nop 0
	v_pk_fma_f32 v[66:67], v[46:47], v[168:169], v[66:67] neg_lo:[1,0,0] neg_hi:[1,0,0]
	s_nop 0
	v_pk_fma_f32 v[66:67], v[48:49], v[170:171], v[66:67] neg_lo:[1,0,0] neg_hi:[1,0,0]
	s_nop 0
	v_pk_fma_f32 v[66:67], v[52:53], v[172:173], v[66:67] neg_lo:[1,0,0] neg_hi:[1,0,0]
	s_nop 0
	v_pk_fma_f32 v[66:67], v[54:55], v[174:175], v[66:67] neg_lo:[1,0,0] neg_hi:[1,0,0]
	s_nop 0
	v_pk_fma_f32 v[66:67], v[56:57], v[186:187], v[66:67] neg_lo:[1,0,0] neg_hi:[1,0,0]
	s_nop 0
	v_pk_fma_f32 v[66:67], v[58:59], v[188:189], v[66:67] neg_lo:[1,0,0] neg_hi:[1,0,0]
	s_nop 0
	v_pk_fma_f32 v[66:67], v[60:61], v[190:191], v[66:67] neg_lo:[1,0,0] neg_hi:[1,0,0]
	s_nop 0
	v_pk_fma_f32 v[66:67], v[62:63], v[192:193], v[66:67] neg_lo:[1,0,0] neg_hi:[1,0,0]
	s_nop 0
	v_pk_fma_f32 v[66:67], v[200:201], v[64:65], v[66:67] neg_lo:[1,0,0] neg_hi:[1,0,0]
	s_nop 0
	v_pk_add_f32 v[66:67], v[66:67], v[66:67] op_sel:[0,1] op_sel_hi:[1,0]
	v_mov_b32_e32 v185, v1
	v_pk_fma_f32 v[70:71], v[2:3], v[70:71], v[184:185] neg_lo:[1,0,0] neg_hi:[1,0,0]
	s_nop 0
	v_pk_fma_f32 v[70:71], v[4:5], v[72:73], v[70:71] neg_lo:[1,0,0] neg_hi:[1,0,0]
	s_nop 0
	v_pk_fma_f32 v[70:71], v[6:7], v[74:75], v[70:71] neg_lo:[1,0,0] neg_hi:[1,0,0]
	s_nop 0
	v_pk_fma_f32 v[70:71], v[8:9], v[76:77], v[70:71] neg_lo:[1,0,0] neg_hi:[1,0,0]
	s_nop 0
	v_pk_fma_f32 v[70:71], v[10:11], v[78:79], v[70:71] neg_lo:[1,0,0] neg_hi:[1,0,0]
	s_nop 0
	v_pk_fma_f32 v[70:71], v[12:13], v[80:81], v[70:71] neg_lo:[1,0,0] neg_hi:[1,0,0]
	s_nop 0
	v_pk_fma_f32 v[70:71], v[14:15], v[88:89], v[70:71] neg_lo:[1,0,0] neg_hi:[1,0,0]
	s_nop 0
	v_pk_fma_f32 v[70:71], v[16:17], v[90:91], v[70:71] neg_lo:[1,0,0] neg_hi:[1,0,0]
	s_nop 0
	v_pk_fma_f32 v[70:71], v[18:19], v[96:97], v[70:71] neg_lo:[1,0,0] neg_hi:[1,0,0]
	s_nop 0
	v_pk_fma_f32 v[70:71], v[20:21], v[98:99], v[70:71] neg_lo:[1,0,0] neg_hi:[1,0,0]
	s_nop 0
	v_pk_fma_f32 v[70:71], v[22:23], v[100:101], v[70:71] neg_lo:[1,0,0] neg_hi:[1,0,0]
	s_nop 0
	v_pk_fma_f32 v[70:71], v[24:25], v[102:103], v[70:71] neg_lo:[1,0,0] neg_hi:[1,0,0]
	s_nop 0
	v_pk_fma_f32 v[70:71], v[26:27], v[104:105], v[70:71] neg_lo:[1,0,0] neg_hi:[1,0,0]
	s_nop 0
	v_pk_fma_f32 v[70:71], v[28:29], v[106:107], v[70:71] neg_lo:[1,0,0] neg_hi:[1,0,0]
	s_nop 0
	v_pk_fma_f32 v[70:71], v[30:31], v[108:109], v[70:71] neg_lo:[1,0,0] neg_hi:[1,0,0]
	s_nop 0
	v_pk_fma_f32 v[70:71], v[32:33], v[110:111], v[70:71] neg_lo:[1,0,0] neg_hi:[1,0,0]
	s_nop 0
; DI void gdn_prep_item(const Params& P, int l, int n, int hh, char* smem) {
;     ...
;       for (int p = 0; p < i / 2; ++p) { const f32x2 lp = (p & 1) ? (f32x2){CUR[p >> 1].z, CUR[p >> 1].w} : (f32x2){CUR[p >> 1].x, CUR[p >> 1].y}; acc = acc - lp * xx[p]; }
;       if (i & 1) { const int j = i - 1; const float lj = ((j & 3) == 0) ? CUR[j >> 2].x : CUR[j >> 2].z; acc.x = fmaf(-lj, xx[j >> 1].x, acc.x); }
;       const float xi = acc.x + acc.y;
;       if (i & 1) xx[i >> 1].y = xi; else xx[i >> 1].x = xi;
;       __builtin_amdgcn_sched_barrier(0);
;     }
;     float x[64];
; #pragma unroll
;     for (int p = 0; p < 32; ++p) { x[2 * p] = xx[p].x; x[2 * p + 1] = xx[p].y; }
;     if (isu) {
	v_pk_fma_f32 v[70:71], v[34:35], v[120:121], v[70:71] neg_lo:[1,0,0] neg_hi:[1,0,0]
	s_nop 0
	v_pk_fma_f32 v[70:71], v[36:37], v[122:123], v[70:71] neg_lo:[1,0,0] neg_hi:[1,0,0]
	s_nop 0
	v_pk_fma_f32 v[70:71], v[38:39], v[128:129], v[70:71] neg_lo:[1,0,0] neg_hi:[1,0,0]
	s_nop 0
	v_pk_fma_f32 v[70:71], v[40:41], v[130:131], v[70:71] neg_lo:[1,0,0] neg_hi:[1,0,0]
	s_nop 0
	v_pk_fma_f32 v[70:71], v[42:43], v[136:137], v[70:71] neg_lo:[1,0,0] neg_hi:[1,0,0]
	s_nop 0
	v_pk_fma_f32 v[70:71], v[44:45], v[138:139], v[70:71] neg_lo:[1,0,0] neg_hi:[1,0,0]
	s_nop 0
	v_pk_fma_f32 v[70:71], v[46:47], v[144:145], v[70:71] neg_lo:[1,0,0] neg_hi:[1,0,0]
	s_nop 0
	v_pk_fma_f32 v[70:71], v[48:49], v[146:147], v[70:71] neg_lo:[1,0,0] neg_hi:[1,0,0]
	s_nop 0
	v_pk_fma_f32 v[70:71], v[52:53], v[164:165], v[70:71] neg_lo:[1,0,0] neg_hi:[1,0,0]
	s_nop 0
	v_pk_fma_f32 v[70:71], v[54:55], v[166:167], v[70:71] neg_lo:[1,0,0] neg_hi:[1,0,0]
	s_nop 0
	v_pk_fma_f32 v[70:71], v[56:57], v[176:177], v[70:71] neg_lo:[1,0,0] neg_hi:[1,0,0]
	s_nop 0
	v_pk_fma_f32 v[70:71], v[58:59], v[178:179], v[70:71] neg_lo:[1,0,0] neg_hi:[1,0,0]
	s_nop 0
	v_pk_fma_f32 v[70:71], v[60:61], v[180:181], v[70:71] neg_lo:[1,0,0] neg_hi:[1,0,0]
	s_nop 0
	v_pk_fma_f32 v[70:71], v[62:63], v[182:183], v[70:71] neg_lo:[1,0,0] neg_hi:[1,0,0]
	s_nop 0
	v_pk_fma_f32 v[70:71], v[64:65], v[194:195], v[70:71] neg_lo:[1,0,0] neg_hi:[1,0,0]
	s_nop 0
	v_fma_f32 v0, -v196, v66, v70
	v_add_f32_e32 v67, v71, v0
	s_and_saveexec_b64 s[10:11], vcc
	s_xor_b64 s[10:11], exec, s[10:11]
	s_cbranch_execz .LBB0_530
; DI bf16_t f2bf(float x) { return (bf16_t)(pack2(x, 0.f) & 0xffffu); }
; DI void gdn_prep_item(const Params& P, int l, int n, int hh, char* smem) {
;     ...
;     } else {
;       const int pp = 32 * (cc >> 5) + perm32(cc & 31);
; #pragma unroll
;       for (int i = 0; i < 64; ++i) Wp[i * 128 + pp] = f2bf(x[i]);
;     }
	s_lshl_b64 s[12:13], s[8:9], 1
	v_lshl_add_u64 v[50:51], v[50:51], 0, s[12:13]
	s_movk_i32 s12, 0x60
	v_and_or_b32 v0, v82, s12, v68
	v_lshlrev_b32_e32 v0, 1, v0
	v_lshl_add_u64 v[50:51], v[50:51], 0, v[0:1]
	s_mov_b64 s[12:13], 0x1d2e8000
	v_lshl_add_u64 v[68:69], v[50:51], 0, s[12:13]
	v_cvt_pk_bf16_f32 v0, v3, s0
	global_store_short v[68:69], v0, off offset:256
	v_cvt_pk_bf16_f32 v0, v4, s0
	global_store_short v[68:69], v0, off offset:512
	v_cvt_pk_bf16_f32 v0, v5, s0
	global_store_short v[68:69], v0, off offset:768
	v_cvt_pk_bf16_f32 v0, v6, s0
	global_store_short v[68:69], v0, off offset:1024
	v_cvt_pk_bf16_f32 v0, v7, s0
	global_store_short v[68:69], v0, off offset:1280
	v_cvt_pk_bf16_f32 v0, v8, s0
	global_store_short v[68:69], v0, off offset:1536
	v_cvt_pk_bf16_f32 v0, v9, s0
	global_store_short v[68:69], v0, off offset:1792
	v_cvt_pk_bf16_f32 v0, v10, s0
	global_store_short v[68:69], v0, off offset:2048
	v_cvt_pk_bf16_f32 v0, v11, s0
	global_store_short v[68:69], v0, off offset:2304
	v_cvt_pk_bf16_f32 v0, v12, s0
	global_store_short v[68:69], v0, off offset:2560
	v_cvt_pk_bf16_f32 v0, v13, s0
	global_store_short v[68:69], v0, off offset:2816
	v_cvt_pk_bf16_f32 v0, v14, s0
	v_add_co_u32_e32 v70, vcc, 0x1d2e8000, v50
	global_store_short v[68:69], v0, off offset:3072
	v_cvt_pk_bf16_f32 v0, v15, s0
	v_cvt_pk_bf16_f32 v2, v2, s0
	v_addc_co_u32_e32 v71, vcc, 0, v51, vcc
	global_store_short v[68:69], v0, off offset:3328
	v_cvt_pk_bf16_f32 v0, v16, s0
	s_mov_b32 s12, 0x1d2e9000
	global_store_short v[70:71], v2, off
	global_store_short v[68:69], v0, off offset:3584
	v_cvt_pk_bf16_f32 v0, v17, s0
	v_add_co_u32_e32 v2, vcc, s12, v50
	global_store_short v[68:69], v0, off offset:3840
	v_cvt_pk_bf16_f32 v0, v18, s0
	v_addc_co_u32_e32 v3, vcc, 0, v51, vcc
	global_store_short v[2:3], v0, off
	v_cvt_pk_bf16_f32 v0, v19, s0
	global_store_short v[2:3], v0, off offset:256
	v_cvt_pk_bf16_f32 v0, v20, s0
	global_store_short v[2:3], v0, off offset:512
	v_cvt_pk_bf16_f32 v0, v21, s0
	global_store_short v[2:3], v0, off offset:768
	v_cvt_pk_bf16_f32 v0, v22, s0
	global_store_short v[2:3], v0, off offset:1024
	v_cvt_pk_bf16_f32 v0, v23, s0
	global_store_short v[2:3], v0, off offset:1280
	v_cvt_pk_bf16_f32 v0, v24, s0
	global_store_short v[2:3], v0, off offset:1536
	v_cvt_pk_bf16_f32 v0, v25, s0
	global_store_short v[2:3], v0, off offset:1792
	v_cvt_pk_bf16_f32 v0, v26, s0
	global_store_short v[2:3], v0, off offset:2048
	v_cvt_pk_bf16_f32 v0, v27, s0
	global_store_short v[2:3], v0, off offset:2304
	v_cvt_pk_bf16_f32 v0, v28, s0
	global_store_short v[2:3], v0, off offset:2560
	v_cvt_pk_bf16_f32 v0, v29, s0
	global_store_short v[2:3], v0, off offset:2816
	v_cvt_pk_bf16_f32 v0, v30, s0
	global_store_short v[2:3], v0, off offset:3072
	v_cvt_pk_bf16_f32 v0, v31, s0
	global_store_short v[2:3], v0, off offset:3328
	v_cvt_pk_bf16_f32 v0, v32, s0
	global_store_short v[2:3], v0, off offset:3584
	v_cvt_pk_bf16_f32 v0, v33, s0
	s_mov_b32 s12, 0x1d2ea000
	global_store_short v[2:3], v0, off offset:3840
	v_add_co_u32_e32 v2, vcc, s12, v50
	v_cvt_pk_bf16_f32 v0, v34, s0
	s_nop 0
	v_addc_co_u32_e32 v3, vcc, 0, v51, vcc
	global_store_short v[2:3], v0, off
	v_cvt_pk_bf16_f32 v0, v35, s0
	global_store_short v[2:3], v0, off offset:256
	v_cvt_pk_bf16_f32 v0, v36, s0
	global_store_short v[2:3], v0, off offset:512
	v_cvt_pk_bf16_f32 v0, v37, s0
	global_store_short v[2:3], v0, off offset:768
	v_cvt_pk_bf16_f32 v0, v38, s0
	global_store_short v[2:3], v0, off offset:1024
	v_cvt_pk_bf16_f32 v0, v39, s0
	global_store_short v[2:3], v0, off offset:1280
	v_cvt_pk_bf16_f32 v0, v40, s0
	global_store_short v[2:3], v0, off offset:1536
	v_cvt_pk_bf16_f32 v0, v41, s0
	global_store_short v[2:3], v0, off offset:1792
	v_cvt_pk_bf16_f32 v0, v42, s0
	global_store_short v[2:3], v0, off offset:2048
	v_cvt_pk_bf16_f32 v0, v43, s0
	global_store_short v[2:3], v0, off offset:2304
	v_cvt_pk_bf16_f32 v0, v44, s0
	global_store_short v[2:3], v0, off offset:2560
	v_cvt_pk_bf16_f32 v0, v45, s0
	global_store_short v[2:3], v0, off offset:2816
	v_cvt_pk_bf16_f32 v0, v46, s0
	global_store_short v[2:3], v0, off offset:3072
	v_cvt_pk_bf16_f32 v0, v47, s0
	global_store_short v[2:3], v0, off offset:3328
	v_cvt_pk_bf16_f32 v0, v48, s0
	global_store_short v[2:3], v0, off offset:3584
	v_cvt_pk_bf16_f32 v0, v49, s0
	s_mov_b32 s12, 0x1d2eb000
	global_store_short v[2:3], v0, off offset:3840
	v_add_co_u32_e32 v2, vcc, s12, v50
	v_cvt_pk_bf16_f32 v0, v52, s0
	s_nop 0
	v_addc_co_u32_e32 v3, vcc, 0, v51, vcc
	global_store_short v[2:3], v0, off
	v_cvt_pk_bf16_f32 v0, v53, s0
	global_store_short v[2:3], v0, off offset:256
	v_cvt_pk_bf16_f32 v0, v54, s0
	global_store_short v[2:3], v0, off offset:512
	v_cvt_pk_bf16_f32 v0, v55, s0
	global_store_short v[2:3], v0, off offset:768
	v_cvt_pk_bf16_f32 v0, v56, s0
	global_store_short v[2:3], v0, off offset:1024
	v_cvt_pk_bf16_f32 v0, v57, s0
	global_store_short v[2:3], v0, off offset:1280
	v_cvt_pk_bf16_f32 v0, v58, s0
	global_store_short v[2:3], v0, off offset:1536
	v_cvt_pk_bf16_f32 v0, v59, s0
	global_store_short v[2:3], v0, off offset:1792
	v_cvt_pk_bf16_f32 v0, v60, s0
	global_store_short v[2:3], v0, off offset:2048
	v_cvt_pk_bf16_f32 v0, v61, s0
	global_store_short v[2:3], v0, off offset:2304
	v_cvt_pk_bf16_f32 v0, v62, s0
	global_store_short v[2:3], v0, off offset:2560
	v_cvt_pk_bf16_f32 v0, v63, s0
	global_store_short v[2:3], v0, off offset:2816
	v_cvt_pk_bf16_f32 v0, v64, s0
	global_store_short v[2:3], v0, off offset:3072
	v_cvt_pk_bf16_f32 v0, v65, s0
	global_store_short v[2:3], v0, off offset:3328
	v_cvt_pk_bf16_f32 v0, v66, s0
	global_store_short v[2:3], v0, off offset:3584
	v_cvt_pk_bf16_f32 v0, v67, s0
	global_store_short v[2:3], v0, off offset:3840
